# wave-specialised GEMMs (4 loader waves issue all LDS-DMA, 4 compute waves own 96x64 quarters, ds_reads interleaved with MFMAs); prep_dt items dequeued first
# speedup vs baseline: 1.1924x; 1.0264x over previous
.Lgm_f1_cnt:
	s_add_u32 s30, s30, 16
	s_add_u32 s4, s4, s52
	s_cmp_lt_u32 s4, s54
	s_cbranch_scc1 .Lgm_f1_cnt
	s_add_u32 s48, s96, 0x2e24000
	s_addc_u32 s49, s97, 0
	s_mul_i32 s4, s36, 0x800000
	s_add_u32 s50, s96, 0xd80000
	s_addc_u32 s51, s97, 0
	s_add_u32 s50, s50, s4
	s_addc_u32 s51, s51, 0
	v_and_b32_e32 v0, 63, v206
	v_lshrrev_b32_e32 v1, 6, v206
	s_mov_b32 s31, 0
	v_readfirstlane_b32 s42, v1
	s_nop 0
	s_cmp_ge_u32 s42, 4
	s_cbranch_scc1 .Lgm_f1_compute
	v_lshrrev_b32_e32 v3, 3, v0
	v_and_b32_e32 v4, 7, v0
	v_xor_b32_e32 v4, v4, v3
	v_lshl_add_u32 v3, v1, 3, v3
	v_lshlrev_b32_e32 v3, 11, v3
	v_lshl_add_u32 v180, v4, 4, v3
	v_add_u32_e32 v181, 0x10000, v180
	v_add_u32_e32 v182, 0x20000, v180
	v_add_u32_e32 v183, 0x30000, v180
	v_add_u32_e32 v184, 0x40000, v180
	v_add_u32_e32 v185, 0x50000, v180
	s_lshl_b32 s42, s42, 10
	s_mov_b32 s38, s53
	s_mov_b32 s39, 0
	s_mov_b32 s41, s42
	s_and_b32 s4, s38, 31
	s_mul_i32 s4, s4, 0x60000
	s_add_u32 s44, s48, s4
	s_addc_u32 s45, s49, 0
	s_lshr_b32 s4, s38, 5
	s_mul_i32 s4, s4, 0x40000
	s_add_u32 s46, s50, s4
	s_addc_u32 s47, s51, 0
	s_add_u32 m0, s41, 0x0
	s_nop 0
	global_load_lds_dwordx4 v180, s[44:45]
	s_add_u32 m0, s41, 0x1000
	s_nop 0
	global_load_lds_dwordx4 v181, s[44:45]
	s_add_u32 m0, s41, 0x2000
	s_nop 0
	global_load_lds_dwordx4 v182, s[44:45]
	s_add_u32 m0, s41, 0x3000
	s_nop 0
	global_load_lds_dwordx4 v183, s[44:45]
	s_add_u32 m0, s41, 0x4000
	s_nop 0
	global_load_lds_dwordx4 v184, s[44:45]
	s_add_u32 m0, s41, 0x5000
	s_nop 0
	global_load_lds_dwordx4 v185, s[44:45]
	s_add_u32 m0, s41, 0x6000
	s_nop 0
	global_load_lds_dwordx4 v180, s[46:47]
	s_add_u32 m0, s41, 0x7000
	s_nop 0
	global_load_lds_dwordx4 v181, s[46:47]
	s_add_u32 m0, s41, 0x8000
	s_nop 0
	global_load_lds_dwordx4 v182, s[46:47]
	s_add_u32 m0, s41, 0x9000
	s_nop 0
	global_load_lds_dwordx4 v183, s[46:47]
	s_add_u32 s39, s39, 1
	s_add_u32 s44, s44, 0x80
	s_addc_u32 s45, s45, 0
	s_add_u32 s46, s46, 0x80
	s_addc_u32 s47, s47, 0
	s_cmp_lt_u32 s39, 16
	s_cbranch_scc1 .Lgm_f1_dadv1
	s_mov_b32 s39, 0
	s_add_u32 s4, s38, s52
	s_cmp_lt_u32 s4, s54
	s_cselect_b32 s38, s4, s38
	s_and_b32 s4, s38, 31
	s_mul_i32 s4, s4, 0x60000
	s_add_u32 s44, s48, s4
	s_addc_u32 s45, s49, 0
	s_lshr_b32 s4, s38, 5
	s_mul_i32 s4, s4, 0x40000
	s_add_u32 s46, s50, s4
	s_addc_u32 s47, s51, 0
.Lgm_f1_dadv1:
	s_add_u32 s41, s41, 0xa000
	s_sub_u32 s4, s41, 0x1e000
	s_cmp_ge_u32 s41, 0x1e000
	s_cselect_b32 s41, s4, s41
	s_add_u32 m0, s41, 0x0
	s_nop 0
	global_load_lds_dwordx4 v180, s[44:45]
	s_add_u32 m0, s41, 0x1000
	s_nop 0
	global_load_lds_dwordx4 v181, s[44:45]
	s_add_u32 m0, s41, 0x2000
	s_nop 0
	global_load_lds_dwordx4 v182, s[44:45]
	s_add_u32 m0, s41, 0x3000
	s_nop 0
	global_load_lds_dwordx4 v183, s[44:45]
	s_add_u32 m0, s41, 0x4000
	s_nop 0
	global_load_lds_dwordx4 v184, s[44:45]
	s_add_u32 m0, s41, 0x5000
	s_nop 0
	global_load_lds_dwordx4 v185, s[44:45]
	s_add_u32 m0, s41, 0x6000
	s_nop 0
	global_load_lds_dwordx4 v180, s[46:47]
	s_add_u32 m0, s41, 0x7000
	s_nop 0
	global_load_lds_dwordx4 v181, s[46:47]
	s_add_u32 m0, s41, 0x8000
	s_nop 0
	global_load_lds_dwordx4 v182, s[46:47]
	s_add_u32 m0, s41, 0x9000
	s_nop 0
	global_load_lds_dwordx4 v183, s[46:47]
	s_add_u32 s39, s39, 1
	s_add_u32 s44, s44, 0x80
	s_addc_u32 s45, s45, 0
	s_add_u32 s46, s46, 0x80
	s_addc_u32 s47, s47, 0
	s_cmp_lt_u32 s39, 16
	s_cbranch_scc1 .Lgm_f1_dadv2
	s_mov_b32 s39, 0
	s_add_u32 s4, s38, s52
	s_cmp_lt_u32 s4, s54
	s_cselect_b32 s38, s4, s38
	s_and_b32 s4, s38, 31
	s_mul_i32 s4, s4, 0x60000
	s_add_u32 s44, s48, s4
	s_addc_u32 s45, s49, 0
	s_lshr_b32 s4, s38, 5
	s_mul_i32 s4, s4, 0x40000
	s_add_u32 s46, s50, s4
	s_addc_u32 s47, s51, 0
.Lgm_f1_dadv2:
	s_add_u32 s41, s41, 0xa000
	s_sub_u32 s4, s41, 0x1e000
	s_cmp_ge_u32 s41, 0x1e000
	s_cselect_b32 s41, s4, s41
	s_waitcnt vmcnt(10)
.Lgm_f1_ld_loop:
	s_barrier
	s_add_u32 m0, s41, 0x0
	s_nop 0
	global_load_lds_dwordx4 v180, s[44:45]
	s_add_u32 m0, s41, 0x1000
	s_nop 0
	global_load_lds_dwordx4 v181, s[44:45]
	s_add_u32 m0, s41, 0x2000
	s_nop 0
	global_load_lds_dwordx4 v182, s[44:45]
	s_add_u32 m0, s41, 0x3000
	s_nop 0
	global_load_lds_dwordx4 v183, s[44:45]
	s_add_u32 m0, s41, 0x4000
	s_nop 0
	global_load_lds_dwordx4 v184, s[44:45]
	s_add_u32 m0, s41, 0x5000
	s_nop 0
	global_load_lds_dwordx4 v185, s[44:45]
	s_add_u32 m0, s41, 0x6000
	s_nop 0
	global_load_lds_dwordx4 v180, s[46:47]
	s_add_u32 m0, s41, 0x7000
	s_nop 0
	global_load_lds_dwordx4 v181, s[46:47]
	s_add_u32 m0, s41, 0x8000
	s_nop 0
	global_load_lds_dwordx4 v182, s[46:47]
	s_add_u32 m0, s41, 0x9000
	s_nop 0
	global_load_lds_dwordx4 v183, s[46:47]
	s_add_u32 s39, s39, 1
	s_add_u32 s44, s44, 0x80
	s_addc_u32 s45, s45, 0
	s_add_u32 s46, s46, 0x80
	s_addc_u32 s47, s47, 0
	s_cmp_lt_u32 s39, 16
	s_cbranch_scc1 .Lgm_f1_dadv3
	s_mov_b32 s39, 0
	s_add_u32 s4, s38, s52
	s_cmp_lt_u32 s4, s54
	s_cselect_b32 s38, s4, s38
	s_and_b32 s4, s38, 31
	s_mul_i32 s4, s4, 0x60000
	s_add_u32 s44, s48, s4
	s_addc_u32 s45, s49, 0
	s_lshr_b32 s4, s38, 5
	s_mul_i32 s4, s4, 0x40000
	s_add_u32 s46, s50, s4
	s_addc_u32 s47, s51, 0
.Lgm_f1_dadv3:
	s_add_u32 s41, s41, 0xa000
	s_sub_u32 s4, s41, 0x1e000
	s_cmp_ge_u32 s41, 0x1e000
	s_cselect_b32 s41, s4, s41
	s_add_u32 s31, s31, 1
	s_cmp_ge_u32 s31, s30
	s_cbranch_scc1 .Lgm_f1_exit
	s_waitcnt vmcnt(10)
	s_branch .Lgm_f1_ld_loop
.Lgm_f1_compute:
	v_and_b32_e32 v1, 3, v1
	v_and_b32_e32 v194, 15, v0
	v_lshrrev_b32_e32 v195, 4, v0
	v_and_b32_e32 v3, 7, v194
	v_xor_b32_e32 v3, v3, v195
	v_lshlrev_b32_e32 v3, 4, v3
	v_lshrrev_b32_e32 v176, 1, v1
	v_and_b32_e32 v177, 1, v1
	v_mul_u32_u24_e32 v178, 96, v176
	v_add_u32_e32 v179, v178, v194
	v_lshl_add_u32 v199, v179, 7, v3
	v_xor_b32_e32 v200, 64, v199
	v_lshl_add_u32 v179, v177, 6, v194
	v_lshl_add_u32 v201, v179, 7, v3
	v_add_u32_e32 v201, 0x6000, v201
	v_xor_b32_e32 v202, 64, v201
	s_sub_u32 s42, s42, 4
	s_mul_i32 s5, s42, 4352
	s_add_u32 s5, s5, 0x1e000
	v_mul_u32_u24_e32 v3, 1088, v195
	v_lshl_add_u32 v3, v194, 2, v3
	v_add_u32_e32 v203, s5, v3
	v_mul_u32_u24_e32 v3, 272, v195
	v_lshl_add_u32 v3, v194, 4, v3
	v_add_u32_e32 v204, s5, v3
	v_add_u32_e32 v190, v178, v195
	v_lshlrev_b32_e32 v3, 6, v177
	v_lshl_add_u32 v3, v194, 2, v3
	s_mov_b32 s4, 0x2000
	v_mul_lo_u32 v205, v190, s4
	v_lshl_add_u32 v205, v3, 1, v205
	v_lshlrev_b32_e32 v191, 2, v3
	v_mov_b32_e32 v193, v3
	v_mov_b32_e32 v4, 0
	v_mov_b32_e32 v5, 0
	v_mov_b32_e32 v6, 0
	v_mov_b32_e32 v7, 0
	v_mov_b32_e32 v8, 0
	v_mov_b32_e32 v9, 0
	v_mov_b32_e32 v10, 0
	v_mov_b32_e32 v11, 0
	v_mov_b32_e32 v12, 0
	v_mov_b32_e32 v13, 0
	v_mov_b32_e32 v14, 0
	v_mov_b32_e32 v15, 0
	v_mov_b32_e32 v16, 0
	v_mov_b32_e32 v17, 0
	v_mov_b32_e32 v18, 0
	v_mov_b32_e32 v19, 0
	v_mov_b32_e32 v20, 0
	v_mov_b32_e32 v21, 0
	v_mov_b32_e32 v22, 0
	v_mov_b32_e32 v23, 0
	v_mov_b32_e32 v24, 0
	v_mov_b32_e32 v25, 0
	v_mov_b32_e32 v26, 0
	v_mov_b32_e32 v27, 0
	v_mov_b32_e32 v28, 0
	v_mov_b32_e32 v29, 0
	v_mov_b32_e32 v30, 0
	v_mov_b32_e32 v31, 0
	v_mov_b32_e32 v32, 0
	v_mov_b32_e32 v33, 0
	v_mov_b32_e32 v34, 0
	v_mov_b32_e32 v35, 0
	v_mov_b32_e32 v36, 0
	v_mov_b32_e32 v37, 0
	v_mov_b32_e32 v38, 0
	v_mov_b32_e32 v39, 0
	v_mov_b32_e32 v40, 0
	v_mov_b32_e32 v41, 0
	v_mov_b32_e32 v42, 0
	v_mov_b32_e32 v43, 0
	v_mov_b32_e32 v44, 0
	v_mov_b32_e32 v45, 0
	v_mov_b32_e32 v46, 0
	v_mov_b32_e32 v47, 0
	v_mov_b32_e32 v48, 0
	v_mov_b32_e32 v49, 0
	v_mov_b32_e32 v50, 0
	v_mov_b32_e32 v51, 0
	v_mov_b32_e32 v52, 0
	v_mov_b32_e32 v53, 0
	v_mov_b32_e32 v54, 0
	v_mov_b32_e32 v55, 0
	v_mov_b32_e32 v56, 0
	v_mov_b32_e32 v57, 0
	v_mov_b32_e32 v58, 0
	v_mov_b32_e32 v59, 0
	v_mov_b32_e32 v60, 0
	v_mov_b32_e32 v61, 0
	v_mov_b32_e32 v62, 0
	v_mov_b32_e32 v63, 0
	v_mov_b32_e32 v64, 0
	v_mov_b32_e32 v65, 0
	v_mov_b32_e32 v66, 0
	v_mov_b32_e32 v67, 0
	v_mov_b32_e32 v68, 0
	v_mov_b32_e32 v69, 0
	v_mov_b32_e32 v70, 0
	v_mov_b32_e32 v71, 0
	v_mov_b32_e32 v72, 0
	v_mov_b32_e32 v73, 0
	v_mov_b32_e32 v74, 0
	v_mov_b32_e32 v75, 0
	v_mov_b32_e32 v76, 0
	v_mov_b32_e32 v77, 0
	v_mov_b32_e32 v78, 0
	v_mov_b32_e32 v79, 0
	v_mov_b32_e32 v80, 0
	v_mov_b32_e32 v81, 0
	v_mov_b32_e32 v82, 0
	v_mov_b32_e32 v83, 0
	v_mov_b32_e32 v84, 0
	v_mov_b32_e32 v85, 0
	v_mov_b32_e32 v86, 0
	v_mov_b32_e32 v87, 0
	v_mov_b32_e32 v88, 0
	v_mov_b32_e32 v89, 0
	v_mov_b32_e32 v90, 0
	v_mov_b32_e32 v91, 0
	v_mov_b32_e32 v92, 0
	v_mov_b32_e32 v93, 0
	v_mov_b32_e32 v94, 0
	v_mov_b32_e32 v95, 0
	v_mov_b32_e32 v96, 0
	v_mov_b32_e32 v97, 0
	v_mov_b32_e32 v98, 0
	v_mov_b32_e32 v99, 0
	s_mov_b32 s34, 0
	s_mov_b32 s35, s53
	s_mov_b32 s40, 0
.Lgm_f1_loop:
	s_barrier
	s_cmp_eq_u32 s34, 0
	s_cbranch_scc1 .Lgm_f1_first
	v_mfma_f32_16x16x32_bf16 v[4:7], v[140:143], v[164:167], v[4:7]
	ds_read_b128 v[100:103], v199 offset:0
	v_mfma_f32_16x16x32_bf16 v[20:23], v[144:147], v[164:167], v[20:23]
	ds_read_b128 v[104:107], v199 offset:2048
	v_mfma_f32_16x16x32_bf16 v[36:39], v[148:151], v[164:167], v[36:39]
	ds_read_b128 v[108:111], v199 offset:4096
	v_mfma_f32_16x16x32_bf16 v[52:55], v[152:155], v[164:167], v[52:55]
	ds_read_b128 v[112:115], v199 offset:6144
	v_mfma_f32_16x16x32_bf16 v[68:71], v[156:159], v[164:167], v[68:71]
	ds_read_b128 v[116:119], v199 offset:8192
	v_mfma_f32_16x16x32_bf16 v[84:87], v[160:163], v[164:167], v[84:87]
	ds_read_b128 v[120:123], v199 offset:10240
	v_mfma_f32_16x16x32_bf16 v[8:11], v[140:143], v[168:171], v[8:11]
	ds_read_b128 v[124:127], v201 offset:0
	v_mfma_f32_16x16x32_bf16 v[24:27], v[144:147], v[168:171], v[24:27]
	ds_read_b128 v[128:131], v201 offset:2048
	v_mfma_f32_16x16x32_bf16 v[40:43], v[148:151], v[168:171], v[40:43]
	ds_read_b128 v[132:135], v201 offset:4096
	v_mfma_f32_16x16x32_bf16 v[56:59], v[152:155], v[168:171], v[56:59]
	ds_read_b128 v[136:139], v201 offset:6144
	v_mfma_f32_16x16x32_bf16 v[72:75], v[156:159], v[168:171], v[72:75]
	v_mfma_f32_16x16x32_bf16 v[88:91], v[160:163], v[168:171], v[88:91]
	v_mfma_f32_16x16x32_bf16 v[12:15], v[140:143], v[172:175], v[12:15]
	v_mfma_f32_16x16x32_bf16 v[28:31], v[144:147], v[172:175], v[28:31]
	v_mfma_f32_16x16x32_bf16 v[44:47], v[148:151], v[172:175], v[44:47]
	v_mfma_f32_16x16x32_bf16 v[60:63], v[152:155], v[172:175], v[60:63]
	v_mfma_f32_16x16x32_bf16 v[76:79], v[156:159], v[172:175], v[76:79]
	v_mfma_f32_16x16x32_bf16 v[92:95], v[160:163], v[172:175], v[92:95]
	v_mfma_f32_16x16x32_bf16 v[16:19], v[140:143], v[176:179], v[16:19]
	ds_read_b128 v[140:143], v200 offset:0
	v_mfma_f32_16x16x32_bf16 v[32:35], v[144:147], v[176:179], v[32:35]
	ds_read_b128 v[144:147], v200 offset:2048
	v_mfma_f32_16x16x32_bf16 v[48:51], v[148:151], v[176:179], v[48:51]
	ds_read_b128 v[148:151], v200 offset:4096
	v_mfma_f32_16x16x32_bf16 v[64:67], v[152:155], v[176:179], v[64:67]
	ds_read_b128 v[152:155], v200 offset:6144
	v_mfma_f32_16x16x32_bf16 v[80:83], v[156:159], v[176:179], v[80:83]
	ds_read_b128 v[156:159], v200 offset:8192
	v_mfma_f32_16x16x32_bf16 v[96:99], v[160:163], v[176:179], v[96:99]
	ds_read_b128 v[160:163], v200 offset:10240
	ds_read_b128 v[164:167], v202 offset:0
	ds_read_b128 v[168:171], v202 offset:2048
	ds_read_b128 v[172:175], v202 offset:4096
	ds_read_b128 v[176:179], v202 offset:6144
	s_branch .Lgm_f1_join
.Lgm_f1_first:
	ds_read_b128 v[100:103], v199 offset:0
	ds_read_b128 v[104:107], v199 offset:2048
	ds_read_b128 v[108:111], v199 offset:4096
	ds_read_b128 v[112:115], v199 offset:6144
	ds_read_b128 v[116:119], v199 offset:8192
	ds_read_b128 v[120:123], v199 offset:10240
	ds_read_b128 v[124:127], v201 offset:0
	ds_read_b128 v[128:131], v201 offset:2048
	ds_read_b128 v[132:135], v201 offset:4096
	ds_read_b128 v[136:139], v201 offset:6144
	ds_read_b128 v[140:143], v200 offset:0
	ds_read_b128 v[144:147], v200 offset:2048
	ds_read_b128 v[148:151], v200 offset:4096
	ds_read_b128 v[152:155], v200 offset:6144
	ds_read_b128 v[156:159], v200 offset:8192
	ds_read_b128 v[160:163], v200 offset:10240
	ds_read_b128 v[164:167], v202 offset:0
	ds_read_b128 v[168:171], v202 offset:2048
	ds_read_b128 v[172:175], v202 offset:4096
	ds_read_b128 v[176:179], v202 offset:6144
.Lgm_f1_join:
	s_waitcnt lgkmcnt(13)
	v_mfma_f32_16x16x32_bf16 v[4:7], v[100:103], v[124:127], v[4:7]
	v_mfma_f32_16x16x32_bf16 v[20:23], v[104:107], v[124:127], v[20:23]
	v_mfma_f32_16x16x32_bf16 v[36:39], v[108:111], v[124:127], v[36:39]
	v_mfma_f32_16x16x32_bf16 v[52:55], v[112:115], v[124:127], v[52:55]
	v_mfma_f32_16x16x32_bf16 v[68:71], v[116:119], v[124:127], v[68:71]
	v_mfma_f32_16x16x32_bf16 v[84:87], v[120:123], v[124:127], v[84:87]
	s_waitcnt lgkmcnt(12)
	v_mfma_f32_16x16x32_bf16 v[8:11], v[100:103], v[128:131], v[8:11]
	v_mfma_f32_16x16x32_bf16 v[24:27], v[104:107], v[128:131], v[24:27]
	v_mfma_f32_16x16x32_bf16 v[40:43], v[108:111], v[128:131], v[40:43]
	v_mfma_f32_16x16x32_bf16 v[56:59], v[112:115], v[128:131], v[56:59]
	v_mfma_f32_16x16x32_bf16 v[72:75], v[116:119], v[128:131], v[72:75]
	v_mfma_f32_16x16x32_bf16 v[88:91], v[120:123], v[128:131], v[88:91]
	s_waitcnt lgkmcnt(11)
	v_mfma_f32_16x16x32_bf16 v[12:15], v[100:103], v[132:135], v[12:15]
	v_mfma_f32_16x16x32_bf16 v[28:31], v[104:107], v[132:135], v[28:31]
	v_mfma_f32_16x16x32_bf16 v[44:47], v[108:111], v[132:135], v[44:47]
	v_mfma_f32_16x16x32_bf16 v[60:63], v[112:115], v[132:135], v[60:63]
	v_mfma_f32_16x16x32_bf16 v[76:79], v[116:119], v[132:135], v[76:79]
	v_mfma_f32_16x16x32_bf16 v[92:95], v[120:123], v[132:135], v[92:95]
	s_waitcnt lgkmcnt(10)
	v_mfma_f32_16x16x32_bf16 v[16:19], v[100:103], v[136:139], v[16:19]
	v_mfma_f32_16x16x32_bf16 v[32:35], v[104:107], v[136:139], v[32:35]
	v_mfma_f32_16x16x32_bf16 v[48:51], v[108:111], v[136:139], v[48:51]
	v_mfma_f32_16x16x32_bf16 v[64:67], v[112:115], v[136:139], v[64:67]
	v_mfma_f32_16x16x32_bf16 v[80:83], v[116:119], v[136:139], v[80:83]
	v_mfma_f32_16x16x32_bf16 v[96:99], v[120:123], v[136:139], v[96:99]
	s_waitcnt lgkmcnt(0)
	s_add_u32 s34, s34, 1
	s_add_u32 s31, s31, 1
	s_cmp_lt_u32 s34, 16
	s_cbranch_scc1 .Lgm_f1_rot
	v_mfma_f32_16x16x32_bf16 v[4:7], v[140:143], v[164:167], v[4:7]
	v_mfma_f32_16x16x32_bf16 v[20:23], v[144:147], v[164:167], v[20:23]
	v_mfma_f32_16x16x32_bf16 v[36:39], v[148:151], v[164:167], v[36:39]
	v_mfma_f32_16x16x32_bf16 v[52:55], v[152:155], v[164:167], v[52:55]
	v_mfma_f32_16x16x32_bf16 v[68:71], v[156:159], v[164:167], v[68:71]
	v_mfma_f32_16x16x32_bf16 v[84:87], v[160:163], v[164:167], v[84:87]
	v_mfma_f32_16x16x32_bf16 v[8:11], v[140:143], v[168:171], v[8:11]
	v_mfma_f32_16x16x32_bf16 v[24:27], v[144:147], v[168:171], v[24:27]
	v_mfma_f32_16x16x32_bf16 v[40:43], v[148:151], v[168:171], v[40:43]
	v_mfma_f32_16x16x32_bf16 v[56:59], v[152:155], v[168:171], v[56:59]
	v_mfma_f32_16x16x32_bf16 v[72:75], v[156:159], v[168:171], v[72:75]
	v_mfma_f32_16x16x32_bf16 v[88:91], v[160:163], v[168:171], v[88:91]
	v_mfma_f32_16x16x32_bf16 v[12:15], v[140:143], v[172:175], v[12:15]
	v_mfma_f32_16x16x32_bf16 v[28:31], v[144:147], v[172:175], v[28:31]
	v_mfma_f32_16x16x32_bf16 v[44:47], v[148:151], v[172:175], v[44:47]
	v_mfma_f32_16x16x32_bf16 v[60:63], v[152:155], v[172:175], v[60:63]
	v_mfma_f32_16x16x32_bf16 v[76:79], v[156:159], v[172:175], v[76:79]
	v_mfma_f32_16x16x32_bf16 v[92:95], v[160:163], v[172:175], v[92:95]
	v_mfma_f32_16x16x32_bf16 v[16:19], v[140:143], v[176:179], v[16:19]
	v_mfma_f32_16x16x32_bf16 v[32:35], v[144:147], v[176:179], v[32:35]
	v_mfma_f32_16x16x32_bf16 v[48:51], v[148:151], v[176:179], v[48:51]
	v_mfma_f32_16x16x32_bf16 v[64:67], v[152:155], v[176:179], v[64:67]
	v_mfma_f32_16x16x32_bf16 v[80:83], v[156:159], v[176:179], v[80:83]
	v_mfma_f32_16x16x32_bf16 v[96:99], v[160:163], v[176:179], v[96:99]
	s_and_b32 s6, s35, 31
	s_mul_i32 s6, s6, 192
	s_lshr_b32 s7, s35, 5
	s_lshl_b32 s7, s7, 7
	s_nop 7
	s_mul_i32 s4, s6, 0x2000
	s_lshl_b32 s5, s7, 1
	s_add_u32 s4, s4, s5
	v_add_u32_e32 v197, s4, v205
	ds_write_b32 v203, v4 offset:0
	ds_write_b32 v203, v5 offset:272
	ds_write_b32 v203, v6 offset:544
	ds_write_b32 v203, v7 offset:816
	ds_write_b32 v203, v8 offset:64
	ds_write_b32 v203, v9 offset:336
	ds_write_b32 v203, v10 offset:608
	ds_write_b32 v203, v11 offset:880
	ds_write_b32 v203, v12 offset:128
	ds_write_b32 v203, v13 offset:400
	ds_write_b32 v203, v14 offset:672
	ds_write_b32 v203, v15 offset:944
	ds_write_b32 v203, v16 offset:192
	ds_write_b32 v203, v17 offset:464
	ds_write_b32 v203, v18 offset:736
	ds_write_b32 v203, v19 offset:1008
	s_waitcnt lgkmcnt(0)
	ds_read_b128 v[156:159], v204 offset:0
	ds_read_b128 v[160:163], v204 offset:1088
	ds_read_b128 v[164:167], v204 offset:2176
	ds_read_b128 v[168:171], v204 offset:3264
	s_waitcnt lgkmcnt(3)
	v_max_f32_e32 v156, 0, v156
	v_max_f32_e32 v157, 0, v157
	v_max_f32_e32 v158, 0, v158
	v_max_f32_e32 v159, 0, v159
	v_mul_f32_e32 v156, v156, v156
	v_mul_f32_e32 v157, v157, v157
	v_mul_f32_e32 v158, v158, v158
	v_mul_f32_e32 v159, v159, v159
	v_cvt_pk_bf16_f32 v176, v156, v157
	v_cvt_pk_bf16_f32 v177, v158, v159
	global_store_dwordx2 v197, v[176:177], s[56:57] sc0 sc1
	v_add_u32_e32 v197, 0x8000, v197
	s_waitcnt lgkmcnt(2)
	v_max_f32_e32 v160, 0, v160
	v_max_f32_e32 v161, 0, v161
	v_max_f32_e32 v162, 0, v162
	v_max_f32_e32 v163, 0, v163
	v_mul_f32_e32 v160, v160, v160
	v_mul_f32_e32 v161, v161, v161
	v_mul_f32_e32 v162, v162, v162
	v_mul_f32_e32 v163, v163, v163
	v_cvt_pk_bf16_f32 v178, v160, v161
	v_cvt_pk_bf16_f32 v179, v162, v163
	global_store_dwordx2 v197, v[178:179], s[56:57] sc0 sc1
	v_add_u32_e32 v197, 0x8000, v197
	s_waitcnt lgkmcnt(1)
	v_max_f32_e32 v164, 0, v164
	v_max_f32_e32 v165, 0, v165
	v_max_f32_e32 v166, 0, v166
	v_max_f32_e32 v167, 0, v167
	v_mul_f32_e32 v164, v164, v164
	v_mul_f32_e32 v165, v165, v165
	v_mul_f32_e32 v166, v166, v166
	v_mul_f32_e32 v167, v167, v167
	v_cvt_pk_bf16_f32 v176, v164, v165
	v_cvt_pk_bf16_f32 v177, v166, v167
	global_store_dwordx2 v197, v[176:177], s[56:57] sc0 sc1
	v_add_u32_e32 v197, 0x8000, v197
	s_waitcnt lgkmcnt(0)
	v_max_f32_e32 v168, 0, v168
	v_max_f32_e32 v169, 0, v169
	v_max_f32_e32 v170, 0, v170
	v_max_f32_e32 v171, 0, v171
	v_mul_f32_e32 v168, v168, v168
	v_mul_f32_e32 v169, v169, v169
	v_mul_f32_e32 v170, v170, v170
	v_mul_f32_e32 v171, v171, v171
	v_cvt_pk_bf16_f32 v178, v168, v169
	v_cvt_pk_bf16_f32 v179, v170, v171
	global_store_dwordx2 v197, v[178:179], s[56:57] sc0 sc1
	v_add_u32_e32 v197, 0x8000, v197
	ds_write_b32 v203, v20 offset:0
	ds_write_b32 v203, v21 offset:272
	ds_write_b32 v203, v22 offset:544
	ds_write_b32 v203, v23 offset:816
	ds_write_b32 v203, v24 offset:64
	ds_write_b32 v203, v25 offset:336
	ds_write_b32 v203, v26 offset:608
	ds_write_b32 v203, v27 offset:880
	ds_write_b32 v203, v28 offset:128
	ds_write_b32 v203, v29 offset:400
	ds_write_b32 v203, v30 offset:672
	ds_write_b32 v203, v31 offset:944
	ds_write_b32 v203, v32 offset:192
	ds_write_b32 v203, v33 offset:464
	ds_write_b32 v203, v34 offset:736
	ds_write_b32 v203, v35 offset:1008
	s_waitcnt lgkmcnt(0)
	ds_read_b128 v[156:159], v204 offset:0
	ds_read_b128 v[160:163], v204 offset:1088
	ds_read_b128 v[164:167], v204 offset:2176
	ds_read_b128 v[168:171], v204 offset:3264
	s_waitcnt lgkmcnt(3)
	v_max_f32_e32 v156, 0, v156
	v_max_f32_e32 v157, 0, v157
	v_max_f32_e32 v158, 0, v158
	v_max_f32_e32 v159, 0, v159
	v_mul_f32_e32 v156, v156, v156
	v_mul_f32_e32 v157, v157, v157
	v_mul_f32_e32 v158, v158, v158
	v_mul_f32_e32 v159, v159, v159
	v_cvt_pk_bf16_f32 v176, v156, v157
	v_cvt_pk_bf16_f32 v177, v158, v159
	global_store_dwordx2 v197, v[176:177], s[56:57] sc0 sc1
	v_add_u32_e32 v197, 0x8000, v197
	s_waitcnt lgkmcnt(2)
	v_max_f32_e32 v160, 0, v160
	v_max_f32_e32 v161, 0, v161
	v_max_f32_e32 v162, 0, v162
	v_max_f32_e32 v163, 0, v163
	v_mul_f32_e32 v160, v160, v160
	v_mul_f32_e32 v161, v161, v161
	v_mul_f32_e32 v162, v162, v162
	v_mul_f32_e32 v163, v163, v163
	v_cvt_pk_bf16_f32 v178, v160, v161
	v_cvt_pk_bf16_f32 v179, v162, v163
	global_store_dwordx2 v197, v[178:179], s[56:57] sc0 sc1
	v_add_u32_e32 v197, 0x8000, v197
	s_waitcnt lgkmcnt(1)
	v_max_f32_e32 v164, 0, v164
	v_max_f32_e32 v165, 0, v165
	v_max_f32_e32 v166, 0, v166
	v_max_f32_e32 v167, 0, v167
	v_mul_f32_e32 v164, v164, v164
	v_mul_f32_e32 v165, v165, v165
	v_mul_f32_e32 v166, v166, v166
	v_mul_f32_e32 v167, v167, v167
	v_cvt_pk_bf16_f32 v176, v164, v165
	v_cvt_pk_bf16_f32 v177, v166, v167
	global_store_dwordx2 v197, v[176:177], s[56:57] sc0 sc1
	v_add_u32_e32 v197, 0x8000, v197
	s_waitcnt lgkmcnt(0)
	v_max_f32_e32 v168, 0, v168
	v_max_f32_e32 v169, 0, v169
	v_max_f32_e32 v170, 0, v170
	v_max_f32_e32 v171, 0, v171
	v_mul_f32_e32 v168, v168, v168
	v_mul_f32_e32 v169, v169, v169
	v_mul_f32_e32 v170, v170, v170
	v_mul_f32_e32 v171, v171, v171
	v_cvt_pk_bf16_f32 v178, v168, v169
	v_cvt_pk_bf16_f32 v179, v170, v171
	global_store_dwordx2 v197, v[178:179], s[56:57] sc0 sc1
	v_add_u32_e32 v197, 0x8000, v197
	ds_write_b32 v203, v36 offset:0
	ds_write_b32 v203, v37 offset:272
	ds_write_b32 v203, v38 offset:544
	ds_write_b32 v203, v39 offset:816
	ds_write_b32 v203, v40 offset:64
	ds_write_b32 v203, v41 offset:336
	ds_write_b32 v203, v42 offset:608
	ds_write_b32 v203, v43 offset:880
	ds_write_b32 v203, v44 offset:128
	ds_write_b32 v203, v45 offset:400
	ds_write_b32 v203, v46 offset:672
	ds_write_b32 v203, v47 offset:944
	ds_write_b32 v203, v48 offset:192
	ds_write_b32 v203, v49 offset:464
	ds_write_b32 v203, v50 offset:736
	ds_write_b32 v203, v51 offset:1008
	s_waitcnt lgkmcnt(0)
	ds_read_b128 v[156:159], v204 offset:0
	ds_read_b128 v[160:163], v204 offset:1088
	ds_read_b128 v[164:167], v204 offset:2176
	ds_read_b128 v[168:171], v204 offset:3264
	s_waitcnt lgkmcnt(3)
	v_max_f32_e32 v156, 0, v156
	v_max_f32_e32 v157, 0, v157
	v_max_f32_e32 v158, 0, v158
	v_max_f32_e32 v159, 0, v159
	v_mul_f32_e32 v156, v156, v156
	v_mul_f32_e32 v157, v157, v157
	v_mul_f32_e32 v158, v158, v158
	v_mul_f32_e32 v159, v159, v159
	v_cvt_pk_bf16_f32 v176, v156, v157
	v_cvt_pk_bf16_f32 v177, v158, v159
	global_store_dwordx2 v197, v[176:177], s[56:57] sc0 sc1
	v_add_u32_e32 v197, 0x8000, v197
	s_waitcnt lgkmcnt(2)
	v_max_f32_e32 v160, 0, v160
	v_max_f32_e32 v161, 0, v161
	v_max_f32_e32 v162, 0, v162
	v_max_f32_e32 v163, 0, v163
	v_mul_f32_e32 v160, v160, v160
	v_mul_f32_e32 v161, v161, v161
	v_mul_f32_e32 v162, v162, v162
	v_mul_f32_e32 v163, v163, v163
	v_cvt_pk_bf16_f32 v178, v160, v161
	v_cvt_pk_bf16_f32 v179, v162, v163
	global_store_dwordx2 v197, v[178:179], s[56:57] sc0 sc1
	v_add_u32_e32 v197, 0x8000, v197
	s_waitcnt lgkmcnt(1)
	v_max_f32_e32 v164, 0, v164
	v_max_f32_e32 v165, 0, v165
	v_max_f32_e32 v166, 0, v166
	v_max_f32_e32 v167, 0, v167
	v_mul_f32_e32 v164, v164, v164
	v_mul_f32_e32 v165, v165, v165
	v_mul_f32_e32 v166, v166, v166
	v_mul_f32_e32 v167, v167, v167
	v_cvt_pk_bf16_f32 v176, v164, v165
	v_cvt_pk_bf16_f32 v177, v166, v167
	global_store_dwordx2 v197, v[176:177], s[56:57] sc0 sc1
	v_add_u32_e32 v197, 0x8000, v197
	s_waitcnt lgkmcnt(0)
	v_max_f32_e32 v168, 0, v168
	v_max_f32_e32 v169, 0, v169
	v_max_f32_e32 v170, 0, v170
	v_max_f32_e32 v171, 0, v171
	v_mul_f32_e32 v168, v168, v168
	v_mul_f32_e32 v169, v169, v169
	v_mul_f32_e32 v170, v170, v170
	v_mul_f32_e32 v171, v171, v171
	v_cvt_pk_bf16_f32 v178, v168, v169
	v_cvt_pk_bf16_f32 v179, v170, v171
	global_store_dwordx2 v197, v[178:179], s[56:57] sc0 sc1
	v_add_u32_e32 v197, 0x8000, v197
	ds_write_b32 v203, v52 offset:0
	ds_write_b32 v203, v53 offset:272
	ds_write_b32 v203, v54 offset:544
	ds_write_b32 v203, v55 offset:816
	ds_write_b32 v203, v56 offset:64
	ds_write_b32 v203, v57 offset:336
	ds_write_b32 v203, v58 offset:608
	ds_write_b32 v203, v59 offset:880
	ds_write_b32 v203, v60 offset:128
	ds_write_b32 v203, v61 offset:400
	ds_write_b32 v203, v62 offset:672
	ds_write_b32 v203, v63 offset:944
	ds_write_b32 v203, v64 offset:192
	ds_write_b32 v203, v65 offset:464
	ds_write_b32 v203, v66 offset:736
	ds_write_b32 v203, v67 offset:1008
	s_waitcnt lgkmcnt(0)
	ds_read_b128 v[156:159], v204 offset:0
	ds_read_b128 v[160:163], v204 offset:1088
	ds_read_b128 v[164:167], v204 offset:2176
	ds_read_b128 v[168:171], v204 offset:3264
	s_waitcnt lgkmcnt(3)
	v_max_f32_e32 v156, 0, v156
	v_max_f32_e32 v157, 0, v157
	v_max_f32_e32 v158, 0, v158
	v_max_f32_e32 v159, 0, v159
	v_mul_f32_e32 v156, v156, v156
	v_mul_f32_e32 v157, v157, v157
	v_mul_f32_e32 v158, v158, v158
	v_mul_f32_e32 v159, v159, v159
	v_cvt_pk_bf16_f32 v176, v156, v157
	v_cvt_pk_bf16_f32 v177, v158, v159
	global_store_dwordx2 v197, v[176:177], s[56:57] sc0 sc1
	v_add_u32_e32 v197, 0x8000, v197
	s_waitcnt lgkmcnt(2)
	v_max_f32_e32 v160, 0, v160
	v_max_f32_e32 v161, 0, v161
	v_max_f32_e32 v162, 0, v162
	v_max_f32_e32 v163, 0, v163
	v_mul_f32_e32 v160, v160, v160
	v_mul_f32_e32 v161, v161, v161
	v_mul_f32_e32 v162, v162, v162
	v_mul_f32_e32 v163, v163, v163
	v_cvt_pk_bf16_f32 v178, v160, v161
	v_cvt_pk_bf16_f32 v179, v162, v163
	global_store_dwordx2 v197, v[178:179], s[56:57] sc0 sc1
	v_add_u32_e32 v197, 0x8000, v197
	s_waitcnt lgkmcnt(1)
	v_max_f32_e32 v164, 0, v164
	v_max_f32_e32 v165, 0, v165
	v_max_f32_e32 v166, 0, v166
	v_max_f32_e32 v167, 0, v167
	v_mul_f32_e32 v164, v164, v164
	v_mul_f32_e32 v165, v165, v165
	v_mul_f32_e32 v166, v166, v166
	v_mul_f32_e32 v167, v167, v167
	v_cvt_pk_bf16_f32 v176, v164, v165
	v_cvt_pk_bf16_f32 v177, v166, v167
	global_store_dwordx2 v197, v[176:177], s[56:57] sc0 sc1
	v_add_u32_e32 v197, 0x8000, v197
	s_waitcnt lgkmcnt(0)
	v_max_f32_e32 v168, 0, v168
	v_max_f32_e32 v169, 0, v169
	v_max_f32_e32 v170, 0, v170
	v_max_f32_e32 v171, 0, v171
	v_mul_f32_e32 v168, v168, v168
	v_mul_f32_e32 v169, v169, v169
	v_mul_f32_e32 v170, v170, v170
	v_mul_f32_e32 v171, v171, v171
	v_cvt_pk_bf16_f32 v178, v168, v169
	v_cvt_pk_bf16_f32 v179, v170, v171
	global_store_dwordx2 v197, v[178:179], s[56:57] sc0 sc1
	v_add_u32_e32 v197, 0x8000, v197
	ds_write_b32 v203, v68 offset:0
	ds_write_b32 v203, v69 offset:272
	ds_write_b32 v203, v70 offset:544
	ds_write_b32 v203, v71 offset:816
	ds_write_b32 v203, v72 offset:64
	ds_write_b32 v203, v73 offset:336
	ds_write_b32 v203, v74 offset:608
	ds_write_b32 v203, v75 offset:880
	ds_write_b32 v203, v76 offset:128
	ds_write_b32 v203, v77 offset:400
	ds_write_b32 v203, v78 offset:672
	ds_write_b32 v203, v79 offset:944
	ds_write_b32 v203, v80 offset:192
	ds_write_b32 v203, v81 offset:464
	ds_write_b32 v203, v82 offset:736
	ds_write_b32 v203, v83 offset:1008
	s_waitcnt lgkmcnt(0)
	ds_read_b128 v[156:159], v204 offset:0
	ds_read_b128 v[160:163], v204 offset:1088
	ds_read_b128 v[164:167], v204 offset:2176
	ds_read_b128 v[168:171], v204 offset:3264
	s_waitcnt lgkmcnt(3)
	v_max_f32_e32 v156, 0, v156
	v_max_f32_e32 v157, 0, v157
	v_max_f32_e32 v158, 0, v158
	v_max_f32_e32 v159, 0, v159
	v_mul_f32_e32 v156, v156, v156
	v_mul_f32_e32 v157, v157, v157
	v_mul_f32_e32 v158, v158, v158
	v_mul_f32_e32 v159, v159, v159
	v_cvt_pk_bf16_f32 v176, v156, v157
	v_cvt_pk_bf16_f32 v177, v158, v159
	global_store_dwordx2 v197, v[176:177], s[56:57] sc0 sc1
	v_add_u32_e32 v197, 0x8000, v197
	s_waitcnt lgkmcnt(2)
	v_max_f32_e32 v160, 0, v160
	v_max_f32_e32 v161, 0, v161
	v_max_f32_e32 v162, 0, v162
	v_max_f32_e32 v163, 0, v163
	v_mul_f32_e32 v160, v160, v160
	v_mul_f32_e32 v161, v161, v161
	v_mul_f32_e32 v162, v162, v162
	v_mul_f32_e32 v163, v163, v163
	v_cvt_pk_bf16_f32 v178, v160, v161
	v_cvt_pk_bf16_f32 v179, v162, v163
	global_store_dwordx2 v197, v[178:179], s[56:57] sc0 sc1
	v_add_u32_e32 v197, 0x8000, v197
	s_waitcnt lgkmcnt(1)
	v_max_f32_e32 v164, 0, v164
	v_max_f32_e32 v165, 0, v165
	v_max_f32_e32 v166, 0, v166
	v_max_f32_e32 v167, 0, v167
	v_mul_f32_e32 v164, v164, v164
	v_mul_f32_e32 v165, v165, v165
	v_mul_f32_e32 v166, v166, v166
	v_mul_f32_e32 v167, v167, v167
	v_cvt_pk_bf16_f32 v176, v164, v165
	v_cvt_pk_bf16_f32 v177, v166, v167
	global_store_dwordx2 v197, v[176:177], s[56:57] sc0 sc1
	v_add_u32_e32 v197, 0x8000, v197
	s_waitcnt lgkmcnt(0)
	v_max_f32_e32 v168, 0, v168
	v_max_f32_e32 v169, 0, v169
	v_max_f32_e32 v170, 0, v170
	v_max_f32_e32 v171, 0, v171
	v_mul_f32_e32 v168, v168, v168
	v_mul_f32_e32 v169, v169, v169
	v_mul_f32_e32 v170, v170, v170
	v_mul_f32_e32 v171, v171, v171
	v_cvt_pk_bf16_f32 v178, v168, v169
	v_cvt_pk_bf16_f32 v179, v170, v171
	global_store_dwordx2 v197, v[178:179], s[56:57] sc0 sc1
	v_add_u32_e32 v197, 0x8000, v197
	ds_write_b32 v203, v84 offset:0
	ds_write_b32 v203, v85 offset:272
	ds_write_b32 v203, v86 offset:544
	ds_write_b32 v203, v87 offset:816
	ds_write_b32 v203, v88 offset:64
	ds_write_b32 v203, v89 offset:336
	ds_write_b32 v203, v90 offset:608
	ds_write_b32 v203, v91 offset:880
	ds_write_b32 v203, v92 offset:128
	ds_write_b32 v203, v93 offset:400
	ds_write_b32 v203, v94 offset:672
	ds_write_b32 v203, v95 offset:944
	ds_write_b32 v203, v96 offset:192
	ds_write_b32 v203, v97 offset:464
	ds_write_b32 v203, v98 offset:736
	ds_write_b32 v203, v99 offset:1008
	s_waitcnt lgkmcnt(0)
	ds_read_b128 v[156:159], v204 offset:0
	ds_read_b128 v[160:163], v204 offset:1088
	ds_read_b128 v[164:167], v204 offset:2176
	ds_read_b128 v[168:171], v204 offset:3264
	s_waitcnt lgkmcnt(3)
	v_max_f32_e32 v156, 0, v156
	v_max_f32_e32 v157, 0, v157
	v_max_f32_e32 v158, 0, v158
	v_max_f32_e32 v159, 0, v159
	v_mul_f32_e32 v156, v156, v156
	v_mul_f32_e32 v157, v157, v157
	v_mul_f32_e32 v158, v158, v158
	v_mul_f32_e32 v159, v159, v159
	v_cvt_pk_bf16_f32 v176, v156, v157
	v_cvt_pk_bf16_f32 v177, v158, v159
	global_store_dwordx2 v197, v[176:177], s[56:57] sc0 sc1
	v_add_u32_e32 v197, 0x8000, v197
	s_waitcnt lgkmcnt(2)
	v_max_f32_e32 v160, 0, v160
	v_max_f32_e32 v161, 0, v161
	v_max_f32_e32 v162, 0, v162
	v_max_f32_e32 v163, 0, v163
	v_mul_f32_e32 v160, v160, v160
	v_mul_f32_e32 v161, v161, v161
	v_mul_f32_e32 v162, v162, v162
	v_mul_f32_e32 v163, v163, v163
	v_cvt_pk_bf16_f32 v178, v160, v161
	v_cvt_pk_bf16_f32 v179, v162, v163
	global_store_dwordx2 v197, v[178:179], s[56:57] sc0 sc1
	v_add_u32_e32 v197, 0x8000, v197
	s_waitcnt lgkmcnt(1)
	v_max_f32_e32 v164, 0, v164
	v_max_f32_e32 v165, 0, v165
	v_max_f32_e32 v166, 0, v166
	v_max_f32_e32 v167, 0, v167
	v_mul_f32_e32 v164, v164, v164
	v_mul_f32_e32 v165, v165, v165
	v_mul_f32_e32 v166, v166, v166
	v_mul_f32_e32 v167, v167, v167
	v_cvt_pk_bf16_f32 v176, v164, v165
	v_cvt_pk_bf16_f32 v177, v166, v167
	global_store_dwordx2 v197, v[176:177], s[56:57] sc0 sc1
	v_add_u32_e32 v197, 0x8000, v197
	s_waitcnt lgkmcnt(0)
	v_max_f32_e32 v168, 0, v168
	v_max_f32_e32 v169, 0, v169
	v_max_f32_e32 v170, 0, v170
	v_max_f32_e32 v171, 0, v171
	v_mul_f32_e32 v168, v168, v168
	v_mul_f32_e32 v169, v169, v169
	v_mul_f32_e32 v170, v170, v170
	v_mul_f32_e32 v171, v171, v171
	v_cvt_pk_bf16_f32 v178, v168, v169
	v_cvt_pk_bf16_f32 v179, v170, v171
	global_store_dwordx2 v197, v[178:179], s[56:57] sc0 sc1
	v_add_u32_e32 v197, 0x8000, v197
	v_mov_b32_e32 v4, 0
	v_mov_b32_e32 v5, 0
	v_mov_b32_e32 v6, 0
	v_mov_b32_e32 v7, 0
	v_mov_b32_e32 v8, 0
	v_mov_b32_e32 v9, 0
	v_mov_b32_e32 v10, 0
	v_mov_b32_e32 v11, 0
	v_mov_b32_e32 v12, 0
	v_mov_b32_e32 v13, 0
	v_mov_b32_e32 v14, 0
	v_mov_b32_e32 v15, 0
	v_mov_b32_e32 v16, 0
	v_mov_b32_e32 v17, 0
	v_mov_b32_e32 v18, 0
	v_mov_b32_e32 v19, 0
	v_mov_b32_e32 v20, 0
	v_mov_b32_e32 v21, 0
	v_mov_b32_e32 v22, 0
	v_mov_b32_e32 v23, 0
	v_mov_b32_e32 v24, 0
	v_mov_b32_e32 v25, 0
	v_mov_b32_e32 v26, 0
	v_mov_b32_e32 v27, 0
	v_mov_b32_e32 v28, 0
	v_mov_b32_e32 v29, 0
	v_mov_b32_e32 v30, 0
	v_mov_b32_e32 v31, 0
	v_mov_b32_e32 v32, 0
	v_mov_b32_e32 v33, 0
	v_mov_b32_e32 v34, 0
	v_mov_b32_e32 v35, 0
	v_mov_b32_e32 v36, 0
	v_mov_b32_e32 v37, 0
	v_mov_b32_e32 v38, 0
	v_mov_b32_e32 v39, 0
	v_mov_b32_e32 v40, 0
	v_mov_b32_e32 v41, 0
	v_mov_b32_e32 v42, 0
	v_mov_b32_e32 v43, 0
	v_mov_b32_e32 v44, 0
	v_mov_b32_e32 v45, 0
	v_mov_b32_e32 v46, 0
	v_mov_b32_e32 v47, 0
	v_mov_b32_e32 v48, 0
	v_mov_b32_e32 v49, 0
	v_mov_b32_e32 v50, 0
	v_mov_b32_e32 v51, 0
	v_mov_b32_e32 v52, 0
	v_mov_b32_e32 v53, 0
	v_mov_b32_e32 v54, 0
	v_mov_b32_e32 v55, 0
	v_mov_b32_e32 v56, 0
	v_mov_b32_e32 v57, 0
	v_mov_b32_e32 v58, 0
	v_mov_b32_e32 v59, 0
	v_mov_b32_e32 v60, 0
	v_mov_b32_e32 v61, 0
	v_mov_b32_e32 v62, 0
	v_mov_b32_e32 v63, 0
	v_mov_b32_e32 v64, 0
	v_mov_b32_e32 v65, 0
	v_mov_b32_e32 v66, 0
	v_mov_b32_e32 v67, 0
	v_mov_b32_e32 v68, 0
	v_mov_b32_e32 v69, 0
	v_mov_b32_e32 v70, 0
	v_mov_b32_e32 v71, 0
	v_mov_b32_e32 v72, 0
	v_mov_b32_e32 v73, 0
	v_mov_b32_e32 v74, 0
	v_mov_b32_e32 v75, 0
	v_mov_b32_e32 v76, 0
	v_mov_b32_e32 v77, 0
	v_mov_b32_e32 v78, 0
	v_mov_b32_e32 v79, 0
	v_mov_b32_e32 v80, 0
	v_mov_b32_e32 v81, 0
	v_mov_b32_e32 v82, 0
	v_mov_b32_e32 v83, 0
	v_mov_b32_e32 v84, 0
	v_mov_b32_e32 v85, 0
	v_mov_b32_e32 v86, 0
	v_mov_b32_e32 v87, 0
	v_mov_b32_e32 v88, 0
	v_mov_b32_e32 v89, 0
	v_mov_b32_e32 v90, 0
	v_mov_b32_e32 v91, 0
	v_mov_b32_e32 v92, 0
	v_mov_b32_e32 v93, 0
	v_mov_b32_e32 v94, 0
	v_mov_b32_e32 v95, 0
	v_mov_b32_e32 v96, 0
	v_mov_b32_e32 v97, 0
	v_mov_b32_e32 v98, 0
	v_mov_b32_e32 v99, 0
	s_mov_b32 s34, 0
	s_add_u32 s35, s35, s52
	s_cmp_ge_u32 s31, s30
	s_cbranch_scc1 .Lgm_f1_exit
.Lgm_f1_rot:
	s_add_u32 s40, s40, 0xa000
	s_mov_b32 s4, 0xa000
	s_cmp_ge_u32 s40, 0x1e000
	s_cselect_b32 s4, 0xfffec000, s4
	s_cselect_b32 s40, 0, s40
	v_add_u32_e32 v199, s4, v199
	v_add_u32_e32 v200, s4, v200
	v_add_u32_e32 v201, s4, v201
	v_add_u32_e32 v202, s4, v202
	s_branch .Lgm_f1_loop

.Lgm_f2_cnt:
	s_add_u32 s30, s30, 64
	s_add_u32 s4, s4, s52
	s_cmp_lt_u32 s4, s54
	s_cbranch_scc1 .Lgm_f2_cnt
	s_add_u32 s48, s96, 0x3a24000
	s_addc_u32 s49, s97, 0
	s_mul_i32 s4, s36, 0x800000
	s_add_u32 s50, s96, 0x1d80000
	s_addc_u32 s51, s97, 0
	s_add_u32 s50, s50, s4
	s_addc_u32 s51, s51, 0
	v_and_b32_e32 v0, 63, v206
	v_lshrrev_b32_e32 v1, 6, v206
	s_mov_b32 s31, 0
	v_readfirstlane_b32 s42, v1
	s_nop 0
	s_cmp_ge_u32 s42, 4
	s_cbranch_scc1 .Lgm_f2_compute
	v_lshrrev_b32_e32 v3, 3, v0
	v_and_b32_e32 v4, 7, v0
	v_xor_b32_e32 v4, v4, v3
	v_lshl_add_u32 v3, v1, 3, v3
	v_lshlrev_b32_e32 v3, 13, v3
	v_lshl_add_u32 v180, v4, 4, v3
	v_add_u32_e32 v181, 0x40000, v180
	v_add_u32_e32 v182, 0x80000, v180
	v_add_u32_e32 v183, 0xc0000, v180
	v_add_u32_e32 v184, 0x100000, v180
	v_add_u32_e32 v185, 0x140000, v180
	s_lshl_b32 s42, s42, 10
	s_mov_b32 s38, s53
	s_mov_b32 s39, 0
	s_mov_b32 s41, s42
	s_and_b32 s4, s38, 31
	s_mul_i32 s4, s4, 0x180000
	s_add_u32 s44, s48, s4
	s_addc_u32 s45, s49, 0
	s_lshr_b32 s4, s38, 5
	s_mul_i32 s4, s4, 0x100000
	s_add_u32 s46, s50, s4
	s_addc_u32 s47, s51, 0
	s_add_u32 m0, s41, 0x0
	s_nop 0
	global_load_lds_dwordx4 v180, s[44:45]
	s_add_u32 m0, s41, 0x1000
	s_nop 0
	global_load_lds_dwordx4 v181, s[44:45]
	s_add_u32 m0, s41, 0x2000
	s_nop 0
	global_load_lds_dwordx4 v182, s[44:45]
	s_add_u32 m0, s41, 0x3000
	s_nop 0
	global_load_lds_dwordx4 v183, s[44:45]
	s_add_u32 m0, s41, 0x4000
	s_nop 0
	global_load_lds_dwordx4 v184, s[44:45]
	s_add_u32 m0, s41, 0x5000
	s_nop 0
	global_load_lds_dwordx4 v185, s[44:45]
	s_add_u32 m0, s41, 0x6000
	s_nop 0
	global_load_lds_dwordx4 v180, s[46:47]
	s_add_u32 m0, s41, 0x7000
	s_nop 0
	global_load_lds_dwordx4 v181, s[46:47]
	s_add_u32 m0, s41, 0x8000
	s_nop 0
	global_load_lds_dwordx4 v182, s[46:47]
	s_add_u32 m0, s41, 0x9000
	s_nop 0
	global_load_lds_dwordx4 v183, s[46:47]
	s_add_u32 s39, s39, 1
	s_add_u32 s44, s44, 0x80
	s_addc_u32 s45, s45, 0
	s_add_u32 s46, s46, 0x80
	s_addc_u32 s47, s47, 0
	s_cmp_lt_u32 s39, 64
	s_cbranch_scc1 .Lgm_f2_dadv1
	s_mov_b32 s39, 0
	s_add_u32 s4, s38, s52
	s_cmp_lt_u32 s4, s54
	s_cselect_b32 s38, s4, s38
	s_and_b32 s4, s38, 31
	s_mul_i32 s4, s4, 0x180000
	s_add_u32 s44, s48, s4
	s_addc_u32 s45, s49, 0
	s_lshr_b32 s4, s38, 5
	s_mul_i32 s4, s4, 0x100000
	s_add_u32 s46, s50, s4
	s_addc_u32 s47, s51, 0
.Lgm_f2_dadv1:
	s_add_u32 s41, s41, 0xa000
	s_sub_u32 s4, s41, 0x1e000
	s_cmp_ge_u32 s41, 0x1e000
	s_cselect_b32 s41, s4, s41
	s_add_u32 m0, s41, 0x0
	s_nop 0
	global_load_lds_dwordx4 v180, s[44:45]
	s_add_u32 m0, s41, 0x1000
	s_nop 0
	global_load_lds_dwordx4 v181, s[44:45]
	s_add_u32 m0, s41, 0x2000
	s_nop 0
	global_load_lds_dwordx4 v182, s[44:45]
	s_add_u32 m0, s41, 0x3000
	s_nop 0
	global_load_lds_dwordx4 v183, s[44:45]
	s_add_u32 m0, s41, 0x4000
	s_nop 0
	global_load_lds_dwordx4 v184, s[44:45]
	s_add_u32 m0, s41, 0x5000
	s_nop 0
	global_load_lds_dwordx4 v185, s[44:45]
	s_add_u32 m0, s41, 0x6000
	s_nop 0
	global_load_lds_dwordx4 v180, s[46:47]
	s_add_u32 m0, s41, 0x7000
	s_nop 0
	global_load_lds_dwordx4 v181, s[46:47]
	s_add_u32 m0, s41, 0x8000
	s_nop 0
	global_load_lds_dwordx4 v182, s[46:47]
	s_add_u32 m0, s41, 0x9000
	s_nop 0
	global_load_lds_dwordx4 v183, s[46:47]
	s_add_u32 s39, s39, 1
	s_add_u32 s44, s44, 0x80
	s_addc_u32 s45, s45, 0
	s_add_u32 s46, s46, 0x80
	s_addc_u32 s47, s47, 0
	s_cmp_lt_u32 s39, 64
	s_cbranch_scc1 .Lgm_f2_dadv2
	s_mov_b32 s39, 0
	s_add_u32 s4, s38, s52
	s_cmp_lt_u32 s4, s54
	s_cselect_b32 s38, s4, s38
	s_and_b32 s4, s38, 31
	s_mul_i32 s4, s4, 0x180000
	s_add_u32 s44, s48, s4
	s_addc_u32 s45, s49, 0
	s_lshr_b32 s4, s38, 5
	s_mul_i32 s4, s4, 0x100000
	s_add_u32 s46, s50, s4
	s_addc_u32 s47, s51, 0

.Lgm_f2_ld_loop:
	s_barrier
	s_add_u32 m0, s41, 0x0
	s_nop 0
	global_load_lds_dwordx4 v180, s[44:45]
	s_add_u32 m0, s41, 0x1000
	s_nop 0
	global_load_lds_dwordx4 v181, s[44:45]
	s_add_u32 m0, s41, 0x2000
	s_nop 0
	global_load_lds_dwordx4 v182, s[44:45]
	s_add_u32 m0, s41, 0x3000
	s_nop 0
	global_load_lds_dwordx4 v183, s[44:45]
	s_add_u32 m0, s41, 0x4000
	s_nop 0
	global_load_lds_dwordx4 v184, s[44:45]
	s_add_u32 m0, s41, 0x5000
	s_nop 0
	global_load_lds_dwordx4 v185, s[44:45]
	s_add_u32 m0, s41, 0x6000
	s_nop 0
	global_load_lds_dwordx4 v180, s[46:47]
	s_add_u32 m0, s41, 0x7000
	s_nop 0
	global_load_lds_dwordx4 v181, s[46:47]
	s_add_u32 m0, s41, 0x8000
	s_nop 0
	global_load_lds_dwordx4 v182, s[46:47]
	s_add_u32 m0, s41, 0x9000
	s_nop 0
	global_load_lds_dwordx4 v183, s[46:47]
	s_add_u32 s39, s39, 1
	s_add_u32 s44, s44, 0x80
	s_addc_u32 s45, s45, 0
	s_add_u32 s46, s46, 0x80
	s_addc_u32 s47, s47, 0
	s_cmp_lt_u32 s39, 64
	s_cbranch_scc1 .Lgm_f2_dadv3
	s_mov_b32 s39, 0
	s_add_u32 s4, s38, s52
	s_cmp_lt_u32 s4, s54
	s_cselect_b32 s38, s4, s38
	s_and_b32 s4, s38, 31
	s_mul_i32 s4, s4, 0x180000
	s_add_u32 s44, s48, s4
	s_addc_u32 s45, s49, 0
	s_lshr_b32 s4, s38, 5
	s_mul_i32 s4, s4, 0x100000
	s_add_u32 s46, s50, s4
	s_addc_u32 s47, s51, 0

.Lgm_f2_compute:
	v_and_b32_e32 v1, 3, v1
	v_and_b32_e32 v194, 15, v0
	v_lshrrev_b32_e32 v195, 4, v0
	v_and_b32_e32 v3, 7, v194
	v_xor_b32_e32 v3, v3, v195
	v_lshlrev_b32_e32 v3, 4, v3
	v_lshrrev_b32_e32 v176, 1, v1
	v_and_b32_e32 v177, 1, v1
	v_mul_u32_u24_e32 v178, 96, v176
	v_add_u32_e32 v179, v178, v194
	v_lshl_add_u32 v199, v179, 7, v3
	v_xor_b32_e32 v200, 64, v199
	v_lshl_add_u32 v179, v177, 6, v194
	v_lshl_add_u32 v201, v179, 7, v3
	v_add_u32_e32 v201, 0x6000, v201
	v_xor_b32_e32 v202, 64, v201
	s_sub_u32 s42, s42, 4
	s_mul_i32 s5, s42, 4352
	s_add_u32 s5, s5, 0x1e000
	v_mul_u32_u24_e32 v3, 1088, v195
	v_lshl_add_u32 v3, v194, 2, v3
	v_add_u32_e32 v203, s5, v3
	v_mul_u32_u24_e32 v3, 272, v195
	v_lshl_add_u32 v3, v194, 4, v3
	v_add_u32_e32 v204, s5, v3
	v_add_u32_e32 v190, v178, v195
	v_lshlrev_b32_e32 v3, 6, v177
	v_lshl_add_u32 v3, v194, 2, v3
	s_mov_b32 s4, 0x1000
	v_mul_lo_u32 v205, v190, s4
	v_lshl_add_u32 v205, v3, 2, v205
	v_lshlrev_b32_e32 v191, 2, v3
	v_mov_b32_e32 v193, v3
	v_mov_b32_e32 v4, 0
	v_mov_b32_e32 v5, 0
	v_mov_b32_e32 v6, 0
	v_mov_b32_e32 v7, 0
	v_mov_b32_e32 v8, 0
	v_mov_b32_e32 v9, 0
	v_mov_b32_e32 v10, 0
	v_mov_b32_e32 v11, 0
	v_mov_b32_e32 v12, 0
	v_mov_b32_e32 v13, 0
	v_mov_b32_e32 v14, 0
	v_mov_b32_e32 v15, 0
	v_mov_b32_e32 v16, 0
	v_mov_b32_e32 v17, 0
	v_mov_b32_e32 v18, 0
	v_mov_b32_e32 v19, 0
	v_mov_b32_e32 v20, 0
	v_mov_b32_e32 v21, 0
	v_mov_b32_e32 v22, 0
	v_mov_b32_e32 v23, 0
	v_mov_b32_e32 v24, 0
	v_mov_b32_e32 v25, 0
	v_mov_b32_e32 v26, 0
	v_mov_b32_e32 v27, 0
	v_mov_b32_e32 v28, 0
	v_mov_b32_e32 v29, 0
	v_mov_b32_e32 v30, 0
	v_mov_b32_e32 v31, 0
	v_mov_b32_e32 v32, 0
	v_mov_b32_e32 v33, 0
	v_mov_b32_e32 v34, 0
	v_mov_b32_e32 v35, 0
	v_mov_b32_e32 v36, 0
	v_mov_b32_e32 v37, 0
	v_mov_b32_e32 v38, 0
	v_mov_b32_e32 v39, 0
	v_mov_b32_e32 v40, 0
	v_mov_b32_e32 v41, 0
	v_mov_b32_e32 v42, 0
	v_mov_b32_e32 v43, 0
	v_mov_b32_e32 v44, 0
	v_mov_b32_e32 v45, 0
	v_mov_b32_e32 v46, 0
	v_mov_b32_e32 v47, 0
	v_mov_b32_e32 v48, 0
	v_mov_b32_e32 v49, 0
	v_mov_b32_e32 v50, 0
	v_mov_b32_e32 v51, 0
	v_mov_b32_e32 v52, 0
	v_mov_b32_e32 v53, 0
	v_mov_b32_e32 v54, 0
	v_mov_b32_e32 v55, 0
	v_mov_b32_e32 v56, 0
	v_mov_b32_e32 v57, 0
	v_mov_b32_e32 v58, 0
	v_mov_b32_e32 v59, 0
	v_mov_b32_e32 v60, 0
	v_mov_b32_e32 v61, 0
	v_mov_b32_e32 v62, 0
	v_mov_b32_e32 v63, 0
	v_mov_b32_e32 v64, 0
	v_mov_b32_e32 v65, 0
	v_mov_b32_e32 v66, 0
	v_mov_b32_e32 v67, 0
	v_mov_b32_e32 v68, 0
	v_mov_b32_e32 v69, 0
	v_mov_b32_e32 v70, 0
	v_mov_b32_e32 v71, 0
	v_mov_b32_e32 v72, 0
	v_mov_b32_e32 v73, 0
	v_mov_b32_e32 v74, 0
	v_mov_b32_e32 v75, 0
	v_mov_b32_e32 v76, 0
	v_mov_b32_e32 v77, 0
	v_mov_b32_e32 v78, 0
	v_mov_b32_e32 v79, 0
	v_mov_b32_e32 v80, 0
	v_mov_b32_e32 v81, 0
	v_mov_b32_e32 v82, 0
	v_mov_b32_e32 v83, 0
	v_mov_b32_e32 v84, 0
	v_mov_b32_e32 v85, 0
	v_mov_b32_e32 v86, 0
	v_mov_b32_e32 v87, 0
	v_mov_b32_e32 v88, 0
	v_mov_b32_e32 v89, 0
	v_mov_b32_e32 v90, 0
	v_mov_b32_e32 v91, 0
	v_mov_b32_e32 v92, 0
	v_mov_b32_e32 v93, 0
	v_mov_b32_e32 v94, 0
	v_mov_b32_e32 v95, 0
	v_mov_b32_e32 v96, 0
	v_mov_b32_e32 v97, 0
	v_mov_b32_e32 v98, 0
	v_mov_b32_e32 v99, 0
	s_mov_b32 s34, 0
	s_mov_b32 s35, s53
	s_mov_b32 s40, 0

.Lgm_f2_join:
	s_waitcnt lgkmcnt(13)
	v_mfma_f32_16x16x32_bf16 v[4:7], v[100:103], v[124:127], v[4:7]
	v_mfma_f32_16x16x32_bf16 v[20:23], v[104:107], v[124:127], v[20:23]
	v_mfma_f32_16x16x32_bf16 v[36:39], v[108:111], v[124:127], v[36:39]
	v_mfma_f32_16x16x32_bf16 v[52:55], v[112:115], v[124:127], v[52:55]
	v_mfma_f32_16x16x32_bf16 v[68:71], v[116:119], v[124:127], v[68:71]
	v_mfma_f32_16x16x32_bf16 v[84:87], v[120:123], v[124:127], v[84:87]
	s_waitcnt lgkmcnt(12)
	v_mfma_f32_16x16x32_bf16 v[8:11], v[100:103], v[128:131], v[8:11]
	v_mfma_f32_16x16x32_bf16 v[24:27], v[104:107], v[128:131], v[24:27]
	v_mfma_f32_16x16x32_bf16 v[40:43], v[108:111], v[128:131], v[40:43]
	v_mfma_f32_16x16x32_bf16 v[56:59], v[112:115], v[128:131], v[56:59]
	v_mfma_f32_16x16x32_bf16 v[72:75], v[116:119], v[128:131], v[72:75]
	v_mfma_f32_16x16x32_bf16 v[88:91], v[120:123], v[128:131], v[88:91]
	s_waitcnt lgkmcnt(11)
	v_mfma_f32_16x16x32_bf16 v[12:15], v[100:103], v[132:135], v[12:15]
	v_mfma_f32_16x16x32_bf16 v[28:31], v[104:107], v[132:135], v[28:31]
	v_mfma_f32_16x16x32_bf16 v[44:47], v[108:111], v[132:135], v[44:47]
	v_mfma_f32_16x16x32_bf16 v[60:63], v[112:115], v[132:135], v[60:63]
	v_mfma_f32_16x16x32_bf16 v[76:79], v[116:119], v[132:135], v[76:79]
	v_mfma_f32_16x16x32_bf16 v[92:95], v[120:123], v[132:135], v[92:95]
	s_waitcnt lgkmcnt(10)
	v_mfma_f32_16x16x32_bf16 v[16:19], v[100:103], v[136:139], v[16:19]
	v_mfma_f32_16x16x32_bf16 v[32:35], v[104:107], v[136:139], v[32:35]
	v_mfma_f32_16x16x32_bf16 v[48:51], v[108:111], v[136:139], v[48:51]
	v_mfma_f32_16x16x32_bf16 v[64:67], v[112:115], v[136:139], v[64:67]
	v_mfma_f32_16x16x32_bf16 v[80:83], v[116:119], v[136:139], v[80:83]
	v_mfma_f32_16x16x32_bf16 v[96:99], v[120:123], v[136:139], v[96:99]
	s_waitcnt lgkmcnt(0)
	s_add_u32 s34, s34, 1
	s_add_u32 s31, s31, 1
	s_cmp_lt_u32 s34, 64
	s_cbranch_scc1 .Lgm_f2_rot
	v_mfma_f32_16x16x32_bf16 v[4:7], v[140:143], v[164:167], v[4:7]
	v_mfma_f32_16x16x32_bf16 v[20:23], v[144:147], v[164:167], v[20:23]
	v_mfma_f32_16x16x32_bf16 v[36:39], v[148:151], v[164:167], v[36:39]
	v_mfma_f32_16x16x32_bf16 v[52:55], v[152:155], v[164:167], v[52:55]
	v_mfma_f32_16x16x32_bf16 v[68:71], v[156:159], v[164:167], v[68:71]
	v_mfma_f32_16x16x32_bf16 v[84:87], v[160:163], v[164:167], v[84:87]
	v_mfma_f32_16x16x32_bf16 v[8:11], v[140:143], v[168:171], v[8:11]
	v_mfma_f32_16x16x32_bf16 v[24:27], v[144:147], v[168:171], v[24:27]
	v_mfma_f32_16x16x32_bf16 v[40:43], v[148:151], v[168:171], v[40:43]
	v_mfma_f32_16x16x32_bf16 v[56:59], v[152:155], v[168:171], v[56:59]
	v_mfma_f32_16x16x32_bf16 v[72:75], v[156:159], v[168:171], v[72:75]
	v_mfma_f32_16x16x32_bf16 v[88:91], v[160:163], v[168:171], v[88:91]
	v_mfma_f32_16x16x32_bf16 v[12:15], v[140:143], v[172:175], v[12:15]
	v_mfma_f32_16x16x32_bf16 v[28:31], v[144:147], v[172:175], v[28:31]
	v_mfma_f32_16x16x32_bf16 v[44:47], v[148:151], v[172:175], v[44:47]
	v_mfma_f32_16x16x32_bf16 v[60:63], v[152:155], v[172:175], v[60:63]
	v_mfma_f32_16x16x32_bf16 v[76:79], v[156:159], v[172:175], v[76:79]
	v_mfma_f32_16x16x32_bf16 v[92:95], v[160:163], v[172:175], v[92:95]
	v_mfma_f32_16x16x32_bf16 v[16:19], v[140:143], v[176:179], v[16:19]
	v_mfma_f32_16x16x32_bf16 v[32:35], v[144:147], v[176:179], v[32:35]
	v_mfma_f32_16x16x32_bf16 v[48:51], v[148:151], v[176:179], v[48:51]
	v_mfma_f32_16x16x32_bf16 v[64:67], v[152:155], v[176:179], v[64:67]
	v_mfma_f32_16x16x32_bf16 v[80:83], v[156:159], v[176:179], v[80:83]
	v_mfma_f32_16x16x32_bf16 v[96:99], v[160:163], v[176:179], v[96:99]
	s_and_b32 s6, s35, 31
	s_mul_i32 s6, s6, 192
	s_lshr_b32 s7, s35, 5
	s_lshl_b32 s7, s7, 7
	s_nop 7
	s_mul_i32 s4, s6, 0x1000
	s_lshl_b32 s5, s7, 2
	s_add_u32 s4, s4, s5
	v_add_u32_e32 v197, s4, v205
	v_add_u32_e32 v192, s6, v190
	v_lshl_add_u32 v193, s7, 2, v191
	s_sub_i32 s4, s6, 0xc00
	s_max_i32 s4, s4, 0
	s_lshr_b32 s4, s4, 10
	s_add_i32 s5, s6, -2881
	s_max_i32 s5, s5, 0
	s_lshr_b32 s5, s5, 10
	s_movk_i32 s7, 0x1400
	s_cmp_eq_u32 s4, 0
	s_cselect_b32 s7, 0x1000, s7
	s_mul_i32 s4, s4, 0x6000
	s_mul_i32 s5, s5, 0x6000
	v_mov_b32_e32 v194, v197
	v_add_u32_e32 v195, 0, v192
	v_cmp_gt_u32_e32 vcc, 0x1000, v195
	v_mov_b32_e32 v0, s98
	v_mov_b32_e32 v1, s99
	v_mov_b32_e32 v3, s58
	v_cndmask_b32_e32 v0, v0, v3, vcc
	v_mov_b32_e32 v3, s59
	v_cndmask_b32_e32 v1, v1, v3, vcc
	v_add_co_u32_e32 v0, vcc, v0, v194
	s_nop 1
	v_addc_co_u32_e32 v1, vcc, 0, v1, vcc
	global_load_dwordx4 v[100:103], v[0:1], off
	v_add_u32_e32 v194, 0x4000, v194
	v_add_u32_e32 v195, 4, v192
	v_cmp_gt_u32_e32 vcc, 0x1000, v195
	v_mov_b32_e32 v0, s98
	v_mov_b32_e32 v1, s99
	v_mov_b32_e32 v3, s58
	v_cndmask_b32_e32 v0, v0, v3, vcc
	v_mov_b32_e32 v3, s59
	v_cndmask_b32_e32 v1, v1, v3, vcc
	v_add_co_u32_e32 v0, vcc, v0, v194
	s_nop 1
	v_addc_co_u32_e32 v1, vcc, 0, v1, vcc
	global_load_dwordx4 v[104:107], v[0:1], off
	v_add_u32_e32 v194, 0x4000, v194
	v_add_u32_e32 v195, 8, v192
	v_cmp_gt_u32_e32 vcc, 0x1000, v195
	v_mov_b32_e32 v0, s98
	v_mov_b32_e32 v1, s99
	v_mov_b32_e32 v3, s58
	v_cndmask_b32_e32 v0, v0, v3, vcc
	v_mov_b32_e32 v3, s59
	v_cndmask_b32_e32 v1, v1, v3, vcc
	v_add_co_u32_e32 v0, vcc, v0, v194
	s_nop 1
	v_addc_co_u32_e32 v1, vcc, 0, v1, vcc
	global_load_dwordx4 v[108:111], v[0:1], off
	v_add_u32_e32 v194, 0x4000, v194
	v_add_u32_e32 v195, 12, v192
	v_cmp_gt_u32_e32 vcc, 0x1000, v195
	v_mov_b32_e32 v0, s98
	v_mov_b32_e32 v1, s99
	v_mov_b32_e32 v3, s58
	v_cndmask_b32_e32 v0, v0, v3, vcc
	v_mov_b32_e32 v3, s59
	v_cndmask_b32_e32 v1, v1, v3, vcc
	v_add_co_u32_e32 v0, vcc, v0, v194
	s_nop 1
	v_addc_co_u32_e32 v1, vcc, 0, v1, vcc
	global_load_dwordx4 v[112:115], v[0:1], off
	v_add_u32_e32 v194, 0x4000, v194
	v_add_u32_e32 v195, 16, v192
	v_cmp_gt_u32_e32 vcc, 0x1000, v195
	v_mov_b32_e32 v0, s98
	v_mov_b32_e32 v1, s99
	v_mov_b32_e32 v3, s58
	v_cndmask_b32_e32 v0, v0, v3, vcc
	v_mov_b32_e32 v3, s59
	v_cndmask_b32_e32 v1, v1, v3, vcc
	v_add_co_u32_e32 v0, vcc, v0, v194
	s_nop 1
	v_addc_co_u32_e32 v1, vcc, 0, v1, vcc
	global_load_dwordx4 v[116:119], v[0:1], off
	v_add_u32_e32 v194, 0x4000, v194
	v_add_u32_e32 v195, 20, v192
	v_cmp_gt_u32_e32 vcc, 0x1000, v195
	v_mov_b32_e32 v0, s98
	v_mov_b32_e32 v1, s99
	v_mov_b32_e32 v3, s58
	v_cndmask_b32_e32 v0, v0, v3, vcc
	v_mov_b32_e32 v3, s59
	v_cndmask_b32_e32 v1, v1, v3, vcc
	v_add_co_u32_e32 v0, vcc, v0, v194
	s_nop 1
	v_addc_co_u32_e32 v1, vcc, 0, v1, vcc
	global_load_dwordx4 v[120:123], v[0:1], off
	v_add_u32_e32 v194, 0x4000, v194
	v_add_u32_e32 v195, 24, v192
	v_cmp_gt_u32_e32 vcc, 0x1000, v195
	v_mov_b32_e32 v0, s98
	v_mov_b32_e32 v1, s99
	v_mov_b32_e32 v3, s58
	v_cndmask_b32_e32 v0, v0, v3, vcc
	v_mov_b32_e32 v3, s59
	v_cndmask_b32_e32 v1, v1, v3, vcc
	v_add_co_u32_e32 v0, vcc, v0, v194
	s_nop 1
	v_addc_co_u32_e32 v1, vcc, 0, v1, vcc
	global_load_dwordx4 v[124:127], v[0:1], off
	v_add_u32_e32 v194, 0x4000, v194
	v_add_u32_e32 v195, 28, v192
	v_cmp_gt_u32_e32 vcc, 0x1000, v195
	v_mov_b32_e32 v0, s98
	v_mov_b32_e32 v1, s99
	v_mov_b32_e32 v3, s58
	v_cndmask_b32_e32 v0, v0, v3, vcc
	v_mov_b32_e32 v3, s59
	v_cndmask_b32_e32 v1, v1, v3, vcc
	v_add_co_u32_e32 v0, vcc, v0, v194
	s_nop 1
	v_addc_co_u32_e32 v1, vcc, 0, v1, vcc
	global_load_dwordx4 v[128:131], v[0:1], off
	v_add_u32_e32 v194, 0x4000, v194
	v_add_u32_e32 v195, 32, v192
	v_cmp_gt_u32_e32 vcc, 0x1000, v195
	v_mov_b32_e32 v0, s98
	v_mov_b32_e32 v1, s99
	v_mov_b32_e32 v3, s58
	v_cndmask_b32_e32 v0, v0, v3, vcc
	v_mov_b32_e32 v3, s59
	v_cndmask_b32_e32 v1, v1, v3, vcc
	v_add_co_u32_e32 v0, vcc, v0, v194
	s_nop 1
	v_addc_co_u32_e32 v1, vcc, 0, v1, vcc
	global_load_dwordx4 v[132:135], v[0:1], off
	v_add_u32_e32 v194, 0x4000, v194
	v_add_u32_e32 v195, 36, v192
	v_cmp_gt_u32_e32 vcc, 0x1000, v195
	v_mov_b32_e32 v0, s98
	v_mov_b32_e32 v1, s99
	v_mov_b32_e32 v3, s58
	v_cndmask_b32_e32 v0, v0, v3, vcc
	v_mov_b32_e32 v3, s59
	v_cndmask_b32_e32 v1, v1, v3, vcc
	v_add_co_u32_e32 v0, vcc, v0, v194
	s_nop 1
	v_addc_co_u32_e32 v1, vcc, 0, v1, vcc
	global_load_dwordx4 v[136:139], v[0:1], off
	v_add_u32_e32 v194, 0x4000, v194
	v_add_u32_e32 v195, 40, v192
	v_cmp_gt_u32_e32 vcc, 0x1000, v195
	v_mov_b32_e32 v0, s98
	v_mov_b32_e32 v1, s99
	v_mov_b32_e32 v3, s58
	v_cndmask_b32_e32 v0, v0, v3, vcc
	v_mov_b32_e32 v3, s59
	v_cndmask_b32_e32 v1, v1, v3, vcc
	v_add_co_u32_e32 v0, vcc, v0, v194
	s_nop 1
	v_addc_co_u32_e32 v1, vcc, 0, v1, vcc
	global_load_dwordx4 v[140:143], v[0:1], off
	v_add_u32_e32 v194, 0x4000, v194
	v_add_u32_e32 v195, 44, v192
	v_cmp_gt_u32_e32 vcc, 0x1000, v195
	v_mov_b32_e32 v0, s98
	v_mov_b32_e32 v1, s99
	v_mov_b32_e32 v3, s58
	v_cndmask_b32_e32 v0, v0, v3, vcc
	v_mov_b32_e32 v3, s59
	v_cndmask_b32_e32 v1, v1, v3, vcc
	v_add_co_u32_e32 v0, vcc, v0, v194
	s_nop 1
	v_addc_co_u32_e32 v1, vcc, 0, v1, vcc
	global_load_dwordx4 v[144:147], v[0:1], off
	v_add_u32_e32 v194, 0x4000, v194
	v_add_u32_e32 v195, s4, v193
	global_load_dwordx4 v[148:151], v195, s[100:101]
	v_add_u32_e32 v195, s5, v193
	global_load_dwordx4 v[152:155], v195, s[100:101]
	ds_write_b32 v203, v4 offset:0
	ds_write_b32 v203, v5 offset:272
	ds_write_b32 v203, v6 offset:544
	ds_write_b32 v203, v7 offset:816
	ds_write_b32 v203, v8 offset:64
	ds_write_b32 v203, v9 offset:336
	ds_write_b32 v203, v10 offset:608
	ds_write_b32 v203, v11 offset:880
	ds_write_b32 v203, v12 offset:128
	ds_write_b32 v203, v13 offset:400
	ds_write_b32 v203, v14 offset:672
	ds_write_b32 v203, v15 offset:944
	ds_write_b32 v203, v16 offset:192
	ds_write_b32 v203, v17 offset:464
	ds_write_b32 v203, v18 offset:736
	ds_write_b32 v203, v19 offset:1008
	s_waitcnt lgkmcnt(0)
	ds_read_b128 v[156:159], v204 offset:0
	ds_read_b128 v[160:163], v204 offset:1088
	ds_read_b128 v[164:167], v204 offset:2176
	ds_read_b128 v[168:171], v204 offset:3264
	v_add_u32_e32 v195, 0, v192
	v_cmp_le_u32_e32 vcc, s7, v195
	s_waitcnt vmcnt(0)
	s_waitcnt lgkmcnt(3)
	v_cndmask_b32_e32 v172, v148, v152, vcc
	v_cndmask_b32_e32 v173, v149, v153, vcc
	v_cndmask_b32_e32 v174, v150, v154, vcc
	v_cndmask_b32_e32 v175, v151, v155, vcc
	v_fmac_f32_e32 v100, v172, v156
	v_fmac_f32_e32 v101, v173, v157
	v_fmac_f32_e32 v102, v174, v158
	v_fmac_f32_e32 v103, v175, v159
	global_store_dwordx4 v197, v[100:103], s[56:57] sc0 sc1
	v_add_u32_e32 v197, 0x4000, v197
	v_add_u32_e32 v195, 4, v192
	v_cmp_le_u32_e32 vcc, s7, v195
	s_waitcnt vmcnt(1)
	s_waitcnt lgkmcnt(2)
	v_cndmask_b32_e32 v172, v148, v152, vcc
	v_cndmask_b32_e32 v173, v149, v153, vcc
	v_cndmask_b32_e32 v174, v150, v154, vcc
	v_cndmask_b32_e32 v175, v151, v155, vcc
	v_fmac_f32_e32 v104, v172, v160
	v_fmac_f32_e32 v105, v173, v161
	v_fmac_f32_e32 v106, v174, v162
	v_fmac_f32_e32 v107, v175, v163
	global_store_dwordx4 v197, v[104:107], s[56:57] sc0 sc1
	v_add_u32_e32 v197, 0x4000, v197
	v_add_u32_e32 v195, 8, v192
	v_cmp_le_u32_e32 vcc, s7, v195
	s_waitcnt vmcnt(2)
	s_waitcnt lgkmcnt(1)
	v_cndmask_b32_e32 v172, v148, v152, vcc
	v_cndmask_b32_e32 v173, v149, v153, vcc
	v_cndmask_b32_e32 v174, v150, v154, vcc
	v_cndmask_b32_e32 v175, v151, v155, vcc
	v_fmac_f32_e32 v108, v172, v164
	v_fmac_f32_e32 v109, v173, v165
	v_fmac_f32_e32 v110, v174, v166
	v_fmac_f32_e32 v111, v175, v167
	global_store_dwordx4 v197, v[108:111], s[56:57] sc0 sc1
	v_add_u32_e32 v197, 0x4000, v197
	v_add_u32_e32 v195, 12, v192
	v_cmp_le_u32_e32 vcc, s7, v195
	s_waitcnt vmcnt(3)
	s_waitcnt lgkmcnt(0)
	v_cndmask_b32_e32 v172, v148, v152, vcc
	v_cndmask_b32_e32 v173, v149, v153, vcc
	v_cndmask_b32_e32 v174, v150, v154, vcc
	v_cndmask_b32_e32 v175, v151, v155, vcc
	v_fmac_f32_e32 v112, v172, v168
	v_fmac_f32_e32 v113, v173, v169
	v_fmac_f32_e32 v114, v174, v170
	v_fmac_f32_e32 v115, v175, v171
	global_store_dwordx4 v197, v[112:115], s[56:57] sc0 sc1
	v_add_u32_e32 v197, 0x4000, v197
	ds_write_b32 v203, v20 offset:0
	ds_write_b32 v203, v21 offset:272
	ds_write_b32 v203, v22 offset:544
	ds_write_b32 v203, v23 offset:816
	ds_write_b32 v203, v24 offset:64
	ds_write_b32 v203, v25 offset:336
	ds_write_b32 v203, v26 offset:608
	ds_write_b32 v203, v27 offset:880
	ds_write_b32 v203, v28 offset:128
	ds_write_b32 v203, v29 offset:400
	ds_write_b32 v203, v30 offset:672
	ds_write_b32 v203, v31 offset:944
	ds_write_b32 v203, v32 offset:192
	ds_write_b32 v203, v33 offset:464
	ds_write_b32 v203, v34 offset:736
	ds_write_b32 v203, v35 offset:1008
	s_waitcnt lgkmcnt(0)
	ds_read_b128 v[156:159], v204 offset:0
	ds_read_b128 v[160:163], v204 offset:1088
	ds_read_b128 v[164:167], v204 offset:2176
	ds_read_b128 v[168:171], v204 offset:3264
	v_add_u32_e32 v195, 16, v192
	v_cmp_le_u32_e32 vcc, s7, v195
	s_waitcnt vmcnt(4)
	s_waitcnt lgkmcnt(3)
	v_cndmask_b32_e32 v172, v148, v152, vcc
	v_cndmask_b32_e32 v173, v149, v153, vcc
	v_cndmask_b32_e32 v174, v150, v154, vcc
	v_cndmask_b32_e32 v175, v151, v155, vcc
	v_fmac_f32_e32 v116, v172, v156
	v_fmac_f32_e32 v117, v173, v157
	v_fmac_f32_e32 v118, v174, v158
	v_fmac_f32_e32 v119, v175, v159
	global_store_dwordx4 v197, v[116:119], s[56:57] sc0 sc1
	v_add_u32_e32 v197, 0x4000, v197
	v_add_u32_e32 v195, 20, v192
	v_cmp_le_u32_e32 vcc, s7, v195
	s_waitcnt vmcnt(5)
	s_waitcnt lgkmcnt(2)
	v_cndmask_b32_e32 v172, v148, v152, vcc
	v_cndmask_b32_e32 v173, v149, v153, vcc
	v_cndmask_b32_e32 v174, v150, v154, vcc
	v_cndmask_b32_e32 v175, v151, v155, vcc
	v_fmac_f32_e32 v120, v172, v160
	v_fmac_f32_e32 v121, v173, v161
	v_fmac_f32_e32 v122, v174, v162
	v_fmac_f32_e32 v123, v175, v163
	global_store_dwordx4 v197, v[120:123], s[56:57] sc0 sc1
	v_add_u32_e32 v197, 0x4000, v197
	v_add_u32_e32 v195, 24, v192
	v_cmp_le_u32_e32 vcc, s7, v195
	s_waitcnt vmcnt(6)
	s_waitcnt lgkmcnt(1)
	v_cndmask_b32_e32 v172, v148, v152, vcc
	v_cndmask_b32_e32 v173, v149, v153, vcc
	v_cndmask_b32_e32 v174, v150, v154, vcc
	v_cndmask_b32_e32 v175, v151, v155, vcc
	v_fmac_f32_e32 v124, v172, v164
	v_fmac_f32_e32 v125, v173, v165
	v_fmac_f32_e32 v126, v174, v166
	v_fmac_f32_e32 v127, v175, v167
	global_store_dwordx4 v197, v[124:127], s[56:57] sc0 sc1
	v_add_u32_e32 v197, 0x4000, v197
	v_add_u32_e32 v195, 28, v192
	v_cmp_le_u32_e32 vcc, s7, v195
	s_waitcnt vmcnt(7)
	s_waitcnt lgkmcnt(0)
	v_cndmask_b32_e32 v172, v148, v152, vcc
	v_cndmask_b32_e32 v173, v149, v153, vcc
	v_cndmask_b32_e32 v174, v150, v154, vcc
	v_cndmask_b32_e32 v175, v151, v155, vcc
	v_fmac_f32_e32 v128, v172, v168
	v_fmac_f32_e32 v129, v173, v169
	v_fmac_f32_e32 v130, v174, v170
	v_fmac_f32_e32 v131, v175, v171
	global_store_dwordx4 v197, v[128:131], s[56:57] sc0 sc1
	v_add_u32_e32 v197, 0x4000, v197
	ds_write_b32 v203, v36 offset:0
	ds_write_b32 v203, v37 offset:272
	ds_write_b32 v203, v38 offset:544
	ds_write_b32 v203, v39 offset:816
	ds_write_b32 v203, v40 offset:64
	ds_write_b32 v203, v41 offset:336
	ds_write_b32 v203, v42 offset:608
	ds_write_b32 v203, v43 offset:880
	ds_write_b32 v203, v44 offset:128
	ds_write_b32 v203, v45 offset:400
	ds_write_b32 v203, v46 offset:672
	ds_write_b32 v203, v47 offset:944
	ds_write_b32 v203, v48 offset:192
	ds_write_b32 v203, v49 offset:464
	ds_write_b32 v203, v50 offset:736
	ds_write_b32 v203, v51 offset:1008
	s_waitcnt lgkmcnt(0)
	ds_read_b128 v[156:159], v204 offset:0
	ds_read_b128 v[160:163], v204 offset:1088
	ds_read_b128 v[164:167], v204 offset:2176
	ds_read_b128 v[168:171], v204 offset:3264
	v_add_u32_e32 v195, 32, v192
	v_cmp_le_u32_e32 vcc, s7, v195
	s_waitcnt vmcnt(8)
	s_waitcnt lgkmcnt(3)
	v_cndmask_b32_e32 v172, v148, v152, vcc
	v_cndmask_b32_e32 v173, v149, v153, vcc
	v_cndmask_b32_e32 v174, v150, v154, vcc
	v_cndmask_b32_e32 v175, v151, v155, vcc
	v_fmac_f32_e32 v132, v172, v156
	v_fmac_f32_e32 v133, v173, v157
	v_fmac_f32_e32 v134, v174, v158
	v_fmac_f32_e32 v135, v175, v159
	global_store_dwordx4 v197, v[132:135], s[56:57] sc0 sc1
	v_add_u32_e32 v197, 0x4000, v197
	v_add_u32_e32 v195, 36, v192
	v_cmp_le_u32_e32 vcc, s7, v195
	s_waitcnt vmcnt(9)
	s_waitcnt lgkmcnt(2)
	v_cndmask_b32_e32 v172, v148, v152, vcc
	v_cndmask_b32_e32 v173, v149, v153, vcc
	v_cndmask_b32_e32 v174, v150, v154, vcc
	v_cndmask_b32_e32 v175, v151, v155, vcc
	v_fmac_f32_e32 v136, v172, v160
	v_fmac_f32_e32 v137, v173, v161
	v_fmac_f32_e32 v138, v174, v162
	v_fmac_f32_e32 v139, v175, v163
	global_store_dwordx4 v197, v[136:139], s[56:57] sc0 sc1
	v_add_u32_e32 v197, 0x4000, v197
	v_add_u32_e32 v195, 40, v192
	v_cmp_le_u32_e32 vcc, s7, v195
	s_waitcnt vmcnt(10)
	s_waitcnt lgkmcnt(1)
	v_cndmask_b32_e32 v172, v148, v152, vcc
	v_cndmask_b32_e32 v173, v149, v153, vcc
	v_cndmask_b32_e32 v174, v150, v154, vcc
	v_cndmask_b32_e32 v175, v151, v155, vcc
	v_fmac_f32_e32 v140, v172, v164
	v_fmac_f32_e32 v141, v173, v165
	v_fmac_f32_e32 v142, v174, v166
	v_fmac_f32_e32 v143, v175, v167
	global_store_dwordx4 v197, v[140:143], s[56:57] sc0 sc1
	v_add_u32_e32 v197, 0x4000, v197
	v_add_u32_e32 v195, 44, v192
	v_cmp_le_u32_e32 vcc, s7, v195
	s_waitcnt vmcnt(11)
	s_waitcnt lgkmcnt(0)
	v_cndmask_b32_e32 v172, v148, v152, vcc
	v_cndmask_b32_e32 v173, v149, v153, vcc
	v_cndmask_b32_e32 v174, v150, v154, vcc
	v_cndmask_b32_e32 v175, v151, v155, vcc
	v_fmac_f32_e32 v144, v172, v168
	v_fmac_f32_e32 v145, v173, v169
	v_fmac_f32_e32 v146, v174, v170
	v_fmac_f32_e32 v147, v175, v171
	global_store_dwordx4 v197, v[144:147], s[56:57] sc0 sc1
	v_add_u32_e32 v197, 0x4000, v197
	v_add_u32_e32 v195, 48, v192
	v_cmp_gt_u32_e32 vcc, 0x1000, v195
	v_mov_b32_e32 v0, s98
	v_mov_b32_e32 v1, s99
	v_mov_b32_e32 v3, s58
	v_cndmask_b32_e32 v0, v0, v3, vcc
	v_mov_b32_e32 v3, s59
	v_cndmask_b32_e32 v1, v1, v3, vcc
	v_add_co_u32_e32 v0, vcc, v0, v194
	s_nop 1
	v_addc_co_u32_e32 v1, vcc, 0, v1, vcc
	global_load_dwordx4 v[100:103], v[0:1], off
	v_add_u32_e32 v194, 0x4000, v194
	v_add_u32_e32 v195, 52, v192
	v_cmp_gt_u32_e32 vcc, 0x1000, v195
	v_mov_b32_e32 v0, s98
	v_mov_b32_e32 v1, s99
	v_mov_b32_e32 v3, s58
	v_cndmask_b32_e32 v0, v0, v3, vcc
	v_mov_b32_e32 v3, s59
	v_cndmask_b32_e32 v1, v1, v3, vcc
	v_add_co_u32_e32 v0, vcc, v0, v194
	s_nop 1
	v_addc_co_u32_e32 v1, vcc, 0, v1, vcc
	global_load_dwordx4 v[104:107], v[0:1], off
	v_add_u32_e32 v194, 0x4000, v194
	v_add_u32_e32 v195, 56, v192
	v_cmp_gt_u32_e32 vcc, 0x1000, v195
	v_mov_b32_e32 v0, s98
	v_mov_b32_e32 v1, s99
	v_mov_b32_e32 v3, s58
	v_cndmask_b32_e32 v0, v0, v3, vcc
	v_mov_b32_e32 v3, s59
	v_cndmask_b32_e32 v1, v1, v3, vcc
	v_add_co_u32_e32 v0, vcc, v0, v194
	s_nop 1
	v_addc_co_u32_e32 v1, vcc, 0, v1, vcc
	global_load_dwordx4 v[108:111], v[0:1], off
	v_add_u32_e32 v194, 0x4000, v194
	v_add_u32_e32 v195, 60, v192
	v_cmp_gt_u32_e32 vcc, 0x1000, v195
	v_mov_b32_e32 v0, s98
	v_mov_b32_e32 v1, s99
	v_mov_b32_e32 v3, s58
	v_cndmask_b32_e32 v0, v0, v3, vcc
	v_mov_b32_e32 v3, s59
	v_cndmask_b32_e32 v1, v1, v3, vcc
	v_add_co_u32_e32 v0, vcc, v0, v194
	s_nop 1
	v_addc_co_u32_e32 v1, vcc, 0, v1, vcc
	global_load_dwordx4 v[112:115], v[0:1], off
	v_add_u32_e32 v194, 0x4000, v194
	v_add_u32_e32 v195, 64, v192
	v_cmp_gt_u32_e32 vcc, 0x1000, v195
	v_mov_b32_e32 v0, s98
	v_mov_b32_e32 v1, s99
	v_mov_b32_e32 v3, s58
	v_cndmask_b32_e32 v0, v0, v3, vcc
	v_mov_b32_e32 v3, s59
	v_cndmask_b32_e32 v1, v1, v3, vcc
	v_add_co_u32_e32 v0, vcc, v0, v194
	s_nop 1
	v_addc_co_u32_e32 v1, vcc, 0, v1, vcc
	global_load_dwordx4 v[116:119], v[0:1], off
	v_add_u32_e32 v194, 0x4000, v194
	v_add_u32_e32 v195, 68, v192
	v_cmp_gt_u32_e32 vcc, 0x1000, v195
	v_mov_b32_e32 v0, s98
	v_mov_b32_e32 v1, s99
	v_mov_b32_e32 v3, s58
	v_cndmask_b32_e32 v0, v0, v3, vcc
	v_mov_b32_e32 v3, s59
	v_cndmask_b32_e32 v1, v1, v3, vcc
	v_add_co_u32_e32 v0, vcc, v0, v194
	s_nop 1
	v_addc_co_u32_e32 v1, vcc, 0, v1, vcc
	global_load_dwordx4 v[120:123], v[0:1], off
	v_add_u32_e32 v194, 0x4000, v194
	v_add_u32_e32 v195, 72, v192
	v_cmp_gt_u32_e32 vcc, 0x1000, v195
	v_mov_b32_e32 v0, s98
	v_mov_b32_e32 v1, s99
	v_mov_b32_e32 v3, s58
	v_cndmask_b32_e32 v0, v0, v3, vcc
	v_mov_b32_e32 v3, s59
	v_cndmask_b32_e32 v1, v1, v3, vcc
	v_add_co_u32_e32 v0, vcc, v0, v194
	s_nop 1
	v_addc_co_u32_e32 v1, vcc, 0, v1, vcc
	global_load_dwordx4 v[124:127], v[0:1], off
	v_add_u32_e32 v194, 0x4000, v194
	v_add_u32_e32 v195, 76, v192
	v_cmp_gt_u32_e32 vcc, 0x1000, v195
	v_mov_b32_e32 v0, s98
	v_mov_b32_e32 v1, s99
	v_mov_b32_e32 v3, s58
	v_cndmask_b32_e32 v0, v0, v3, vcc
	v_mov_b32_e32 v3, s59
	v_cndmask_b32_e32 v1, v1, v3, vcc
	v_add_co_u32_e32 v0, vcc, v0, v194
	s_nop 1
	v_addc_co_u32_e32 v1, vcc, 0, v1, vcc
	global_load_dwordx4 v[128:131], v[0:1], off
	v_add_u32_e32 v194, 0x4000, v194
	v_add_u32_e32 v195, 80, v192
	v_cmp_gt_u32_e32 vcc, 0x1000, v195
	v_mov_b32_e32 v0, s98
	v_mov_b32_e32 v1, s99
	v_mov_b32_e32 v3, s58
	v_cndmask_b32_e32 v0, v0, v3, vcc
	v_mov_b32_e32 v3, s59
	v_cndmask_b32_e32 v1, v1, v3, vcc
	v_add_co_u32_e32 v0, vcc, v0, v194
	s_nop 1
	v_addc_co_u32_e32 v1, vcc, 0, v1, vcc
	global_load_dwordx4 v[132:135], v[0:1], off
	v_add_u32_e32 v194, 0x4000, v194
	v_add_u32_e32 v195, 84, v192
	v_cmp_gt_u32_e32 vcc, 0x1000, v195
	v_mov_b32_e32 v0, s98
	v_mov_b32_e32 v1, s99
	v_mov_b32_e32 v3, s58
	v_cndmask_b32_e32 v0, v0, v3, vcc
	v_mov_b32_e32 v3, s59
	v_cndmask_b32_e32 v1, v1, v3, vcc
	v_add_co_u32_e32 v0, vcc, v0, v194
	s_nop 1
	v_addc_co_u32_e32 v1, vcc, 0, v1, vcc
	global_load_dwordx4 v[136:139], v[0:1], off
	v_add_u32_e32 v194, 0x4000, v194
	v_add_u32_e32 v195, 88, v192
	v_cmp_gt_u32_e32 vcc, 0x1000, v195
	v_mov_b32_e32 v0, s98
	v_mov_b32_e32 v1, s99
	v_mov_b32_e32 v3, s58
	v_cndmask_b32_e32 v0, v0, v3, vcc
	v_mov_b32_e32 v3, s59
	v_cndmask_b32_e32 v1, v1, v3, vcc
	v_add_co_u32_e32 v0, vcc, v0, v194
	s_nop 1
	v_addc_co_u32_e32 v1, vcc, 0, v1, vcc
	global_load_dwordx4 v[140:143], v[0:1], off
	v_add_u32_e32 v194, 0x4000, v194
	v_add_u32_e32 v195, 92, v192
	v_cmp_gt_u32_e32 vcc, 0x1000, v195
	v_mov_b32_e32 v0, s98
	v_mov_b32_e32 v1, s99
	v_mov_b32_e32 v3, s58
	v_cndmask_b32_e32 v0, v0, v3, vcc
	v_mov_b32_e32 v3, s59
	v_cndmask_b32_e32 v1, v1, v3, vcc
	v_add_co_u32_e32 v0, vcc, v0, v194
	s_nop 1
	v_addc_co_u32_e32 v1, vcc, 0, v1, vcc
	global_load_dwordx4 v[144:147], v[0:1], off
	v_add_u32_e32 v194, 0x4000, v194
	ds_write_b32 v203, v52 offset:0
	ds_write_b32 v203, v53 offset:272
	ds_write_b32 v203, v54 offset:544
	ds_write_b32 v203, v55 offset:816
	ds_write_b32 v203, v56 offset:64
	ds_write_b32 v203, v57 offset:336
	ds_write_b32 v203, v58 offset:608
	ds_write_b32 v203, v59 offset:880
	ds_write_b32 v203, v60 offset:128
	ds_write_b32 v203, v61 offset:400
	ds_write_b32 v203, v62 offset:672
	ds_write_b32 v203, v63 offset:944
	ds_write_b32 v203, v64 offset:192
	ds_write_b32 v203, v65 offset:464
	ds_write_b32 v203, v66 offset:736
	ds_write_b32 v203, v67 offset:1008
	s_waitcnt lgkmcnt(0)
	ds_read_b128 v[156:159], v204 offset:0
	ds_read_b128 v[160:163], v204 offset:1088
	ds_read_b128 v[164:167], v204 offset:2176
	ds_read_b128 v[168:171], v204 offset:3264
	v_add_u32_e32 v195, 48, v192
	v_cmp_le_u32_e32 vcc, s7, v195
	s_waitcnt vmcnt(11)
	s_waitcnt lgkmcnt(3)
	v_cndmask_b32_e32 v172, v148, v152, vcc
	v_cndmask_b32_e32 v173, v149, v153, vcc
	v_cndmask_b32_e32 v174, v150, v154, vcc
	v_cndmask_b32_e32 v175, v151, v155, vcc
	v_fmac_f32_e32 v100, v172, v156
	v_fmac_f32_e32 v101, v173, v157
	v_fmac_f32_e32 v102, v174, v158
	v_fmac_f32_e32 v103, v175, v159
	global_store_dwordx4 v197, v[100:103], s[56:57] sc0 sc1
	v_add_u32_e32 v197, 0x4000, v197
	v_add_u32_e32 v195, 52, v192
	v_cmp_le_u32_e32 vcc, s7, v195
	s_waitcnt vmcnt(11)
	s_waitcnt lgkmcnt(2)
	v_cndmask_b32_e32 v172, v148, v152, vcc
	v_cndmask_b32_e32 v173, v149, v153, vcc
	v_cndmask_b32_e32 v174, v150, v154, vcc
	v_cndmask_b32_e32 v175, v151, v155, vcc
	v_fmac_f32_e32 v104, v172, v160
	v_fmac_f32_e32 v105, v173, v161
	v_fmac_f32_e32 v106, v174, v162
	v_fmac_f32_e32 v107, v175, v163
	global_store_dwordx4 v197, v[104:107], s[56:57] sc0 sc1
	v_add_u32_e32 v197, 0x4000, v197
	v_add_u32_e32 v195, 56, v192
	v_cmp_le_u32_e32 vcc, s7, v195
	s_waitcnt vmcnt(11)
	s_waitcnt lgkmcnt(1)
	v_cndmask_b32_e32 v172, v148, v152, vcc
	v_cndmask_b32_e32 v173, v149, v153, vcc
	v_cndmask_b32_e32 v174, v150, v154, vcc
	v_cndmask_b32_e32 v175, v151, v155, vcc
	v_fmac_f32_e32 v108, v172, v164
	v_fmac_f32_e32 v109, v173, v165
	v_fmac_f32_e32 v110, v174, v166
	v_fmac_f32_e32 v111, v175, v167
	global_store_dwordx4 v197, v[108:111], s[56:57] sc0 sc1
	v_add_u32_e32 v197, 0x4000, v197
	v_add_u32_e32 v195, 60, v192
	v_cmp_le_u32_e32 vcc, s7, v195
	s_waitcnt vmcnt(11)
	s_waitcnt lgkmcnt(0)
	v_cndmask_b32_e32 v172, v148, v152, vcc
	v_cndmask_b32_e32 v173, v149, v153, vcc
	v_cndmask_b32_e32 v174, v150, v154, vcc
	v_cndmask_b32_e32 v175, v151, v155, vcc
	v_fmac_f32_e32 v112, v172, v168
	v_fmac_f32_e32 v113, v173, v169
	v_fmac_f32_e32 v114, v174, v170
	v_fmac_f32_e32 v115, v175, v171
	global_store_dwordx4 v197, v[112:115], s[56:57] sc0 sc1
	v_add_u32_e32 v197, 0x4000, v197
	ds_write_b32 v203, v68 offset:0
	ds_write_b32 v203, v69 offset:272
	ds_write_b32 v203, v70 offset:544
	ds_write_b32 v203, v71 offset:816
	ds_write_b32 v203, v72 offset:64
	ds_write_b32 v203, v73 offset:336
	ds_write_b32 v203, v74 offset:608
	ds_write_b32 v203, v75 offset:880
	ds_write_b32 v203, v76 offset:128
	ds_write_b32 v203, v77 offset:400
	ds_write_b32 v203, v78 offset:672
	ds_write_b32 v203, v79 offset:944
	ds_write_b32 v203, v80 offset:192
	ds_write_b32 v203, v81 offset:464
	ds_write_b32 v203, v82 offset:736
	ds_write_b32 v203, v83 offset:1008
	s_waitcnt lgkmcnt(0)
	ds_read_b128 v[156:159], v204 offset:0
	ds_read_b128 v[160:163], v204 offset:1088
	ds_read_b128 v[164:167], v204 offset:2176
	ds_read_b128 v[168:171], v204 offset:3264
	v_add_u32_e32 v195, 64, v192
	v_cmp_le_u32_e32 vcc, s7, v195
	s_waitcnt vmcnt(11)
	s_waitcnt lgkmcnt(3)
	v_cndmask_b32_e32 v172, v148, v152, vcc
	v_cndmask_b32_e32 v173, v149, v153, vcc
	v_cndmask_b32_e32 v174, v150, v154, vcc
	v_cndmask_b32_e32 v175, v151, v155, vcc
	v_fmac_f32_e32 v116, v172, v156
	v_fmac_f32_e32 v117, v173, v157
	v_fmac_f32_e32 v118, v174, v158
	v_fmac_f32_e32 v119, v175, v159
	global_store_dwordx4 v197, v[116:119], s[56:57] sc0 sc1
	v_add_u32_e32 v197, 0x4000, v197
	v_add_u32_e32 v195, 68, v192
	v_cmp_le_u32_e32 vcc, s7, v195
	s_waitcnt vmcnt(11)
	s_waitcnt lgkmcnt(2)
	v_cndmask_b32_e32 v172, v148, v152, vcc
	v_cndmask_b32_e32 v173, v149, v153, vcc
	v_cndmask_b32_e32 v174, v150, v154, vcc
	v_cndmask_b32_e32 v175, v151, v155, vcc
	v_fmac_f32_e32 v120, v172, v160
	v_fmac_f32_e32 v121, v173, v161
	v_fmac_f32_e32 v122, v174, v162
	v_fmac_f32_e32 v123, v175, v163
	global_store_dwordx4 v197, v[120:123], s[56:57] sc0 sc1
	v_add_u32_e32 v197, 0x4000, v197
	v_add_u32_e32 v195, 72, v192
	v_cmp_le_u32_e32 vcc, s7, v195
	s_waitcnt vmcnt(11)
	s_waitcnt lgkmcnt(1)
	v_cndmask_b32_e32 v172, v148, v152, vcc
	v_cndmask_b32_e32 v173, v149, v153, vcc
	v_cndmask_b32_e32 v174, v150, v154, vcc
	v_cndmask_b32_e32 v175, v151, v155, vcc
	v_fmac_f32_e32 v124, v172, v164
	v_fmac_f32_e32 v125, v173, v165
	v_fmac_f32_e32 v126, v174, v166
	v_fmac_f32_e32 v127, v175, v167
	global_store_dwordx4 v197, v[124:127], s[56:57] sc0 sc1
	v_add_u32_e32 v197, 0x4000, v197
	v_add_u32_e32 v195, 76, v192
	v_cmp_le_u32_e32 vcc, s7, v195
	s_waitcnt vmcnt(11)
	s_waitcnt lgkmcnt(0)
	v_cndmask_b32_e32 v172, v148, v152, vcc
	v_cndmask_b32_e32 v173, v149, v153, vcc
	v_cndmask_b32_e32 v174, v150, v154, vcc
	v_cndmask_b32_e32 v175, v151, v155, vcc
	v_fmac_f32_e32 v128, v172, v168
	v_fmac_f32_e32 v129, v173, v169
	v_fmac_f32_e32 v130, v174, v170
	v_fmac_f32_e32 v131, v175, v171
	global_store_dwordx4 v197, v[128:131], s[56:57] sc0 sc1
	v_add_u32_e32 v197, 0x4000, v197
	ds_write_b32 v203, v84 offset:0
	ds_write_b32 v203, v85 offset:272
	ds_write_b32 v203, v86 offset:544
	ds_write_b32 v203, v87 offset:816
	ds_write_b32 v203, v88 offset:64
	ds_write_b32 v203, v89 offset:336
	ds_write_b32 v203, v90 offset:608
	ds_write_b32 v203, v91 offset:880
	ds_write_b32 v203, v92 offset:128
	ds_write_b32 v203, v93 offset:400
	ds_write_b32 v203, v94 offset:672
	ds_write_b32 v203, v95 offset:944
	ds_write_b32 v203, v96 offset:192
	ds_write_b32 v203, v97 offset:464
	ds_write_b32 v203, v98 offset:736
	ds_write_b32 v203, v99 offset:1008
	s_waitcnt lgkmcnt(0)
	ds_read_b128 v[156:159], v204 offset:0
	ds_read_b128 v[160:163], v204 offset:1088
	ds_read_b128 v[164:167], v204 offset:2176
	ds_read_b128 v[168:171], v204 offset:3264
	v_add_u32_e32 v195, 80, v192
	v_cmp_le_u32_e32 vcc, s7, v195
	s_waitcnt vmcnt(11)
	s_waitcnt lgkmcnt(3)
	v_cndmask_b32_e32 v172, v148, v152, vcc
	v_cndmask_b32_e32 v173, v149, v153, vcc
	v_cndmask_b32_e32 v174, v150, v154, vcc
	v_cndmask_b32_e32 v175, v151, v155, vcc
	v_fmac_f32_e32 v132, v172, v156
	v_fmac_f32_e32 v133, v173, v157
	v_fmac_f32_e32 v134, v174, v158
	v_fmac_f32_e32 v135, v175, v159
	global_store_dwordx4 v197, v[132:135], s[56:57] sc0 sc1
	v_add_u32_e32 v197, 0x4000, v197
	v_add_u32_e32 v195, 84, v192
	v_cmp_le_u32_e32 vcc, s7, v195
	s_waitcnt vmcnt(11)
	s_waitcnt lgkmcnt(2)
	v_cndmask_b32_e32 v172, v148, v152, vcc
	v_cndmask_b32_e32 v173, v149, v153, vcc
	v_cndmask_b32_e32 v174, v150, v154, vcc
	v_cndmask_b32_e32 v175, v151, v155, vcc
	v_fmac_f32_e32 v136, v172, v160
	v_fmac_f32_e32 v137, v173, v161
	v_fmac_f32_e32 v138, v174, v162
	v_fmac_f32_e32 v139, v175, v163
	global_store_dwordx4 v197, v[136:139], s[56:57] sc0 sc1
	v_add_u32_e32 v197, 0x4000, v197
	v_add_u32_e32 v195, 88, v192
	v_cmp_le_u32_e32 vcc, s7, v195
	s_waitcnt vmcnt(11)
	s_waitcnt lgkmcnt(1)
	v_cndmask_b32_e32 v172, v148, v152, vcc
	v_cndmask_b32_e32 v173, v149, v153, vcc
	v_cndmask_b32_e32 v174, v150, v154, vcc
	v_cndmask_b32_e32 v175, v151, v155, vcc
	v_fmac_f32_e32 v140, v172, v164
	v_fmac_f32_e32 v141, v173, v165
	v_fmac_f32_e32 v142, v174, v166
	v_fmac_f32_e32 v143, v175, v167
	global_store_dwordx4 v197, v[140:143], s[56:57] sc0 sc1
	v_add_u32_e32 v197, 0x4000, v197
	v_add_u32_e32 v195, 92, v192
	v_cmp_le_u32_e32 vcc, s7, v195
	s_waitcnt vmcnt(11)
	s_waitcnt lgkmcnt(0)
	v_cndmask_b32_e32 v172, v148, v152, vcc
	v_cndmask_b32_e32 v173, v149, v153, vcc
	v_cndmask_b32_e32 v174, v150, v154, vcc
	v_cndmask_b32_e32 v175, v151, v155, vcc
	v_fmac_f32_e32 v144, v172, v168
	v_fmac_f32_e32 v145, v173, v169
	v_fmac_f32_e32 v146, v174, v170
	v_fmac_f32_e32 v147, v175, v171
	global_store_dwordx4 v197, v[144:147], s[56:57] sc0 sc1
	v_add_u32_e32 v197, 0x4000, v197
	v_mov_b32_e32 v4, 0
	v_mov_b32_e32 v5, 0
	v_mov_b32_e32 v6, 0
	v_mov_b32_e32 v7, 0
	v_mov_b32_e32 v8, 0
	v_mov_b32_e32 v9, 0
	v_mov_b32_e32 v10, 0
	v_mov_b32_e32 v11, 0
	v_mov_b32_e32 v12, 0
	v_mov_b32_e32 v13, 0
	v_mov_b32_e32 v14, 0
	v_mov_b32_e32 v15, 0
	v_mov_b32_e32 v16, 0
	v_mov_b32_e32 v17, 0
	v_mov_b32_e32 v18, 0
	v_mov_b32_e32 v19, 0
	v_mov_b32_e32 v20, 0
	v_mov_b32_e32 v21, 0
	v_mov_b32_e32 v22, 0
	v_mov_b32_e32 v23, 0
	v_mov_b32_e32 v24, 0
	v_mov_b32_e32 v25, 0
	v_mov_b32_e32 v26, 0
	v_mov_b32_e32 v27, 0
	v_mov_b32_e32 v28, 0
	v_mov_b32_e32 v29, 0
	v_mov_b32_e32 v30, 0
	v_mov_b32_e32 v31, 0
	v_mov_b32_e32 v32, 0
	v_mov_b32_e32 v33, 0
	v_mov_b32_e32 v34, 0
	v_mov_b32_e32 v35, 0
	v_mov_b32_e32 v36, 0
	v_mov_b32_e32 v37, 0
	v_mov_b32_e32 v38, 0
	v_mov_b32_e32 v39, 0
	v_mov_b32_e32 v40, 0
	v_mov_b32_e32 v41, 0
	v_mov_b32_e32 v42, 0
	v_mov_b32_e32 v43, 0
	v_mov_b32_e32 v44, 0
	v_mov_b32_e32 v45, 0
	v_mov_b32_e32 v46, 0
	v_mov_b32_e32 v47, 0
	v_mov_b32_e32 v48, 0
	v_mov_b32_e32 v49, 0
	v_mov_b32_e32 v50, 0
	v_mov_b32_e32 v51, 0
	v_mov_b32_e32 v52, 0
	v_mov_b32_e32 v53, 0
	v_mov_b32_e32 v54, 0
	v_mov_b32_e32 v55, 0
	v_mov_b32_e32 v56, 0
	v_mov_b32_e32 v57, 0
	v_mov_b32_e32 v58, 0
	v_mov_b32_e32 v59, 0
	v_mov_b32_e32 v60, 0
	v_mov_b32_e32 v61, 0
	v_mov_b32_e32 v62, 0
	v_mov_b32_e32 v63, 0
	v_mov_b32_e32 v64, 0
	v_mov_b32_e32 v65, 0
	v_mov_b32_e32 v66, 0
	v_mov_b32_e32 v67, 0
	v_mov_b32_e32 v68, 0
	v_mov_b32_e32 v69, 0
	v_mov_b32_e32 v70, 0
	v_mov_b32_e32 v71, 0
	v_mov_b32_e32 v72, 0
	v_mov_b32_e32 v73, 0
	v_mov_b32_e32 v74, 0
	v_mov_b32_e32 v75, 0
	v_mov_b32_e32 v76, 0
	v_mov_b32_e32 v77, 0
	v_mov_b32_e32 v78, 0
	v_mov_b32_e32 v79, 0
	v_mov_b32_e32 v80, 0
	v_mov_b32_e32 v81, 0
	v_mov_b32_e32 v82, 0
	v_mov_b32_e32 v83, 0
	v_mov_b32_e32 v84, 0
	v_mov_b32_e32 v85, 0
	v_mov_b32_e32 v86, 0
	v_mov_b32_e32 v87, 0
	v_mov_b32_e32 v88, 0
	v_mov_b32_e32 v89, 0
	v_mov_b32_e32 v90, 0
	v_mov_b32_e32 v91, 0
	v_mov_b32_e32 v92, 0
	v_mov_b32_e32 v93, 0
	v_mov_b32_e32 v94, 0
	v_mov_b32_e32 v95, 0
	v_mov_b32_e32 v96, 0
	v_mov_b32_e32 v97, 0
	v_mov_b32_e32 v98, 0
	v_mov_b32_e32 v99, 0
	s_mov_b32 s34, 0
	s_add_u32 s35, s35, s52
	s_cmp_ge_u32 s31, s30
	s_cbranch_scc1 .Lgm_f2_exit

.Lgm_wo_cnt:
	s_add_u32 s30, s30, 16
	s_add_u32 s4, s4, s52
	s_cmp_lt_u32 s4, s54
	s_cbranch_scc1 .Lgm_wo_cnt
	s_add_u32 s48, s96, 0x7084000
	s_addc_u32 s49, s97, 0
	s_mul_i32 s4, s36, 0x200000
	s_add_u32 s50, s96, 0x980000
	s_addc_u32 s51, s97, 0
	s_add_u32 s50, s50, s4
	s_addc_u32 s51, s51, 0
	v_and_b32_e32 v0, 63, v206
	v_lshrrev_b32_e32 v1, 6, v206
	s_mov_b32 s31, 0
	v_readfirstlane_b32 s42, v1
	s_nop 0
	s_cmp_ge_u32 s42, 4
	s_cbranch_scc1 .Lgm_wo_compute
	v_lshrrev_b32_e32 v3, 3, v0
	v_and_b32_e32 v4, 7, v0
	v_xor_b32_e32 v4, v4, v3
	v_lshl_add_u32 v3, v1, 3, v3
	v_lshlrev_b32_e32 v3, 11, v3
	v_lshl_add_u32 v180, v4, 4, v3
	v_add_u32_e32 v181, 0x10000, v180
	v_add_u32_e32 v182, 0x20000, v180
	v_add_u32_e32 v183, 0x30000, v180
	v_add_u32_e32 v184, 0x40000, v180
	v_add_u32_e32 v185, 0x50000, v180
	s_lshl_b32 s42, s42, 10
	s_mov_b32 s38, s53
	s_mov_b32 s39, 0
	s_mov_b32 s41, s42
	s_and_b32 s4, s38, 31
	s_mul_i32 s4, s4, 0x60000
	s_add_u32 s44, s48, s4
	s_addc_u32 s45, s49, 0
	s_lshr_b32 s4, s38, 5
	s_mul_i32 s4, s4, 0x40000
	s_add_u32 s46, s50, s4
	s_addc_u32 s47, s51, 0
	s_add_u32 m0, s41, 0x0
	s_nop 0
	global_load_lds_dwordx4 v180, s[44:45]
	s_add_u32 m0, s41, 0x1000
	s_nop 0
	global_load_lds_dwordx4 v181, s[44:45]
	s_add_u32 m0, s41, 0x2000
	s_nop 0
	global_load_lds_dwordx4 v182, s[44:45]
	s_add_u32 m0, s41, 0x3000
	s_nop 0
	global_load_lds_dwordx4 v183, s[44:45]
	s_add_u32 m0, s41, 0x4000
	s_nop 0
	global_load_lds_dwordx4 v184, s[44:45]
	s_add_u32 m0, s41, 0x5000
	s_nop 0
	global_load_lds_dwordx4 v185, s[44:45]
	s_add_u32 m0, s41, 0x6000
	s_nop 0
	global_load_lds_dwordx4 v180, s[46:47]
	s_add_u32 m0, s41, 0x7000
	s_nop 0
	global_load_lds_dwordx4 v181, s[46:47]
	s_add_u32 m0, s41, 0x8000
	s_nop 0
	global_load_lds_dwordx4 v182, s[46:47]
	s_add_u32 m0, s41, 0x9000
	s_nop 0
	global_load_lds_dwordx4 v183, s[46:47]
	s_add_u32 s39, s39, 1
	s_add_u32 s44, s44, 0x80
	s_addc_u32 s45, s45, 0
	s_add_u32 s46, s46, 0x80
	s_addc_u32 s47, s47, 0
	s_cmp_lt_u32 s39, 16
	s_cbranch_scc1 .Lgm_wo_dadv1
	s_mov_b32 s39, 0
	s_add_u32 s4, s38, s52
	s_cmp_lt_u32 s4, s54
	s_cselect_b32 s38, s4, s38
	s_and_b32 s4, s38, 31
	s_mul_i32 s4, s4, 0x60000
	s_add_u32 s44, s48, s4
	s_addc_u32 s45, s49, 0
	s_lshr_b32 s4, s38, 5
	s_mul_i32 s4, s4, 0x40000
	s_add_u32 s46, s50, s4
	s_addc_u32 s47, s51, 0

.Lgm_wo_join:
	s_waitcnt lgkmcnt(13)
	v_mfma_f32_16x16x32_bf16 v[4:7], v[100:103], v[124:127], v[4:7]
	v_mfma_f32_16x16x32_bf16 v[20:23], v[104:107], v[124:127], v[20:23]
	v_mfma_f32_16x16x32_bf16 v[36:39], v[108:111], v[124:127], v[36:39]
	v_mfma_f32_16x16x32_bf16 v[52:55], v[112:115], v[124:127], v[52:55]
	v_mfma_f32_16x16x32_bf16 v[68:71], v[116:119], v[124:127], v[68:71]
	v_mfma_f32_16x16x32_bf16 v[84:87], v[120:123], v[124:127], v[84:87]
	s_waitcnt lgkmcnt(12)
	v_mfma_f32_16x16x32_bf16 v[8:11], v[100:103], v[128:131], v[8:11]
	v_mfma_f32_16x16x32_bf16 v[24:27], v[104:107], v[128:131], v[24:27]
	v_mfma_f32_16x16x32_bf16 v[40:43], v[108:111], v[128:131], v[40:43]
	v_mfma_f32_16x16x32_bf16 v[56:59], v[112:115], v[128:131], v[56:59]
	v_mfma_f32_16x16x32_bf16 v[72:75], v[116:119], v[128:131], v[72:75]
	v_mfma_f32_16x16x32_bf16 v[88:91], v[120:123], v[128:131], v[88:91]
	s_waitcnt lgkmcnt(11)
	v_mfma_f32_16x16x32_bf16 v[12:15], v[100:103], v[132:135], v[12:15]
	v_mfma_f32_16x16x32_bf16 v[28:31], v[104:107], v[132:135], v[28:31]
	v_mfma_f32_16x16x32_bf16 v[44:47], v[108:111], v[132:135], v[44:47]
	v_mfma_f32_16x16x32_bf16 v[60:63], v[112:115], v[132:135], v[60:63]
	v_mfma_f32_16x16x32_bf16 v[76:79], v[116:119], v[132:135], v[76:79]
	v_mfma_f32_16x16x32_bf16 v[92:95], v[120:123], v[132:135], v[92:95]
	s_waitcnt lgkmcnt(10)
	v_mfma_f32_16x16x32_bf16 v[16:19], v[100:103], v[136:139], v[16:19]
	v_mfma_f32_16x16x32_bf16 v[32:35], v[104:107], v[136:139], v[32:35]
	v_mfma_f32_16x16x32_bf16 v[48:51], v[108:111], v[136:139], v[48:51]
	v_mfma_f32_16x16x32_bf16 v[64:67], v[112:115], v[136:139], v[64:67]
	v_mfma_f32_16x16x32_bf16 v[80:83], v[116:119], v[136:139], v[80:83]
	v_mfma_f32_16x16x32_bf16 v[96:99], v[120:123], v[136:139], v[96:99]
	s_waitcnt lgkmcnt(0)
	s_add_u32 s34, s34, 1
	s_add_u32 s31, s31, 1
	s_cmp_lt_u32 s34, 16
	s_cbranch_scc1 .Lgm_wo_rot
	v_mfma_f32_16x16x32_bf16 v[4:7], v[140:143], v[164:167], v[4:7]
	v_mfma_f32_16x16x32_bf16 v[20:23], v[144:147], v[164:167], v[20:23]
	v_mfma_f32_16x16x32_bf16 v[36:39], v[148:151], v[164:167], v[36:39]
	v_mfma_f32_16x16x32_bf16 v[52:55], v[152:155], v[164:167], v[52:55]
	v_mfma_f32_16x16x32_bf16 v[68:71], v[156:159], v[164:167], v[68:71]
	v_mfma_f32_16x16x32_bf16 v[84:87], v[160:163], v[164:167], v[84:87]
	v_mfma_f32_16x16x32_bf16 v[8:11], v[140:143], v[168:171], v[8:11]
	v_mfma_f32_16x16x32_bf16 v[24:27], v[144:147], v[168:171], v[24:27]
	v_mfma_f32_16x16x32_bf16 v[40:43], v[148:151], v[168:171], v[40:43]
	v_mfma_f32_16x16x32_bf16 v[56:59], v[152:155], v[168:171], v[56:59]
	v_mfma_f32_16x16x32_bf16 v[72:75], v[156:159], v[168:171], v[72:75]
	v_mfma_f32_16x16x32_bf16 v[88:91], v[160:163], v[168:171], v[88:91]
	v_mfma_f32_16x16x32_bf16 v[12:15], v[140:143], v[172:175], v[12:15]
	v_mfma_f32_16x16x32_bf16 v[28:31], v[144:147], v[172:175], v[28:31]
	v_mfma_f32_16x16x32_bf16 v[44:47], v[148:151], v[172:175], v[44:47]
	v_mfma_f32_16x16x32_bf16 v[60:63], v[152:155], v[172:175], v[60:63]
	v_mfma_f32_16x16x32_bf16 v[76:79], v[156:159], v[172:175], v[76:79]
	v_mfma_f32_16x16x32_bf16 v[92:95], v[160:163], v[172:175], v[92:95]
	v_mfma_f32_16x16x32_bf16 v[16:19], v[140:143], v[176:179], v[16:19]
	v_mfma_f32_16x16x32_bf16 v[32:35], v[144:147], v[176:179], v[32:35]
	v_mfma_f32_16x16x32_bf16 v[48:51], v[148:151], v[176:179], v[48:51]
	v_mfma_f32_16x16x32_bf16 v[64:67], v[152:155], v[176:179], v[64:67]
	v_mfma_f32_16x16x32_bf16 v[80:83], v[156:159], v[176:179], v[80:83]
	v_mfma_f32_16x16x32_bf16 v[96:99], v[160:163], v[176:179], v[96:99]
	s_and_b32 s6, s35, 31
	s_mul_i32 s6, s6, 192
	s_lshr_b32 s7, s35, 5
	s_lshl_b32 s7, s7, 7
	s_nop 7
	s_mul_i32 s4, s6, 0x1000
	s_lshl_b32 s5, s7, 2
	s_add_u32 s4, s4, s5
	v_add_u32_e32 v197, s4, v205
	v_add_u32_e32 v192, s6, v190
	v_lshl_add_u32 v193, s7, 2, v191
	s_sub_i32 s4, s6, 0xc00
	s_max_i32 s4, s4, 0
	s_lshr_b32 s4, s4, 10
	s_add_i32 s5, s6, -2881
	s_max_i32 s5, s5, 0
	s_lshr_b32 s5, s5, 10
	s_movk_i32 s7, 0x1400
	s_cmp_eq_u32 s4, 0
	s_cselect_b32 s7, 0x1000, s7
	s_mul_i32 s4, s4, 0x6000
	s_mul_i32 s5, s5, 0x6000
	v_mov_b32_e32 v194, v197
	v_add_u32_e32 v195, 0, v192
	v_cmp_gt_u32_e32 vcc, 0x1000, v195
	v_mov_b32_e32 v0, s98
	v_mov_b32_e32 v1, s99
	v_mov_b32_e32 v3, s58
	v_cndmask_b32_e32 v0, v0, v3, vcc
	v_mov_b32_e32 v3, s59
	v_cndmask_b32_e32 v1, v1, v3, vcc
	v_add_co_u32_e32 v0, vcc, v0, v194
	s_nop 1
	v_addc_co_u32_e32 v1, vcc, 0, v1, vcc
	global_load_dwordx4 v[100:103], v[0:1], off
	v_add_u32_e32 v194, 0x4000, v194
	v_add_u32_e32 v195, 4, v192
	v_cmp_gt_u32_e32 vcc, 0x1000, v195
	v_mov_b32_e32 v0, s98
	v_mov_b32_e32 v1, s99
	v_mov_b32_e32 v3, s58
	v_cndmask_b32_e32 v0, v0, v3, vcc
	v_mov_b32_e32 v3, s59
	v_cndmask_b32_e32 v1, v1, v3, vcc
	v_add_co_u32_e32 v0, vcc, v0, v194
	s_nop 1
	v_addc_co_u32_e32 v1, vcc, 0, v1, vcc
	global_load_dwordx4 v[104:107], v[0:1], off
	v_add_u32_e32 v194, 0x4000, v194
	v_add_u32_e32 v195, 8, v192
	v_cmp_gt_u32_e32 vcc, 0x1000, v195
	v_mov_b32_e32 v0, s98
	v_mov_b32_e32 v1, s99
	v_mov_b32_e32 v3, s58
	v_cndmask_b32_e32 v0, v0, v3, vcc
	v_mov_b32_e32 v3, s59
	v_cndmask_b32_e32 v1, v1, v3, vcc
	v_add_co_u32_e32 v0, vcc, v0, v194
	s_nop 1
	v_addc_co_u32_e32 v1, vcc, 0, v1, vcc
	global_load_dwordx4 v[108:111], v[0:1], off
	v_add_u32_e32 v194, 0x4000, v194
	v_add_u32_e32 v195, 12, v192
	v_cmp_gt_u32_e32 vcc, 0x1000, v195
	v_mov_b32_e32 v0, s98
	v_mov_b32_e32 v1, s99
	v_mov_b32_e32 v3, s58
	v_cndmask_b32_e32 v0, v0, v3, vcc
	v_mov_b32_e32 v3, s59
	v_cndmask_b32_e32 v1, v1, v3, vcc
	v_add_co_u32_e32 v0, vcc, v0, v194
	s_nop 1
	v_addc_co_u32_e32 v1, vcc, 0, v1, vcc
	global_load_dwordx4 v[112:115], v[0:1], off
	v_add_u32_e32 v194, 0x4000, v194
	v_add_u32_e32 v195, 16, v192
	v_cmp_gt_u32_e32 vcc, 0x1000, v195
	v_mov_b32_e32 v0, s98
	v_mov_b32_e32 v1, s99
	v_mov_b32_e32 v3, s58
	v_cndmask_b32_e32 v0, v0, v3, vcc
	v_mov_b32_e32 v3, s59
	v_cndmask_b32_e32 v1, v1, v3, vcc
	v_add_co_u32_e32 v0, vcc, v0, v194
	s_nop 1
	v_addc_co_u32_e32 v1, vcc, 0, v1, vcc
	global_load_dwordx4 v[116:119], v[0:1], off
	v_add_u32_e32 v194, 0x4000, v194
	v_add_u32_e32 v195, 20, v192
	v_cmp_gt_u32_e32 vcc, 0x1000, v195
	v_mov_b32_e32 v0, s98
	v_mov_b32_e32 v1, s99
	v_mov_b32_e32 v3, s58
	v_cndmask_b32_e32 v0, v0, v3, vcc
	v_mov_b32_e32 v3, s59
	v_cndmask_b32_e32 v1, v1, v3, vcc
	v_add_co_u32_e32 v0, vcc, v0, v194
	s_nop 1
	v_addc_co_u32_e32 v1, vcc, 0, v1, vcc
	global_load_dwordx4 v[120:123], v[0:1], off
	v_add_u32_e32 v194, 0x4000, v194
	v_add_u32_e32 v195, 24, v192
	v_cmp_gt_u32_e32 vcc, 0x1000, v195
	v_mov_b32_e32 v0, s98
	v_mov_b32_e32 v1, s99
	v_mov_b32_e32 v3, s58
	v_cndmask_b32_e32 v0, v0, v3, vcc
	v_mov_b32_e32 v3, s59
	v_cndmask_b32_e32 v1, v1, v3, vcc
	v_add_co_u32_e32 v0, vcc, v0, v194
	s_nop 1
	v_addc_co_u32_e32 v1, vcc, 0, v1, vcc
	global_load_dwordx4 v[124:127], v[0:1], off
	v_add_u32_e32 v194, 0x4000, v194
	v_add_u32_e32 v195, 28, v192
	v_cmp_gt_u32_e32 vcc, 0x1000, v195
	v_mov_b32_e32 v0, s98
	v_mov_b32_e32 v1, s99
	v_mov_b32_e32 v3, s58
	v_cndmask_b32_e32 v0, v0, v3, vcc
	v_mov_b32_e32 v3, s59
	v_cndmask_b32_e32 v1, v1, v3, vcc
	v_add_co_u32_e32 v0, vcc, v0, v194
	s_nop 1
	v_addc_co_u32_e32 v1, vcc, 0, v1, vcc
	global_load_dwordx4 v[128:131], v[0:1], off
	v_add_u32_e32 v194, 0x4000, v194
	v_add_u32_e32 v195, 32, v192
	v_cmp_gt_u32_e32 vcc, 0x1000, v195
	v_mov_b32_e32 v0, s98
	v_mov_b32_e32 v1, s99
	v_mov_b32_e32 v3, s58
	v_cndmask_b32_e32 v0, v0, v3, vcc
	v_mov_b32_e32 v3, s59
	v_cndmask_b32_e32 v1, v1, v3, vcc
	v_add_co_u32_e32 v0, vcc, v0, v194
	s_nop 1
	v_addc_co_u32_e32 v1, vcc, 0, v1, vcc
	global_load_dwordx4 v[132:135], v[0:1], off
	v_add_u32_e32 v194, 0x4000, v194
	v_add_u32_e32 v195, 36, v192
	v_cmp_gt_u32_e32 vcc, 0x1000, v195
	v_mov_b32_e32 v0, s98
	v_mov_b32_e32 v1, s99
	v_mov_b32_e32 v3, s58
	v_cndmask_b32_e32 v0, v0, v3, vcc
	v_mov_b32_e32 v3, s59
	v_cndmask_b32_e32 v1, v1, v3, vcc
	v_add_co_u32_e32 v0, vcc, v0, v194
	s_nop 1
	v_addc_co_u32_e32 v1, vcc, 0, v1, vcc
	global_load_dwordx4 v[136:139], v[0:1], off
	v_add_u32_e32 v194, 0x4000, v194
	v_add_u32_e32 v195, 40, v192
	v_cmp_gt_u32_e32 vcc, 0x1000, v195
	v_mov_b32_e32 v0, s98
	v_mov_b32_e32 v1, s99
	v_mov_b32_e32 v3, s58
	v_cndmask_b32_e32 v0, v0, v3, vcc
	v_mov_b32_e32 v3, s59
	v_cndmask_b32_e32 v1, v1, v3, vcc
	v_add_co_u32_e32 v0, vcc, v0, v194
	s_nop 1
	v_addc_co_u32_e32 v1, vcc, 0, v1, vcc
	global_load_dwordx4 v[140:143], v[0:1], off
	v_add_u32_e32 v194, 0x4000, v194
	v_add_u32_e32 v195, 44, v192
	v_cmp_gt_u32_e32 vcc, 0x1000, v195
	v_mov_b32_e32 v0, s98
	v_mov_b32_e32 v1, s99
	v_mov_b32_e32 v3, s58
	v_cndmask_b32_e32 v0, v0, v3, vcc
	v_mov_b32_e32 v3, s59
	v_cndmask_b32_e32 v1, v1, v3, vcc
	v_add_co_u32_e32 v0, vcc, v0, v194
	s_nop 1
	v_addc_co_u32_e32 v1, vcc, 0, v1, vcc
	global_load_dwordx4 v[144:147], v[0:1], off
	v_add_u32_e32 v194, 0x4000, v194
	v_add_u32_e32 v195, s4, v193
	global_load_dwordx4 v[148:151], v195, s[100:101]
	v_add_u32_e32 v195, s5, v193
	global_load_dwordx4 v[152:155], v195, s[100:101]
	ds_write_b32 v203, v4 offset:0
	ds_write_b32 v203, v5 offset:272
	ds_write_b32 v203, v6 offset:544
	ds_write_b32 v203, v7 offset:816
	ds_write_b32 v203, v8 offset:64
	ds_write_b32 v203, v9 offset:336
	ds_write_b32 v203, v10 offset:608
	ds_write_b32 v203, v11 offset:880
	ds_write_b32 v203, v12 offset:128
	ds_write_b32 v203, v13 offset:400
	ds_write_b32 v203, v14 offset:672
	ds_write_b32 v203, v15 offset:944
	ds_write_b32 v203, v16 offset:192
	ds_write_b32 v203, v17 offset:464
	ds_write_b32 v203, v18 offset:736
	ds_write_b32 v203, v19 offset:1008
	s_waitcnt lgkmcnt(0)
	ds_read_b128 v[156:159], v204 offset:0
	ds_read_b128 v[160:163], v204 offset:1088
	ds_read_b128 v[164:167], v204 offset:2176
	ds_read_b128 v[168:171], v204 offset:3264
	v_add_u32_e32 v195, 0, v192
	v_cmp_le_u32_e32 vcc, s7, v195
	s_waitcnt vmcnt(0)
	s_waitcnt lgkmcnt(3)
	v_cndmask_b32_e32 v172, v148, v152, vcc
	v_cndmask_b32_e32 v173, v149, v153, vcc
	v_cndmask_b32_e32 v174, v150, v154, vcc
	v_cndmask_b32_e32 v175, v151, v155, vcc
	v_fmac_f32_e32 v100, v172, v156
	v_fmac_f32_e32 v101, v173, v157
	v_fmac_f32_e32 v102, v174, v158
	v_fmac_f32_e32 v103, v175, v159
	global_store_dwordx4 v197, v[100:103], s[56:57] sc0 sc1
	v_add_u32_e32 v197, 0x4000, v197
	v_add_u32_e32 v195, 4, v192
	v_cmp_le_u32_e32 vcc, s7, v195
	s_waitcnt vmcnt(1)
	s_waitcnt lgkmcnt(2)
	v_cndmask_b32_e32 v172, v148, v152, vcc
	v_cndmask_b32_e32 v173, v149, v153, vcc
	v_cndmask_b32_e32 v174, v150, v154, vcc
	v_cndmask_b32_e32 v175, v151, v155, vcc
	v_fmac_f32_e32 v104, v172, v160
	v_fmac_f32_e32 v105, v173, v161
	v_fmac_f32_e32 v106, v174, v162
	v_fmac_f32_e32 v107, v175, v163
	global_store_dwordx4 v197, v[104:107], s[56:57] sc0 sc1
	v_add_u32_e32 v197, 0x4000, v197
	v_add_u32_e32 v195, 8, v192
	v_cmp_le_u32_e32 vcc, s7, v195
	s_waitcnt vmcnt(2)
	s_waitcnt lgkmcnt(1)
	v_cndmask_b32_e32 v172, v148, v152, vcc
	v_cndmask_b32_e32 v173, v149, v153, vcc
	v_cndmask_b32_e32 v174, v150, v154, vcc
	v_cndmask_b32_e32 v175, v151, v155, vcc
	v_fmac_f32_e32 v108, v172, v164
	v_fmac_f32_e32 v109, v173, v165
	v_fmac_f32_e32 v110, v174, v166
	v_fmac_f32_e32 v111, v175, v167
	global_store_dwordx4 v197, v[108:111], s[56:57] sc0 sc1
	v_add_u32_e32 v197, 0x4000, v197
	v_add_u32_e32 v195, 12, v192
	v_cmp_le_u32_e32 vcc, s7, v195
	s_waitcnt vmcnt(3)
	s_waitcnt lgkmcnt(0)
	v_cndmask_b32_e32 v172, v148, v152, vcc
	v_cndmask_b32_e32 v173, v149, v153, vcc
	v_cndmask_b32_e32 v174, v150, v154, vcc
	v_cndmask_b32_e32 v175, v151, v155, vcc
	v_fmac_f32_e32 v112, v172, v168
	v_fmac_f32_e32 v113, v173, v169
	v_fmac_f32_e32 v114, v174, v170
	v_fmac_f32_e32 v115, v175, v171
	global_store_dwordx4 v197, v[112:115], s[56:57] sc0 sc1
	v_add_u32_e32 v197, 0x4000, v197
	ds_write_b32 v203, v20 offset:0
	ds_write_b32 v203, v21 offset:272
	ds_write_b32 v203, v22 offset:544
	ds_write_b32 v203, v23 offset:816
	ds_write_b32 v203, v24 offset:64
	ds_write_b32 v203, v25 offset:336
	ds_write_b32 v203, v26 offset:608
	ds_write_b32 v203, v27 offset:880
	ds_write_b32 v203, v28 offset:128
	ds_write_b32 v203, v29 offset:400
	ds_write_b32 v203, v30 offset:672
	ds_write_b32 v203, v31 offset:944
	ds_write_b32 v203, v32 offset:192
	ds_write_b32 v203, v33 offset:464
	ds_write_b32 v203, v34 offset:736
	ds_write_b32 v203, v35 offset:1008
	s_waitcnt lgkmcnt(0)
	ds_read_b128 v[156:159], v204 offset:0
	ds_read_b128 v[160:163], v204 offset:1088
	ds_read_b128 v[164:167], v204 offset:2176
	ds_read_b128 v[168:171], v204 offset:3264
	v_add_u32_e32 v195, 16, v192
	v_cmp_le_u32_e32 vcc, s7, v195
	s_waitcnt vmcnt(4)
	s_waitcnt lgkmcnt(3)
	v_cndmask_b32_e32 v172, v148, v152, vcc
	v_cndmask_b32_e32 v173, v149, v153, vcc
	v_cndmask_b32_e32 v174, v150, v154, vcc
	v_cndmask_b32_e32 v175, v151, v155, vcc
	v_fmac_f32_e32 v116, v172, v156
	v_fmac_f32_e32 v117, v173, v157
	v_fmac_f32_e32 v118, v174, v158
	v_fmac_f32_e32 v119, v175, v159
	global_store_dwordx4 v197, v[116:119], s[56:57] sc0 sc1
	v_add_u32_e32 v197, 0x4000, v197
	v_add_u32_e32 v195, 20, v192
	v_cmp_le_u32_e32 vcc, s7, v195
	s_waitcnt vmcnt(5)
	s_waitcnt lgkmcnt(2)
	v_cndmask_b32_e32 v172, v148, v152, vcc
	v_cndmask_b32_e32 v173, v149, v153, vcc
	v_cndmask_b32_e32 v174, v150, v154, vcc
	v_cndmask_b32_e32 v175, v151, v155, vcc
	v_fmac_f32_e32 v120, v172, v160
	v_fmac_f32_e32 v121, v173, v161
	v_fmac_f32_e32 v122, v174, v162
	v_fmac_f32_e32 v123, v175, v163
	global_store_dwordx4 v197, v[120:123], s[56:57] sc0 sc1
	v_add_u32_e32 v197, 0x4000, v197
	v_add_u32_e32 v195, 24, v192
	v_cmp_le_u32_e32 vcc, s7, v195
	s_waitcnt vmcnt(6)
	s_waitcnt lgkmcnt(1)
	v_cndmask_b32_e32 v172, v148, v152, vcc
	v_cndmask_b32_e32 v173, v149, v153, vcc
	v_cndmask_b32_e32 v174, v150, v154, vcc
	v_cndmask_b32_e32 v175, v151, v155, vcc
	v_fmac_f32_e32 v124, v172, v164
	v_fmac_f32_e32 v125, v173, v165
	v_fmac_f32_e32 v126, v174, v166
	v_fmac_f32_e32 v127, v175, v167
	global_store_dwordx4 v197, v[124:127], s[56:57] sc0 sc1
	v_add_u32_e32 v197, 0x4000, v197
	v_add_u32_e32 v195, 28, v192
	v_cmp_le_u32_e32 vcc, s7, v195
	s_waitcnt vmcnt(7)
	s_waitcnt lgkmcnt(0)
	v_cndmask_b32_e32 v172, v148, v152, vcc
	v_cndmask_b32_e32 v173, v149, v153, vcc
	v_cndmask_b32_e32 v174, v150, v154, vcc
	v_cndmask_b32_e32 v175, v151, v155, vcc
	v_fmac_f32_e32 v128, v172, v168
	v_fmac_f32_e32 v129, v173, v169
	v_fmac_f32_e32 v130, v174, v170
	v_fmac_f32_e32 v131, v175, v171
	global_store_dwordx4 v197, v[128:131], s[56:57] sc0 sc1
	v_add_u32_e32 v197, 0x4000, v197
	ds_write_b32 v203, v36 offset:0
	ds_write_b32 v203, v37 offset:272
	ds_write_b32 v203, v38 offset:544
	ds_write_b32 v203, v39 offset:816
	ds_write_b32 v203, v40 offset:64
	ds_write_b32 v203, v41 offset:336
	ds_write_b32 v203, v42 offset:608
	ds_write_b32 v203, v43 offset:880
	ds_write_b32 v203, v44 offset:128
	ds_write_b32 v203, v45 offset:400
	ds_write_b32 v203, v46 offset:672
	ds_write_b32 v203, v47 offset:944
	ds_write_b32 v203, v48 offset:192
	ds_write_b32 v203, v49 offset:464
	ds_write_b32 v203, v50 offset:736
	ds_write_b32 v203, v51 offset:1008
	s_waitcnt lgkmcnt(0)
	ds_read_b128 v[156:159], v204 offset:0
	ds_read_b128 v[160:163], v204 offset:1088
	ds_read_b128 v[164:167], v204 offset:2176
	ds_read_b128 v[168:171], v204 offset:3264
	v_add_u32_e32 v195, 32, v192
	v_cmp_le_u32_e32 vcc, s7, v195
	s_waitcnt vmcnt(8)
	s_waitcnt lgkmcnt(3)
	v_cndmask_b32_e32 v172, v148, v152, vcc
	v_cndmask_b32_e32 v173, v149, v153, vcc
	v_cndmask_b32_e32 v174, v150, v154, vcc
	v_cndmask_b32_e32 v175, v151, v155, vcc
	v_fmac_f32_e32 v132, v172, v156
	v_fmac_f32_e32 v133, v173, v157
	v_fmac_f32_e32 v134, v174, v158
	v_fmac_f32_e32 v135, v175, v159
	global_store_dwordx4 v197, v[132:135], s[56:57] sc0 sc1
	v_add_u32_e32 v197, 0x4000, v197
	v_add_u32_e32 v195, 36, v192
	v_cmp_le_u32_e32 vcc, s7, v195
	s_waitcnt vmcnt(9)
	s_waitcnt lgkmcnt(2)
	v_cndmask_b32_e32 v172, v148, v152, vcc
	v_cndmask_b32_e32 v173, v149, v153, vcc
	v_cndmask_b32_e32 v174, v150, v154, vcc
	v_cndmask_b32_e32 v175, v151, v155, vcc
	v_fmac_f32_e32 v136, v172, v160
	v_fmac_f32_e32 v137, v173, v161
	v_fmac_f32_e32 v138, v174, v162
	v_fmac_f32_e32 v139, v175, v163
	global_store_dwordx4 v197, v[136:139], s[56:57] sc0 sc1
	v_add_u32_e32 v197, 0x4000, v197
	v_add_u32_e32 v195, 40, v192
	v_cmp_le_u32_e32 vcc, s7, v195
	s_waitcnt vmcnt(10)
	s_waitcnt lgkmcnt(1)
	v_cndmask_b32_e32 v172, v148, v152, vcc
	v_cndmask_b32_e32 v173, v149, v153, vcc
	v_cndmask_b32_e32 v174, v150, v154, vcc
	v_cndmask_b32_e32 v175, v151, v155, vcc
	v_fmac_f32_e32 v140, v172, v164
	v_fmac_f32_e32 v141, v173, v165
	v_fmac_f32_e32 v142, v174, v166
	v_fmac_f32_e32 v143, v175, v167
	global_store_dwordx4 v197, v[140:143], s[56:57] sc0 sc1
	v_add_u32_e32 v197, 0x4000, v197
	v_add_u32_e32 v195, 44, v192
	v_cmp_le_u32_e32 vcc, s7, v195
	s_waitcnt vmcnt(11)
	s_waitcnt lgkmcnt(0)
	v_cndmask_b32_e32 v172, v148, v152, vcc
	v_cndmask_b32_e32 v173, v149, v153, vcc
	v_cndmask_b32_e32 v174, v150, v154, vcc
	v_cndmask_b32_e32 v175, v151, v155, vcc
	v_fmac_f32_e32 v144, v172, v168
	v_fmac_f32_e32 v145, v173, v169
	v_fmac_f32_e32 v146, v174, v170
	v_fmac_f32_e32 v147, v175, v171
	global_store_dwordx4 v197, v[144:147], s[56:57] sc0 sc1
	v_add_u32_e32 v197, 0x4000, v197
	v_add_u32_e32 v195, 48, v192
	v_cmp_gt_u32_e32 vcc, 0x1000, v195
	v_mov_b32_e32 v0, s98
	v_mov_b32_e32 v1, s99
	v_mov_b32_e32 v3, s58
	v_cndmask_b32_e32 v0, v0, v3, vcc
	v_mov_b32_e32 v3, s59
	v_cndmask_b32_e32 v1, v1, v3, vcc
	v_add_co_u32_e32 v0, vcc, v0, v194
	s_nop 1
	v_addc_co_u32_e32 v1, vcc, 0, v1, vcc
	global_load_dwordx4 v[100:103], v[0:1], off
	v_add_u32_e32 v194, 0x4000, v194
	v_add_u32_e32 v195, 52, v192
	v_cmp_gt_u32_e32 vcc, 0x1000, v195
	v_mov_b32_e32 v0, s98
	v_mov_b32_e32 v1, s99
	v_mov_b32_e32 v3, s58
	v_cndmask_b32_e32 v0, v0, v3, vcc
	v_mov_b32_e32 v3, s59
	v_cndmask_b32_e32 v1, v1, v3, vcc
	v_add_co_u32_e32 v0, vcc, v0, v194
	s_nop 1
	v_addc_co_u32_e32 v1, vcc, 0, v1, vcc
	global_load_dwordx4 v[104:107], v[0:1], off
	v_add_u32_e32 v194, 0x4000, v194
	v_add_u32_e32 v195, 56, v192
	v_cmp_gt_u32_e32 vcc, 0x1000, v195
	v_mov_b32_e32 v0, s98
	v_mov_b32_e32 v1, s99
	v_mov_b32_e32 v3, s58
	v_cndmask_b32_e32 v0, v0, v3, vcc
	v_mov_b32_e32 v3, s59
	v_cndmask_b32_e32 v1, v1, v3, vcc
	v_add_co_u32_e32 v0, vcc, v0, v194
	s_nop 1
	v_addc_co_u32_e32 v1, vcc, 0, v1, vcc
	global_load_dwordx4 v[108:111], v[0:1], off
	v_add_u32_e32 v194, 0x4000, v194
	v_add_u32_e32 v195, 60, v192
	v_cmp_gt_u32_e32 vcc, 0x1000, v195
	v_mov_b32_e32 v0, s98
	v_mov_b32_e32 v1, s99
	v_mov_b32_e32 v3, s58
	v_cndmask_b32_e32 v0, v0, v3, vcc
	v_mov_b32_e32 v3, s59
	v_cndmask_b32_e32 v1, v1, v3, vcc
	v_add_co_u32_e32 v0, vcc, v0, v194
	s_nop 1
	v_addc_co_u32_e32 v1, vcc, 0, v1, vcc
	global_load_dwordx4 v[112:115], v[0:1], off
	v_add_u32_e32 v194, 0x4000, v194
	v_add_u32_e32 v195, 64, v192
	v_cmp_gt_u32_e32 vcc, 0x1000, v195
	v_mov_b32_e32 v0, s98
	v_mov_b32_e32 v1, s99
	v_mov_b32_e32 v3, s58
	v_cndmask_b32_e32 v0, v0, v3, vcc
	v_mov_b32_e32 v3, s59
	v_cndmask_b32_e32 v1, v1, v3, vcc
	v_add_co_u32_e32 v0, vcc, v0, v194
	s_nop 1
	v_addc_co_u32_e32 v1, vcc, 0, v1, vcc
	global_load_dwordx4 v[116:119], v[0:1], off
	v_add_u32_e32 v194, 0x4000, v194
	v_add_u32_e32 v195, 68, v192
	v_cmp_gt_u32_e32 vcc, 0x1000, v195
	v_mov_b32_e32 v0, s98
	v_mov_b32_e32 v1, s99
	v_mov_b32_e32 v3, s58
	v_cndmask_b32_e32 v0, v0, v3, vcc
	v_mov_b32_e32 v3, s59
	v_cndmask_b32_e32 v1, v1, v3, vcc
	v_add_co_u32_e32 v0, vcc, v0, v194
	s_nop 1
	v_addc_co_u32_e32 v1, vcc, 0, v1, vcc
	global_load_dwordx4 v[120:123], v[0:1], off
	v_add_u32_e32 v194, 0x4000, v194
	v_add_u32_e32 v195, 72, v192
	v_cmp_gt_u32_e32 vcc, 0x1000, v195
	v_mov_b32_e32 v0, s98
	v_mov_b32_e32 v1, s99
	v_mov_b32_e32 v3, s58
	v_cndmask_b32_e32 v0, v0, v3, vcc
	v_mov_b32_e32 v3, s59
	v_cndmask_b32_e32 v1, v1, v3, vcc
	v_add_co_u32_e32 v0, vcc, v0, v194
	s_nop 1
	v_addc_co_u32_e32 v1, vcc, 0, v1, vcc
	global_load_dwordx4 v[124:127], v[0:1], off
	v_add_u32_e32 v194, 0x4000, v194
	v_add_u32_e32 v195, 76, v192
	v_cmp_gt_u32_e32 vcc, 0x1000, v195
	v_mov_b32_e32 v0, s98
	v_mov_b32_e32 v1, s99
	v_mov_b32_e32 v3, s58
	v_cndmask_b32_e32 v0, v0, v3, vcc
	v_mov_b32_e32 v3, s59
	v_cndmask_b32_e32 v1, v1, v3, vcc
	v_add_co_u32_e32 v0, vcc, v0, v194
	s_nop 1
	v_addc_co_u32_e32 v1, vcc, 0, v1, vcc
	global_load_dwordx4 v[128:131], v[0:1], off
	v_add_u32_e32 v194, 0x4000, v194
	v_add_u32_e32 v195, 80, v192
	v_cmp_gt_u32_e32 vcc, 0x1000, v195
	v_mov_b32_e32 v0, s98
	v_mov_b32_e32 v1, s99
	v_mov_b32_e32 v3, s58
	v_cndmask_b32_e32 v0, v0, v3, vcc
	v_mov_b32_e32 v3, s59
	v_cndmask_b32_e32 v1, v1, v3, vcc
	v_add_co_u32_e32 v0, vcc, v0, v194
	s_nop 1
	v_addc_co_u32_e32 v1, vcc, 0, v1, vcc
	global_load_dwordx4 v[132:135], v[0:1], off
	v_add_u32_e32 v194, 0x4000, v194
	v_add_u32_e32 v195, 84, v192
	v_cmp_gt_u32_e32 vcc, 0x1000, v195
	v_mov_b32_e32 v0, s98
	v_mov_b32_e32 v1, s99
	v_mov_b32_e32 v3, s58
	v_cndmask_b32_e32 v0, v0, v3, vcc
	v_mov_b32_e32 v3, s59
	v_cndmask_b32_e32 v1, v1, v3, vcc
	v_add_co_u32_e32 v0, vcc, v0, v194
	s_nop 1
	v_addc_co_u32_e32 v1, vcc, 0, v1, vcc
	global_load_dwordx4 v[136:139], v[0:1], off
	v_add_u32_e32 v194, 0x4000, v194
	v_add_u32_e32 v195, 88, v192
	v_cmp_gt_u32_e32 vcc, 0x1000, v195
	v_mov_b32_e32 v0, s98
	v_mov_b32_e32 v1, s99
	v_mov_b32_e32 v3, s58
	v_cndmask_b32_e32 v0, v0, v3, vcc
	v_mov_b32_e32 v3, s59
	v_cndmask_b32_e32 v1, v1, v3, vcc
	v_add_co_u32_e32 v0, vcc, v0, v194
	s_nop 1
	v_addc_co_u32_e32 v1, vcc, 0, v1, vcc
	global_load_dwordx4 v[140:143], v[0:1], off
	v_add_u32_e32 v194, 0x4000, v194
	v_add_u32_e32 v195, 92, v192
	v_cmp_gt_u32_e32 vcc, 0x1000, v195
	v_mov_b32_e32 v0, s98
	v_mov_b32_e32 v1, s99
	v_mov_b32_e32 v3, s58
	v_cndmask_b32_e32 v0, v0, v3, vcc
	v_mov_b32_e32 v3, s59
	v_cndmask_b32_e32 v1, v1, v3, vcc
	v_add_co_u32_e32 v0, vcc, v0, v194
	s_nop 1
	v_addc_co_u32_e32 v1, vcc, 0, v1, vcc
	global_load_dwordx4 v[144:147], v[0:1], off
	v_add_u32_e32 v194, 0x4000, v194
	ds_write_b32 v203, v52 offset:0
	ds_write_b32 v203, v53 offset:272
	ds_write_b32 v203, v54 offset:544
	ds_write_b32 v203, v55 offset:816
	ds_write_b32 v203, v56 offset:64
	ds_write_b32 v203, v57 offset:336
	ds_write_b32 v203, v58 offset:608
	ds_write_b32 v203, v59 offset:880
	ds_write_b32 v203, v60 offset:128
	ds_write_b32 v203, v61 offset:400
	ds_write_b32 v203, v62 offset:672
	ds_write_b32 v203, v63 offset:944
	ds_write_b32 v203, v64 offset:192
	ds_write_b32 v203, v65 offset:464
	ds_write_b32 v203, v66 offset:736
	ds_write_b32 v203, v67 offset:1008
	s_waitcnt lgkmcnt(0)
	ds_read_b128 v[156:159], v204 offset:0
	ds_read_b128 v[160:163], v204 offset:1088
	ds_read_b128 v[164:167], v204 offset:2176
	ds_read_b128 v[168:171], v204 offset:3264
	v_add_u32_e32 v195, 48, v192
	v_cmp_le_u32_e32 vcc, s7, v195
	s_waitcnt vmcnt(11)
	s_waitcnt lgkmcnt(3)
	v_cndmask_b32_e32 v172, v148, v152, vcc
	v_cndmask_b32_e32 v173, v149, v153, vcc
	v_cndmask_b32_e32 v174, v150, v154, vcc
	v_cndmask_b32_e32 v175, v151, v155, vcc
	v_fmac_f32_e32 v100, v172, v156
	v_fmac_f32_e32 v101, v173, v157
	v_fmac_f32_e32 v102, v174, v158
	v_fmac_f32_e32 v103, v175, v159
	global_store_dwordx4 v197, v[100:103], s[56:57] sc0 sc1
	v_add_u32_e32 v197, 0x4000, v197
	v_add_u32_e32 v195, 52, v192
	v_cmp_le_u32_e32 vcc, s7, v195
	s_waitcnt vmcnt(11)
	s_waitcnt lgkmcnt(2)
	v_cndmask_b32_e32 v172, v148, v152, vcc
	v_cndmask_b32_e32 v173, v149, v153, vcc
	v_cndmask_b32_e32 v174, v150, v154, vcc
	v_cndmask_b32_e32 v175, v151, v155, vcc
	v_fmac_f32_e32 v104, v172, v160
	v_fmac_f32_e32 v105, v173, v161
	v_fmac_f32_e32 v106, v174, v162
	v_fmac_f32_e32 v107, v175, v163
	global_store_dwordx4 v197, v[104:107], s[56:57] sc0 sc1
	v_add_u32_e32 v197, 0x4000, v197
	v_add_u32_e32 v195, 56, v192
	v_cmp_le_u32_e32 vcc, s7, v195
	s_waitcnt vmcnt(11)
	s_waitcnt lgkmcnt(1)
	v_cndmask_b32_e32 v172, v148, v152, vcc
	v_cndmask_b32_e32 v173, v149, v153, vcc
	v_cndmask_b32_e32 v174, v150, v154, vcc
	v_cndmask_b32_e32 v175, v151, v155, vcc
	v_fmac_f32_e32 v108, v172, v164
	v_fmac_f32_e32 v109, v173, v165
	v_fmac_f32_e32 v110, v174, v166
	v_fmac_f32_e32 v111, v175, v167
	global_store_dwordx4 v197, v[108:111], s[56:57] sc0 sc1
	v_add_u32_e32 v197, 0x4000, v197
	v_add_u32_e32 v195, 60, v192
	v_cmp_le_u32_e32 vcc, s7, v195
	s_waitcnt vmcnt(11)
	s_waitcnt lgkmcnt(0)
	v_cndmask_b32_e32 v172, v148, v152, vcc
	v_cndmask_b32_e32 v173, v149, v153, vcc
	v_cndmask_b32_e32 v174, v150, v154, vcc
	v_cndmask_b32_e32 v175, v151, v155, vcc
	v_fmac_f32_e32 v112, v172, v168
	v_fmac_f32_e32 v113, v173, v169
	v_fmac_f32_e32 v114, v174, v170
	v_fmac_f32_e32 v115, v175, v171
	global_store_dwordx4 v197, v[112:115], s[56:57] sc0 sc1
	v_add_u32_e32 v197, 0x4000, v197
	ds_write_b32 v203, v68 offset:0
	ds_write_b32 v203, v69 offset:272
	ds_write_b32 v203, v70 offset:544
	ds_write_b32 v203, v71 offset:816
	ds_write_b32 v203, v72 offset:64
	ds_write_b32 v203, v73 offset:336
	ds_write_b32 v203, v74 offset:608
	ds_write_b32 v203, v75 offset:880
	ds_write_b32 v203, v76 offset:128
	ds_write_b32 v203, v77 offset:400
	ds_write_b32 v203, v78 offset:672
	ds_write_b32 v203, v79 offset:944
	ds_write_b32 v203, v80 offset:192
	ds_write_b32 v203, v81 offset:464
	ds_write_b32 v203, v82 offset:736
	ds_write_b32 v203, v83 offset:1008
	s_waitcnt lgkmcnt(0)
	ds_read_b128 v[156:159], v204 offset:0
	ds_read_b128 v[160:163], v204 offset:1088
	ds_read_b128 v[164:167], v204 offset:2176
	ds_read_b128 v[168:171], v204 offset:3264
	v_add_u32_e32 v195, 64, v192
	v_cmp_le_u32_e32 vcc, s7, v195
	s_waitcnt vmcnt(11)
	s_waitcnt lgkmcnt(3)
	v_cndmask_b32_e32 v172, v148, v152, vcc
	v_cndmask_b32_e32 v173, v149, v153, vcc
	v_cndmask_b32_e32 v174, v150, v154, vcc
	v_cndmask_b32_e32 v175, v151, v155, vcc
	v_fmac_f32_e32 v116, v172, v156
	v_fmac_f32_e32 v117, v173, v157
	v_fmac_f32_e32 v118, v174, v158
	v_fmac_f32_e32 v119, v175, v159
	global_store_dwordx4 v197, v[116:119], s[56:57] sc0 sc1
	v_add_u32_e32 v197, 0x4000, v197
	v_add_u32_e32 v195, 68, v192
	v_cmp_le_u32_e32 vcc, s7, v195
	s_waitcnt vmcnt(11)
	s_waitcnt lgkmcnt(2)
	v_cndmask_b32_e32 v172, v148, v152, vcc
	v_cndmask_b32_e32 v173, v149, v153, vcc
	v_cndmask_b32_e32 v174, v150, v154, vcc
	v_cndmask_b32_e32 v175, v151, v155, vcc
	v_fmac_f32_e32 v120, v172, v160
	v_fmac_f32_e32 v121, v173, v161
	v_fmac_f32_e32 v122, v174, v162
	v_fmac_f32_e32 v123, v175, v163
	global_store_dwordx4 v197, v[120:123], s[56:57] sc0 sc1
	v_add_u32_e32 v197, 0x4000, v197
	v_add_u32_e32 v195, 72, v192
	v_cmp_le_u32_e32 vcc, s7, v195
	s_waitcnt vmcnt(11)
	s_waitcnt lgkmcnt(1)
	v_cndmask_b32_e32 v172, v148, v152, vcc
	v_cndmask_b32_e32 v173, v149, v153, vcc
	v_cndmask_b32_e32 v174, v150, v154, vcc
	v_cndmask_b32_e32 v175, v151, v155, vcc
	v_fmac_f32_e32 v124, v172, v164
	v_fmac_f32_e32 v125, v173, v165
	v_fmac_f32_e32 v126, v174, v166
	v_fmac_f32_e32 v127, v175, v167
	global_store_dwordx4 v197, v[124:127], s[56:57] sc0 sc1
	v_add_u32_e32 v197, 0x4000, v197
	v_add_u32_e32 v195, 76, v192
	v_cmp_le_u32_e32 vcc, s7, v195
	s_waitcnt vmcnt(11)
	s_waitcnt lgkmcnt(0)
	v_cndmask_b32_e32 v172, v148, v152, vcc
	v_cndmask_b32_e32 v173, v149, v153, vcc
	v_cndmask_b32_e32 v174, v150, v154, vcc
	v_cndmask_b32_e32 v175, v151, v155, vcc
	v_fmac_f32_e32 v128, v172, v168
	v_fmac_f32_e32 v129, v173, v169
	v_fmac_f32_e32 v130, v174, v170
	v_fmac_f32_e32 v131, v175, v171
	global_store_dwordx4 v197, v[128:131], s[56:57] sc0 sc1
	v_add_u32_e32 v197, 0x4000, v197
	ds_write_b32 v203, v84 offset:0
	ds_write_b32 v203, v85 offset:272
	ds_write_b32 v203, v86 offset:544
	ds_write_b32 v203, v87 offset:816
	ds_write_b32 v203, v88 offset:64
	ds_write_b32 v203, v89 offset:336
	ds_write_b32 v203, v90 offset:608
	ds_write_b32 v203, v91 offset:880
	ds_write_b32 v203, v92 offset:128
	ds_write_b32 v203, v93 offset:400
	ds_write_b32 v203, v94 offset:672
	ds_write_b32 v203, v95 offset:944
	ds_write_b32 v203, v96 offset:192
	ds_write_b32 v203, v97 offset:464
	ds_write_b32 v203, v98 offset:736
	ds_write_b32 v203, v99 offset:1008
	s_waitcnt lgkmcnt(0)
	ds_read_b128 v[156:159], v204 offset:0
	ds_read_b128 v[160:163], v204 offset:1088
	ds_read_b128 v[164:167], v204 offset:2176
	ds_read_b128 v[168:171], v204 offset:3264
	v_add_u32_e32 v195, 80, v192
	v_cmp_le_u32_e32 vcc, s7, v195
	s_waitcnt vmcnt(11)
	s_waitcnt lgkmcnt(3)
	v_cndmask_b32_e32 v172, v148, v152, vcc
	v_cndmask_b32_e32 v173, v149, v153, vcc
	v_cndmask_b32_e32 v174, v150, v154, vcc
	v_cndmask_b32_e32 v175, v151, v155, vcc
	v_fmac_f32_e32 v132, v172, v156
	v_fmac_f32_e32 v133, v173, v157
	v_fmac_f32_e32 v134, v174, v158
	v_fmac_f32_e32 v135, v175, v159
	global_store_dwordx4 v197, v[132:135], s[56:57] sc0 sc1
	v_add_u32_e32 v197, 0x4000, v197
	v_add_u32_e32 v195, 84, v192
	v_cmp_le_u32_e32 vcc, s7, v195
	s_waitcnt vmcnt(11)
	s_waitcnt lgkmcnt(2)
	v_cndmask_b32_e32 v172, v148, v152, vcc
	v_cndmask_b32_e32 v173, v149, v153, vcc
	v_cndmask_b32_e32 v174, v150, v154, vcc
	v_cndmask_b32_e32 v175, v151, v155, vcc
	v_fmac_f32_e32 v136, v172, v160
	v_fmac_f32_e32 v137, v173, v161
	v_fmac_f32_e32 v138, v174, v162
	v_fmac_f32_e32 v139, v175, v163
	global_store_dwordx4 v197, v[136:139], s[56:57] sc0 sc1
	v_add_u32_e32 v197, 0x4000, v197
	v_add_u32_e32 v195, 88, v192
	v_cmp_le_u32_e32 vcc, s7, v195
	s_waitcnt vmcnt(11)
	s_waitcnt lgkmcnt(1)
	v_cndmask_b32_e32 v172, v148, v152, vcc
	v_cndmask_b32_e32 v173, v149, v153, vcc
	v_cndmask_b32_e32 v174, v150, v154, vcc
	v_cndmask_b32_e32 v175, v151, v155, vcc
	v_fmac_f32_e32 v140, v172, v164
	v_fmac_f32_e32 v141, v173, v165
	v_fmac_f32_e32 v142, v174, v166
	v_fmac_f32_e32 v143, v175, v167
	global_store_dwordx4 v197, v[140:143], s[56:57] sc0 sc1
	v_add_u32_e32 v197, 0x4000, v197
	v_add_u32_e32 v195, 92, v192
	v_cmp_le_u32_e32 vcc, s7, v195
	s_waitcnt vmcnt(11)
	s_waitcnt lgkmcnt(0)
	v_cndmask_b32_e32 v172, v148, v152, vcc
	v_cndmask_b32_e32 v173, v149, v153, vcc
	v_cndmask_b32_e32 v174, v150, v154, vcc
	v_cndmask_b32_e32 v175, v151, v155, vcc
	v_fmac_f32_e32 v144, v172, v168
	v_fmac_f32_e32 v145, v173, v169
	v_fmac_f32_e32 v146, v174, v170
	v_fmac_f32_e32 v147, v175, v171
	global_store_dwordx4 v197, v[144:147], s[56:57] sc0 sc1
	v_add_u32_e32 v197, 0x4000, v197
	v_mov_b32_e32 v4, 0
	v_mov_b32_e32 v5, 0
	v_mov_b32_e32 v6, 0
	v_mov_b32_e32 v7, 0
	v_mov_b32_e32 v8, 0
	v_mov_b32_e32 v9, 0
	v_mov_b32_e32 v10, 0
	v_mov_b32_e32 v11, 0
	v_mov_b32_e32 v12, 0
	v_mov_b32_e32 v13, 0
	v_mov_b32_e32 v14, 0
	v_mov_b32_e32 v15, 0
	v_mov_b32_e32 v16, 0
	v_mov_b32_e32 v17, 0
	v_mov_b32_e32 v18, 0
	v_mov_b32_e32 v19, 0
	v_mov_b32_e32 v20, 0
	v_mov_b32_e32 v21, 0
	v_mov_b32_e32 v22, 0
	v_mov_b32_e32 v23, 0
	v_mov_b32_e32 v24, 0
	v_mov_b32_e32 v25, 0
	v_mov_b32_e32 v26, 0
	v_mov_b32_e32 v27, 0
	v_mov_b32_e32 v28, 0
	v_mov_b32_e32 v29, 0
	v_mov_b32_e32 v30, 0
	v_mov_b32_e32 v31, 0
	v_mov_b32_e32 v32, 0
	v_mov_b32_e32 v33, 0
	v_mov_b32_e32 v34, 0
	v_mov_b32_e32 v35, 0
	v_mov_b32_e32 v36, 0
	v_mov_b32_e32 v37, 0
	v_mov_b32_e32 v38, 0
	v_mov_b32_e32 v39, 0
	v_mov_b32_e32 v40, 0
	v_mov_b32_e32 v41, 0
	v_mov_b32_e32 v42, 0
	v_mov_b32_e32 v43, 0
	v_mov_b32_e32 v44, 0
	v_mov_b32_e32 v45, 0
	v_mov_b32_e32 v46, 0
	v_mov_b32_e32 v47, 0
	v_mov_b32_e32 v48, 0
	v_mov_b32_e32 v49, 0
	v_mov_b32_e32 v50, 0
	v_mov_b32_e32 v51, 0
	v_mov_b32_e32 v52, 0
	v_mov_b32_e32 v53, 0
	v_mov_b32_e32 v54, 0
	v_mov_b32_e32 v55, 0
	v_mov_b32_e32 v56, 0
	v_mov_b32_e32 v57, 0
	v_mov_b32_e32 v58, 0
	v_mov_b32_e32 v59, 0
	v_mov_b32_e32 v60, 0
	v_mov_b32_e32 v61, 0
	v_mov_b32_e32 v62, 0
	v_mov_b32_e32 v63, 0
	v_mov_b32_e32 v64, 0
	v_mov_b32_e32 v65, 0
	v_mov_b32_e32 v66, 0
	v_mov_b32_e32 v67, 0
	v_mov_b32_e32 v68, 0
	v_mov_b32_e32 v69, 0
	v_mov_b32_e32 v70, 0
	v_mov_b32_e32 v71, 0
	v_mov_b32_e32 v72, 0
	v_mov_b32_e32 v73, 0
	v_mov_b32_e32 v74, 0
	v_mov_b32_e32 v75, 0
	v_mov_b32_e32 v76, 0
	v_mov_b32_e32 v77, 0
	v_mov_b32_e32 v78, 0
	v_mov_b32_e32 v79, 0
	v_mov_b32_e32 v80, 0
	v_mov_b32_e32 v81, 0
	v_mov_b32_e32 v82, 0
	v_mov_b32_e32 v83, 0
	v_mov_b32_e32 v84, 0
	v_mov_b32_e32 v85, 0
	v_mov_b32_e32 v86, 0
	v_mov_b32_e32 v87, 0
	v_mov_b32_e32 v88, 0
	v_mov_b32_e32 v89, 0
	v_mov_b32_e32 v90, 0
	v_mov_b32_e32 v91, 0
	v_mov_b32_e32 v92, 0
	v_mov_b32_e32 v93, 0
	v_mov_b32_e32 v94, 0
	v_mov_b32_e32 v95, 0
	v_mov_b32_e32 v96, 0
	v_mov_b32_e32 v97, 0
	v_mov_b32_e32 v98, 0
	v_mov_b32_e32 v99, 0
	s_mov_b32 s34, 0
	s_add_u32 s35, s35, s52
	s_cmp_ge_u32 s31, s30
	s_cbranch_scc1 .Lgm_wo_exit

.Lgm_wi_cnt:
	s_add_u32 s30, s30, 16
	s_add_u32 s4, s4, s52
	s_cmp_lt_u32 s4, s54
	s_cbranch_scc1 .Lgm_wi_cnt
	s_add_u32 s48, s96, 0x2e24000
	s_addc_u32 s49, s97, 0
	s_mul_i32 s4, s36, 0x4c0000
	s_add_u32 s50, s96, 0x0
	s_addc_u32 s51, s97, 0
	s_add_u32 s50, s50, s4
	s_addc_u32 s51, s51, 0
	v_and_b32_e32 v0, 63, v206
	v_lshrrev_b32_e32 v1, 6, v206
	s_mov_b32 s31, 0
	v_readfirstlane_b32 s42, v1
	s_nop 0
	s_cmp_ge_u32 s42, 4
	s_cbranch_scc1 .Lgm_wi_compute
	v_lshrrev_b32_e32 v3, 3, v0
	v_and_b32_e32 v4, 7, v0
	v_xor_b32_e32 v4, v4, v3
	v_lshl_add_u32 v3, v1, 3, v3
	v_lshlrev_b32_e32 v3, 11, v3
	v_lshl_add_u32 v180, v4, 4, v3
	v_add_u32_e32 v181, 0x10000, v180
	v_add_u32_e32 v182, 0x20000, v180
	v_add_u32_e32 v183, 0x30000, v180
	v_add_u32_e32 v184, 0x40000, v180
	v_add_u32_e32 v185, 0x50000, v180
	s_lshl_b32 s42, s42, 10
	s_mov_b32 s38, s53
	s_mov_b32 s39, 0
	s_mov_b32 s41, s42
	s_and_b32 s4, s38, 31
	s_mul_i32 s4, s4, 0x60000
	s_add_u32 s44, s48, s4
	s_addc_u32 s45, s49, 0
	s_lshr_b32 s4, s38, 5
	s_mul_i32 s4, s4, 0x40000
	s_add_u32 s46, s50, s4
	s_addc_u32 s47, s51, 0
	s_add_u32 m0, s41, 0x0
	s_nop 0
	global_load_lds_dwordx4 v180, s[44:45]
	s_add_u32 m0, s41, 0x1000
	s_nop 0
	global_load_lds_dwordx4 v181, s[44:45]
	s_add_u32 m0, s41, 0x2000
	s_nop 0
	global_load_lds_dwordx4 v182, s[44:45]
	s_add_u32 m0, s41, 0x3000
	s_nop 0
	global_load_lds_dwordx4 v183, s[44:45]
	s_add_u32 m0, s41, 0x4000
	s_nop 0
	global_load_lds_dwordx4 v184, s[44:45]
	s_add_u32 m0, s41, 0x5000
	s_nop 0
	global_load_lds_dwordx4 v185, s[44:45]
	s_add_u32 m0, s41, 0x6000
	s_nop 0
	global_load_lds_dwordx4 v180, s[46:47]
	s_add_u32 m0, s41, 0x7000
	s_nop 0
	global_load_lds_dwordx4 v181, s[46:47]
	s_add_u32 m0, s41, 0x8000
	s_nop 0
	global_load_lds_dwordx4 v182, s[46:47]
	s_add_u32 m0, s41, 0x9000
	s_nop 0
	global_load_lds_dwordx4 v183, s[46:47]
	s_add_u32 s39, s39, 1
	s_add_u32 s44, s44, 0x80
	s_addc_u32 s45, s45, 0
	s_add_u32 s46, s46, 0x80
	s_addc_u32 s47, s47, 0
	s_cmp_lt_u32 s39, 16
	s_cbranch_scc1 .Lgm_wi_dadv1
	s_mov_b32 s39, 0
	s_add_u32 s4, s38, s52
	s_cmp_lt_u32 s4, s54
	s_cselect_b32 s38, s4, s38
	s_and_b32 s4, s38, 31
	s_mul_i32 s4, s4, 0x60000
	s_add_u32 s44, s48, s4
	s_addc_u32 s45, s49, 0
	s_lshr_b32 s4, s38, 5
	s_mul_i32 s4, s4, 0x40000
	s_add_u32 s46, s50, s4
	s_addc_u32 s47, s51, 0

.Lgm_wi_compute:
	v_and_b32_e32 v1, 3, v1
	v_and_b32_e32 v194, 15, v0
	v_lshrrev_b32_e32 v195, 4, v0
	v_and_b32_e32 v3, 7, v194
	v_xor_b32_e32 v3, v3, v195
	v_lshlrev_b32_e32 v3, 4, v3
	v_lshrrev_b32_e32 v176, 1, v1
	v_and_b32_e32 v177, 1, v1
	v_mul_u32_u24_e32 v178, 96, v176
	v_add_u32_e32 v179, v178, v194
	v_lshl_add_u32 v199, v179, 7, v3
	v_xor_b32_e32 v200, 64, v199
	v_lshl_add_u32 v179, v177, 6, v194
	v_lshl_add_u32 v201, v179, 7, v3
	v_add_u32_e32 v201, 0x6000, v201
	v_xor_b32_e32 v202, 64, v201
	s_sub_u32 s42, s42, 4
	s_mul_i32 s5, s42, 4352
	s_add_u32 s5, s5, 0x1e000
	v_mul_u32_u24_e32 v3, 1088, v195
	v_lshl_add_u32 v3, v194, 2, v3
	v_add_u32_e32 v203, s5, v3
	v_mul_u32_u24_e32 v3, 272, v195
	v_lshl_add_u32 v3, v194, 4, v3
	v_add_u32_e32 v204, s5, v3
	v_add_u32_e32 v190, v178, v195
	v_lshlrev_b32_e32 v3, 6, v177
	v_lshl_add_u32 v3, v194, 2, v3
	s_mov_b32 s4, 0x2440
	v_mul_lo_u32 v205, v190, s4
	v_lshl_add_u32 v205, v3, 2, v205
	v_lshlrev_b32_e32 v191, 2, v3
	v_mov_b32_e32 v193, v3
	v_mov_b32_e32 v4, 0
	v_mov_b32_e32 v5, 0
	v_mov_b32_e32 v6, 0
	v_mov_b32_e32 v7, 0
	v_mov_b32_e32 v8, 0
	v_mov_b32_e32 v9, 0
	v_mov_b32_e32 v10, 0
	v_mov_b32_e32 v11, 0
	v_mov_b32_e32 v12, 0
	v_mov_b32_e32 v13, 0
	v_mov_b32_e32 v14, 0
	v_mov_b32_e32 v15, 0
	v_mov_b32_e32 v16, 0
	v_mov_b32_e32 v17, 0
	v_mov_b32_e32 v18, 0
	v_mov_b32_e32 v19, 0
	v_mov_b32_e32 v20, 0
	v_mov_b32_e32 v21, 0
	v_mov_b32_e32 v22, 0
	v_mov_b32_e32 v23, 0
	v_mov_b32_e32 v24, 0
	v_mov_b32_e32 v25, 0
	v_mov_b32_e32 v26, 0
	v_mov_b32_e32 v27, 0
	v_mov_b32_e32 v28, 0
	v_mov_b32_e32 v29, 0
	v_mov_b32_e32 v30, 0
	v_mov_b32_e32 v31, 0
	v_mov_b32_e32 v32, 0
	v_mov_b32_e32 v33, 0
	v_mov_b32_e32 v34, 0
	v_mov_b32_e32 v35, 0
	v_mov_b32_e32 v36, 0
	v_mov_b32_e32 v37, 0
	v_mov_b32_e32 v38, 0
	v_mov_b32_e32 v39, 0
	v_mov_b32_e32 v40, 0
	v_mov_b32_e32 v41, 0
	v_mov_b32_e32 v42, 0
	v_mov_b32_e32 v43, 0
	v_mov_b32_e32 v44, 0
	v_mov_b32_e32 v45, 0
	v_mov_b32_e32 v46, 0
	v_mov_b32_e32 v47, 0
	v_mov_b32_e32 v48, 0
	v_mov_b32_e32 v49, 0
	v_mov_b32_e32 v50, 0
	v_mov_b32_e32 v51, 0
	v_mov_b32_e32 v52, 0
	v_mov_b32_e32 v53, 0
	v_mov_b32_e32 v54, 0
	v_mov_b32_e32 v55, 0
	v_mov_b32_e32 v56, 0
	v_mov_b32_e32 v57, 0
	v_mov_b32_e32 v58, 0
	v_mov_b32_e32 v59, 0
	v_mov_b32_e32 v60, 0
	v_mov_b32_e32 v61, 0
	v_mov_b32_e32 v62, 0
	v_mov_b32_e32 v63, 0
	v_mov_b32_e32 v64, 0
	v_mov_b32_e32 v65, 0
	v_mov_b32_e32 v66, 0
	v_mov_b32_e32 v67, 0
	v_mov_b32_e32 v68, 0
	v_mov_b32_e32 v69, 0
	v_mov_b32_e32 v70, 0
	v_mov_b32_e32 v71, 0
	v_mov_b32_e32 v72, 0
	v_mov_b32_e32 v73, 0
	v_mov_b32_e32 v74, 0
	v_mov_b32_e32 v75, 0
	v_mov_b32_e32 v76, 0
	v_mov_b32_e32 v77, 0
	v_mov_b32_e32 v78, 0
	v_mov_b32_e32 v79, 0
	v_mov_b32_e32 v80, 0
	v_mov_b32_e32 v81, 0
	v_mov_b32_e32 v82, 0
	v_mov_b32_e32 v83, 0
	v_mov_b32_e32 v84, 0
	v_mov_b32_e32 v85, 0
	v_mov_b32_e32 v86, 0
	v_mov_b32_e32 v87, 0
	v_mov_b32_e32 v88, 0
	v_mov_b32_e32 v89, 0
	v_mov_b32_e32 v90, 0
	v_mov_b32_e32 v91, 0
	v_mov_b32_e32 v92, 0
	v_mov_b32_e32 v93, 0
	v_mov_b32_e32 v94, 0
	v_mov_b32_e32 v95, 0
	v_mov_b32_e32 v96, 0
	v_mov_b32_e32 v97, 0
	v_mov_b32_e32 v98, 0
	v_mov_b32_e32 v99, 0
	s_mov_b32 s34, 0
	s_mov_b32 s35, s53
	s_mov_b32 s40, 0

.Lgm_wi_join:
	s_waitcnt lgkmcnt(13)
	v_mfma_f32_16x16x32_bf16 v[4:7], v[100:103], v[124:127], v[4:7]
	v_mfma_f32_16x16x32_bf16 v[20:23], v[104:107], v[124:127], v[20:23]
	v_mfma_f32_16x16x32_bf16 v[36:39], v[108:111], v[124:127], v[36:39]
	v_mfma_f32_16x16x32_bf16 v[52:55], v[112:115], v[124:127], v[52:55]
	v_mfma_f32_16x16x32_bf16 v[68:71], v[116:119], v[124:127], v[68:71]
	v_mfma_f32_16x16x32_bf16 v[84:87], v[120:123], v[124:127], v[84:87]
	s_waitcnt lgkmcnt(12)
	v_mfma_f32_16x16x32_bf16 v[8:11], v[100:103], v[128:131], v[8:11]
	v_mfma_f32_16x16x32_bf16 v[24:27], v[104:107], v[128:131], v[24:27]
	v_mfma_f32_16x16x32_bf16 v[40:43], v[108:111], v[128:131], v[40:43]
	v_mfma_f32_16x16x32_bf16 v[56:59], v[112:115], v[128:131], v[56:59]
	v_mfma_f32_16x16x32_bf16 v[72:75], v[116:119], v[128:131], v[72:75]
	v_mfma_f32_16x16x32_bf16 v[88:91], v[120:123], v[128:131], v[88:91]
	s_waitcnt lgkmcnt(11)
	v_mfma_f32_16x16x32_bf16 v[12:15], v[100:103], v[132:135], v[12:15]
	v_mfma_f32_16x16x32_bf16 v[28:31], v[104:107], v[132:135], v[28:31]
	v_mfma_f32_16x16x32_bf16 v[44:47], v[108:111], v[132:135], v[44:47]
	v_mfma_f32_16x16x32_bf16 v[60:63], v[112:115], v[132:135], v[60:63]
	v_mfma_f32_16x16x32_bf16 v[76:79], v[116:119], v[132:135], v[76:79]
	v_mfma_f32_16x16x32_bf16 v[92:95], v[120:123], v[132:135], v[92:95]
	s_waitcnt lgkmcnt(10)
	v_mfma_f32_16x16x32_bf16 v[16:19], v[100:103], v[136:139], v[16:19]
	v_mfma_f32_16x16x32_bf16 v[32:35], v[104:107], v[136:139], v[32:35]
	v_mfma_f32_16x16x32_bf16 v[48:51], v[108:111], v[136:139], v[48:51]
	v_mfma_f32_16x16x32_bf16 v[64:67], v[112:115], v[136:139], v[64:67]
	v_mfma_f32_16x16x32_bf16 v[80:83], v[116:119], v[136:139], v[80:83]
	v_mfma_f32_16x16x32_bf16 v[96:99], v[120:123], v[136:139], v[96:99]
	s_waitcnt lgkmcnt(0)
	s_add_u32 s34, s34, 1
	s_add_u32 s31, s31, 1
	s_cmp_lt_u32 s34, 16
	s_cbranch_scc1 .Lgm_wi_rot
	v_mfma_f32_16x16x32_bf16 v[4:7], v[140:143], v[164:167], v[4:7]
	v_mfma_f32_16x16x32_bf16 v[20:23], v[144:147], v[164:167], v[20:23]
	v_mfma_f32_16x16x32_bf16 v[36:39], v[148:151], v[164:167], v[36:39]
	v_mfma_f32_16x16x32_bf16 v[52:55], v[152:155], v[164:167], v[52:55]
	v_mfma_f32_16x16x32_bf16 v[68:71], v[156:159], v[164:167], v[68:71]
	v_mfma_f32_16x16x32_bf16 v[84:87], v[160:163], v[164:167], v[84:87]
	v_mfma_f32_16x16x32_bf16 v[8:11], v[140:143], v[168:171], v[8:11]
	v_mfma_f32_16x16x32_bf16 v[24:27], v[144:147], v[168:171], v[24:27]
	v_mfma_f32_16x16x32_bf16 v[40:43], v[148:151], v[168:171], v[40:43]
	v_mfma_f32_16x16x32_bf16 v[56:59], v[152:155], v[168:171], v[56:59]
	v_mfma_f32_16x16x32_bf16 v[72:75], v[156:159], v[168:171], v[72:75]
	v_mfma_f32_16x16x32_bf16 v[88:91], v[160:163], v[168:171], v[88:91]
	v_mfma_f32_16x16x32_bf16 v[12:15], v[140:143], v[172:175], v[12:15]
	v_mfma_f32_16x16x32_bf16 v[28:31], v[144:147], v[172:175], v[28:31]
	v_mfma_f32_16x16x32_bf16 v[44:47], v[148:151], v[172:175], v[44:47]
	v_mfma_f32_16x16x32_bf16 v[60:63], v[152:155], v[172:175], v[60:63]
	v_mfma_f32_16x16x32_bf16 v[76:79], v[156:159], v[172:175], v[76:79]
	v_mfma_f32_16x16x32_bf16 v[92:95], v[160:163], v[172:175], v[92:95]
	v_mfma_f32_16x16x32_bf16 v[16:19], v[140:143], v[176:179], v[16:19]
	v_mfma_f32_16x16x32_bf16 v[32:35], v[144:147], v[176:179], v[32:35]
	v_mfma_f32_16x16x32_bf16 v[48:51], v[148:151], v[176:179], v[48:51]
	v_mfma_f32_16x16x32_bf16 v[64:67], v[152:155], v[176:179], v[64:67]
	v_mfma_f32_16x16x32_bf16 v[80:83], v[156:159], v[176:179], v[80:83]
	v_mfma_f32_16x16x32_bf16 v[96:99], v[160:163], v[176:179], v[96:99]
	s_and_b32 s6, s35, 31
	s_mul_i32 s6, s6, 192
	s_lshr_b32 s7, s35, 5
	s_lshl_b32 s7, s7, 7
	s_nop 7
	s_mul_i32 s4, s6, 0x2440
	s_lshl_b32 s5, s7, 2
	s_add_u32 s4, s4, s5
	v_add_u32_e32 v197, s4, v205
	v_add_u32_e32 v192, s7, v193
	s_mov_b32 s4, 0x910
	v_cmp_gt_u32_e32 vcc, s4, v192
	s_mov_b64 s[4:5], exec
	ds_write_b32 v203, v4 offset:0
	ds_write_b32 v203, v5 offset:272
	ds_write_b32 v203, v6 offset:544
	ds_write_b32 v203, v7 offset:816
	ds_write_b32 v203, v8 offset:64
	ds_write_b32 v203, v9 offset:336
	ds_write_b32 v203, v10 offset:608
	ds_write_b32 v203, v11 offset:880
	ds_write_b32 v203, v12 offset:128
	ds_write_b32 v203, v13 offset:400
	ds_write_b32 v203, v14 offset:672
	ds_write_b32 v203, v15 offset:944
	ds_write_b32 v203, v16 offset:192
	ds_write_b32 v203, v17 offset:464
	ds_write_b32 v203, v18 offset:736
	ds_write_b32 v203, v19 offset:1008
	s_waitcnt lgkmcnt(0)
	ds_read_b128 v[156:159], v204 offset:0
	ds_read_b128 v[160:163], v204 offset:1088
	ds_read_b128 v[164:167], v204 offset:2176
	ds_read_b128 v[168:171], v204 offset:3264
	s_waitcnt lgkmcnt(0)
	s_and_b64 exec, s[4:5], vcc
	global_store_dwordx4 v197, v[156:159], s[56:57] sc0 sc1
	v_add_u32_e32 v197, 0x9100, v197
	global_store_dwordx4 v197, v[160:163], s[56:57] sc0 sc1
	v_add_u32_e32 v197, 0x9100, v197
	global_store_dwordx4 v197, v[164:167], s[56:57] sc0 sc1
	v_add_u32_e32 v197, 0x9100, v197
	global_store_dwordx4 v197, v[168:171], s[56:57] sc0 sc1
	v_add_u32_e32 v197, 0x9100, v197
	s_mov_b64 exec, s[4:5]
	s_nop 1
	ds_write_b32 v203, v20 offset:0
	ds_write_b32 v203, v21 offset:272
	ds_write_b32 v203, v22 offset:544
	ds_write_b32 v203, v23 offset:816
	ds_write_b32 v203, v24 offset:64
	ds_write_b32 v203, v25 offset:336
	ds_write_b32 v203, v26 offset:608
	ds_write_b32 v203, v27 offset:880
	ds_write_b32 v203, v28 offset:128
	ds_write_b32 v203, v29 offset:400
	ds_write_b32 v203, v30 offset:672
	ds_write_b32 v203, v31 offset:944
	ds_write_b32 v203, v32 offset:192
	ds_write_b32 v203, v33 offset:464
	ds_write_b32 v203, v34 offset:736
	ds_write_b32 v203, v35 offset:1008
	s_waitcnt lgkmcnt(0)
	ds_read_b128 v[156:159], v204 offset:0
	ds_read_b128 v[160:163], v204 offset:1088
	ds_read_b128 v[164:167], v204 offset:2176
	ds_read_b128 v[168:171], v204 offset:3264
	s_waitcnt lgkmcnt(0)
	s_and_b64 exec, s[4:5], vcc
	global_store_dwordx4 v197, v[156:159], s[56:57] sc0 sc1
	v_add_u32_e32 v197, 0x9100, v197
	global_store_dwordx4 v197, v[160:163], s[56:57] sc0 sc1
	v_add_u32_e32 v197, 0x9100, v197
	global_store_dwordx4 v197, v[164:167], s[56:57] sc0 sc1
	v_add_u32_e32 v197, 0x9100, v197
	global_store_dwordx4 v197, v[168:171], s[56:57] sc0 sc1
	v_add_u32_e32 v197, 0x9100, v197
	s_mov_b64 exec, s[4:5]
	s_nop 1
	ds_write_b32 v203, v36 offset:0
	ds_write_b32 v203, v37 offset:272
	ds_write_b32 v203, v38 offset:544
	ds_write_b32 v203, v39 offset:816
	ds_write_b32 v203, v40 offset:64
	ds_write_b32 v203, v41 offset:336
	ds_write_b32 v203, v42 offset:608
	ds_write_b32 v203, v43 offset:880
	ds_write_b32 v203, v44 offset:128
	ds_write_b32 v203, v45 offset:400
	ds_write_b32 v203, v46 offset:672
	ds_write_b32 v203, v47 offset:944
	ds_write_b32 v203, v48 offset:192
	ds_write_b32 v203, v49 offset:464
	ds_write_b32 v203, v50 offset:736
	ds_write_b32 v203, v51 offset:1008
	s_waitcnt lgkmcnt(0)
	ds_read_b128 v[156:159], v204 offset:0
	ds_read_b128 v[160:163], v204 offset:1088
	ds_read_b128 v[164:167], v204 offset:2176
	ds_read_b128 v[168:171], v204 offset:3264
	s_waitcnt lgkmcnt(0)
	s_and_b64 exec, s[4:5], vcc
	global_store_dwordx4 v197, v[156:159], s[56:57] sc0 sc1
	v_add_u32_e32 v197, 0x9100, v197
	global_store_dwordx4 v197, v[160:163], s[56:57] sc0 sc1
	v_add_u32_e32 v197, 0x9100, v197
	global_store_dwordx4 v197, v[164:167], s[56:57] sc0 sc1
	v_add_u32_e32 v197, 0x9100, v197
	global_store_dwordx4 v197, v[168:171], s[56:57] sc0 sc1
	v_add_u32_e32 v197, 0x9100, v197
	s_mov_b64 exec, s[4:5]
	s_nop 1
	ds_write_b32 v203, v52 offset:0
	ds_write_b32 v203, v53 offset:272
	ds_write_b32 v203, v54 offset:544
	ds_write_b32 v203, v55 offset:816
	ds_write_b32 v203, v56 offset:64
	ds_write_b32 v203, v57 offset:336
	ds_write_b32 v203, v58 offset:608
	ds_write_b32 v203, v59 offset:880
	ds_write_b32 v203, v60 offset:128
	ds_write_b32 v203, v61 offset:400
	ds_write_b32 v203, v62 offset:672
	ds_write_b32 v203, v63 offset:944
	ds_write_b32 v203, v64 offset:192
	ds_write_b32 v203, v65 offset:464
	ds_write_b32 v203, v66 offset:736
	ds_write_b32 v203, v67 offset:1008
	s_waitcnt lgkmcnt(0)
	ds_read_b128 v[156:159], v204 offset:0
	ds_read_b128 v[160:163], v204 offset:1088
	ds_read_b128 v[164:167], v204 offset:2176
	ds_read_b128 v[168:171], v204 offset:3264
	s_waitcnt lgkmcnt(0)
	s_and_b64 exec, s[4:5], vcc
	global_store_dwordx4 v197, v[156:159], s[56:57] sc0 sc1
	v_add_u32_e32 v197, 0x9100, v197
	global_store_dwordx4 v197, v[160:163], s[56:57] sc0 sc1
	v_add_u32_e32 v197, 0x9100, v197
	global_store_dwordx4 v197, v[164:167], s[56:57] sc0 sc1
	v_add_u32_e32 v197, 0x9100, v197
	global_store_dwordx4 v197, v[168:171], s[56:57] sc0 sc1
	v_add_u32_e32 v197, 0x9100, v197
	s_mov_b64 exec, s[4:5]
	s_nop 1
	ds_write_b32 v203, v68 offset:0
	ds_write_b32 v203, v69 offset:272
	ds_write_b32 v203, v70 offset:544
	ds_write_b32 v203, v71 offset:816
	ds_write_b32 v203, v72 offset:64
	ds_write_b32 v203, v73 offset:336
	ds_write_b32 v203, v74 offset:608
	ds_write_b32 v203, v75 offset:880
	ds_write_b32 v203, v76 offset:128
	ds_write_b32 v203, v77 offset:400
	ds_write_b32 v203, v78 offset:672
	ds_write_b32 v203, v79 offset:944
	ds_write_b32 v203, v80 offset:192
	ds_write_b32 v203, v81 offset:464
	ds_write_b32 v203, v82 offset:736
	ds_write_b32 v203, v83 offset:1008
	s_waitcnt lgkmcnt(0)
	ds_read_b128 v[156:159], v204 offset:0
	ds_read_b128 v[160:163], v204 offset:1088
	ds_read_b128 v[164:167], v204 offset:2176
	ds_read_b128 v[168:171], v204 offset:3264
	s_waitcnt lgkmcnt(0)
	s_and_b64 exec, s[4:5], vcc
	global_store_dwordx4 v197, v[156:159], s[56:57] sc0 sc1
	v_add_u32_e32 v197, 0x9100, v197
	global_store_dwordx4 v197, v[160:163], s[56:57] sc0 sc1
	v_add_u32_e32 v197, 0x9100, v197
	global_store_dwordx4 v197, v[164:167], s[56:57] sc0 sc1
	v_add_u32_e32 v197, 0x9100, v197
	global_store_dwordx4 v197, v[168:171], s[56:57] sc0 sc1
	v_add_u32_e32 v197, 0x9100, v197
	s_mov_b64 exec, s[4:5]
	s_nop 1
	ds_write_b32 v203, v84 offset:0
	ds_write_b32 v203, v85 offset:272
	ds_write_b32 v203, v86 offset:544
	ds_write_b32 v203, v87 offset:816
	ds_write_b32 v203, v88 offset:64
	ds_write_b32 v203, v89 offset:336
	ds_write_b32 v203, v90 offset:608
	ds_write_b32 v203, v91 offset:880
	ds_write_b32 v203, v92 offset:128
	ds_write_b32 v203, v93 offset:400
	ds_write_b32 v203, v94 offset:672
	ds_write_b32 v203, v95 offset:944
	ds_write_b32 v203, v96 offset:192
	ds_write_b32 v203, v97 offset:464
	ds_write_b32 v203, v98 offset:736
	ds_write_b32 v203, v99 offset:1008
	s_waitcnt lgkmcnt(0)
	ds_read_b128 v[156:159], v204 offset:0
	ds_read_b128 v[160:163], v204 offset:1088
	ds_read_b128 v[164:167], v204 offset:2176
	ds_read_b128 v[168:171], v204 offset:3264
	s_waitcnt lgkmcnt(0)
	s_and_b64 exec, s[4:5], vcc
	global_store_dwordx4 v197, v[156:159], s[56:57] sc0 sc1
	v_add_u32_e32 v197, 0x9100, v197
	global_store_dwordx4 v197, v[160:163], s[56:57] sc0 sc1
	v_add_u32_e32 v197, 0x9100, v197
	global_store_dwordx4 v197, v[164:167], s[56:57] sc0 sc1
	v_add_u32_e32 v197, 0x9100, v197
	global_store_dwordx4 v197, v[168:171], s[56:57] sc0 sc1
	v_add_u32_e32 v197, 0x9100, v197
	s_mov_b64 exec, s[4:5]
	s_nop 1
	v_mov_b32_e32 v4, 0
	v_mov_b32_e32 v5, 0
	v_mov_b32_e32 v6, 0
	v_mov_b32_e32 v7, 0
	v_mov_b32_e32 v8, 0
	v_mov_b32_e32 v9, 0
	v_mov_b32_e32 v10, 0
	v_mov_b32_e32 v11, 0
	v_mov_b32_e32 v12, 0
	v_mov_b32_e32 v13, 0
	v_mov_b32_e32 v14, 0
	v_mov_b32_e32 v15, 0
	v_mov_b32_e32 v16, 0
	v_mov_b32_e32 v17, 0
	v_mov_b32_e32 v18, 0
	v_mov_b32_e32 v19, 0
	v_mov_b32_e32 v20, 0
	v_mov_b32_e32 v21, 0
	v_mov_b32_e32 v22, 0
	v_mov_b32_e32 v23, 0
	v_mov_b32_e32 v24, 0
	v_mov_b32_e32 v25, 0
	v_mov_b32_e32 v26, 0
	v_mov_b32_e32 v27, 0
	v_mov_b32_e32 v28, 0
	v_mov_b32_e32 v29, 0
	v_mov_b32_e32 v30, 0
	v_mov_b32_e32 v31, 0
	v_mov_b32_e32 v32, 0
	v_mov_b32_e32 v33, 0
	v_mov_b32_e32 v34, 0
	v_mov_b32_e32 v35, 0
	v_mov_b32_e32 v36, 0
	v_mov_b32_e32 v37, 0
	v_mov_b32_e32 v38, 0
	v_mov_b32_e32 v39, 0
	v_mov_b32_e32 v40, 0
	v_mov_b32_e32 v41, 0
	v_mov_b32_e32 v42, 0
	v_mov_b32_e32 v43, 0
	v_mov_b32_e32 v44, 0
	v_mov_b32_e32 v45, 0
	v_mov_b32_e32 v46, 0
	v_mov_b32_e32 v47, 0
	v_mov_b32_e32 v48, 0
	v_mov_b32_e32 v49, 0
	v_mov_b32_e32 v50, 0
	v_mov_b32_e32 v51, 0
	v_mov_b32_e32 v52, 0
	v_mov_b32_e32 v53, 0
	v_mov_b32_e32 v54, 0
	v_mov_b32_e32 v55, 0
	v_mov_b32_e32 v56, 0
	v_mov_b32_e32 v57, 0
	v_mov_b32_e32 v58, 0
	v_mov_b32_e32 v59, 0
	v_mov_b32_e32 v60, 0
	v_mov_b32_e32 v61, 0
	v_mov_b32_e32 v62, 0
	v_mov_b32_e32 v63, 0
	v_mov_b32_e32 v64, 0
	v_mov_b32_e32 v65, 0
	v_mov_b32_e32 v66, 0
	v_mov_b32_e32 v67, 0
	v_mov_b32_e32 v68, 0
	v_mov_b32_e32 v69, 0
	v_mov_b32_e32 v70, 0
	v_mov_b32_e32 v71, 0
	v_mov_b32_e32 v72, 0
	v_mov_b32_e32 v73, 0
	v_mov_b32_e32 v74, 0
	v_mov_b32_e32 v75, 0
	v_mov_b32_e32 v76, 0
	v_mov_b32_e32 v77, 0
	v_mov_b32_e32 v78, 0
	v_mov_b32_e32 v79, 0
	v_mov_b32_e32 v80, 0
	v_mov_b32_e32 v81, 0
	v_mov_b32_e32 v82, 0
	v_mov_b32_e32 v83, 0
	v_mov_b32_e32 v84, 0
	v_mov_b32_e32 v85, 0
	v_mov_b32_e32 v86, 0
	v_mov_b32_e32 v87, 0
	v_mov_b32_e32 v88, 0
	v_mov_b32_e32 v89, 0
	v_mov_b32_e32 v90, 0
	v_mov_b32_e32 v91, 0
	v_mov_b32_e32 v92, 0
	v_mov_b32_e32 v93, 0
	v_mov_b32_e32 v94, 0
	v_mov_b32_e32 v95, 0
	v_mov_b32_e32 v96, 0
	v_mov_b32_e32 v97, 0
	v_mov_b32_e32 v98, 0
	v_mov_b32_e32 v99, 0
	s_mov_b32 s34, 0
	s_add_u32 s35, s35, s52
	s_cmp_ge_u32 s31, s30
	s_cbranch_scc1 .Lgm_wi_exit

.LBB0_642:
	s_or_b64 exec, exec, s[38:39]
	s_waitcnt lgkmcnt(0)
	s_barrier
	ds_read_b32 v0, v208
	s_movk_i32 s4, 0x65f
	s_waitcnt lgkmcnt(0)
	v_cmp_lt_i32_e32 vcc, s4, v0
	v_readfirstlane_b32 s60, v0
	s_nop 0
	s_add_u32 s99, s60, 0x630
	s_sub_u32 s98, s60, 48
	s_cmp_lt_u32 s60, 48
	s_cselect_b32 s60, s99, s98
	s_cbranch_vccnz .LBB0_704
	v_readlane_b32 s44, v237, 9
	s_mul_i32 s40, s36, 0x5000
	s_lshl_b64 s[38:39], s[36:37], 12
	v_readlane_b32 s52, v237, 17
	s_mul_hi_i32 s35, s36, 0x5000
	v_readlane_b32 s53, v237, 18
	s_add_u32 s40, s52, s40
	v_readlane_b32 s54, v237, 19
	s_addc_u32 s41, s53, s35
	v_readlane_b32 s4, v235, 61
	v_readlane_b32 s55, v237, 20
	s_add_u32 s42, s54, s38
	v_readlane_b32 s5, v235, 62
	v_writelane_b32 v234, s16, 0
	s_addc_u32 s43, s55, s39
	s_lshl_b64 s[38:39], s[4:5], 2
	v_writelane_b32 v234, s17, 1
	s_mov_b32 s52, s18
	v_readlane_b32 s4, v237, 25
	v_readlane_b32 s8, v237, 29
	v_readlane_b32 s16, v237, 37
	v_readlane_b32 s17, v237, 38
	v_readlane_b32 s45, v237, 10
	v_readlane_b32 s6, v237, 27
	v_readlane_b32 s9, v237, 30
	v_readlane_b32 s16, v234, 0
	s_add_u32 s44, s8, s38
	s_mov_b32 s6, s52
	v_readlane_b32 s17, v234, 1
	s_addc_u32 s45, s9, s39
	v_readlane_b32 s46, v237, 11
	v_readlane_b32 s47, v237, 12
	v_readlane_b32 s48, v237, 13
	v_readlane_b32 s49, v237, 14
	v_readlane_b32 s50, v237, 15
	v_readlane_b32 s51, v237, 16
	v_readlane_b32 s56, v237, 21
	v_readlane_b32 s57, v237, 22
	v_readlane_b32 s58, v237, 23
	v_readlane_b32 s59, v237, 24
	v_readlane_b32 s5, v237, 26
	v_readlane_b32 s7, v237, 28
	v_readlane_b32 s10, v237, 31
	v_readlane_b32 s11, v237, 32
	v_readlane_b32 s12, v237, 33
	v_readlane_b32 s13, v237, 34
	v_readlane_b32 s14, v237, 35
	v_readlane_b32 s15, v237, 36
	v_readlane_b32 s18, v237, 39
	v_readlane_b32 s19, v237, 40
	s_branch .LBB0_646

.LBB0_645:
	s_or_b64 exec, exec, s[38:39]
	s_waitcnt lgkmcnt(0)
	s_barrier
	ds_read_b32 v0, v208
	s_movk_i32 s4, 0x65f
	s_waitcnt lgkmcnt(0)
	v_cmp_lt_i32_e32 vcc, s4, v0
	v_readfirstlane_b32 s60, v0
	s_nop 0
	s_add_u32 s99, s60, 0x630
	s_sub_u32 s98, s60, 48
	s_cmp_lt_u32 s60, 48
	s_cselect_b32 s60, s99, s98
	s_cbranch_vccnz .LBB0_704
